# GEMM K-loops with hipcc's per-phase s_setprio flips removed, no static raise (A/B against the static-raise variant)
# baseline (speedup 1.0000x reference)
.LBB0_132:
	s_add_u32 s34, s28, 0x100
	v_mov_b32_e32 v0, 0
	s_addc_u32 s79, s29, 0
	s_mov_b32 s84, -2
	v_mov_b32_e32 v1, v0
	v_mov_b32_e32 v2, v0
	v_mov_b32_e32 v3, v0
	v_mov_b32_e32 v4, v0
	v_mov_b32_e32 v5, v0
	v_mov_b32_e32 v6, v0
	v_mov_b32_e32 v7, v0
	v_mov_b32_e32 v8, v0
	v_mov_b32_e32 v9, v0
	v_mov_b32_e32 v10, v0
	v_mov_b32_e32 v11, v0
	v_mov_b32_e32 v12, v0
	v_mov_b32_e32 v13, v0
	v_mov_b32_e32 v14, v0
	v_mov_b32_e32 v15, v0
	v_mov_b32_e32 v22, v0
	v_mov_b32_e32 v23, v0
	v_mov_b32_e32 v24, v0
	v_mov_b32_e32 v25, v0
	v_mov_b32_e32 v26, v0
	v_mov_b32_e32 v27, v0
	v_mov_b32_e32 v28, v0
	v_mov_b32_e32 v29, v0
	v_mov_b32_e32 v34, v0
	v_mov_b32_e32 v35, v0
	v_mov_b32_e32 v36, v0
	v_mov_b32_e32 v37, v0
	v_mov_b32_e32 v42, v0
	v_mov_b32_e32 v43, v0
	v_mov_b32_e32 v44, v0
	v_mov_b32_e32 v45, v0
	v_mov_b32_e32 v18, v0
	v_mov_b32_e32 v19, v0
	v_mov_b32_e32 v20, v0
	v_mov_b32_e32 v21, v0
	v_mov_b32_e32 v30, v0
	v_mov_b32_e32 v31, v0
	v_mov_b32_e32 v32, v0
	v_mov_b32_e32 v33, v0
	v_mov_b32_e32 v38, v0
	v_mov_b32_e32 v39, v0
	v_mov_b32_e32 v40, v0
	v_mov_b32_e32 v41, v0
	v_mov_b32_e32 v46, v0
	v_mov_b32_e32 v47, v0
	v_mov_b32_e32 v48, v0
	v_mov_b32_e32 v49, v0
	v_mov_b32_e32 v50, v0
	v_mov_b32_e32 v51, v0
	v_mov_b32_e32 v52, v0
	v_mov_b32_e32 v53, v0
	v_mov_b32_e32 v54, v0
	v_mov_b32_e32 v55, v0
	v_mov_b32_e32 v56, v0
	v_mov_b32_e32 v57, v0
	v_mov_b32_e32 v58, v0
	v_mov_b32_e32 v59, v0
	v_mov_b32_e32 v60, v0
	v_mov_b32_e32 v61, v0
	v_mov_b32_e32 v62, v0
	v_mov_b32_e32 v63, v0
	v_mov_b32_e32 v64, v0
	v_mov_b32_e32 v65, v0
	v_mov_b32_e32 v66, v0
	v_mov_b32_e32 v67, v0
	v_mov_b32_e32 v68, v0
	v_mov_b32_e32 v69, v0
	v_mov_b32_e32 v70, v0
	v_mov_b32_e32 v71, v0
	v_mov_b32_e32 v72, v0
	v_mov_b32_e32 v73, v0
	v_mov_b32_e32 v78, v0
	v_mov_b32_e32 v79, v0
	v_mov_b32_e32 v80, v0
	v_mov_b32_e32 v81, v0
	v_mov_b32_e32 v82, v0
	v_mov_b32_e32 v83, v0
	v_mov_b32_e32 v84, v0
	v_mov_b32_e32 v85, v0
	v_mov_b32_e32 v94, v0
	v_mov_b32_e32 v95, v0
	v_mov_b32_e32 v96, v0
	v_mov_b32_e32 v97, v0
	v_mov_b32_e32 v98, v0
	v_mov_b32_e32 v99, v0
	v_mov_b32_e32 v100, v0
	v_mov_b32_e32 v101, v0
	v_mov_b32_e32 v110, v0
	v_mov_b32_e32 v111, v0
	v_mov_b32_e32 v112, v0
	v_mov_b32_e32 v113, v0
	v_mov_b32_e32 v114, v0
	v_mov_b32_e32 v115, v0
	v_mov_b32_e32 v116, v0
	v_mov_b32_e32 v117, v0
	v_mov_b32_e32 v74, v0
	v_mov_b32_e32 v75, v0
	v_mov_b32_e32 v76, v0
	v_mov_b32_e32 v77, v0
	v_mov_b32_e32 v86, v0
	v_mov_b32_e32 v87, v0
	v_mov_b32_e32 v88, v0
	v_mov_b32_e32 v89, v0
	v_mov_b32_e32 v90, v0
	v_mov_b32_e32 v91, v0
	v_mov_b32_e32 v92, v0
	v_mov_b32_e32 v93, v0
	v_mov_b32_e32 v102, v0
	v_mov_b32_e32 v103, v0
	v_mov_b32_e32 v104, v0
	v_mov_b32_e32 v105, v0
	v_mov_b32_e32 v106, v0
	v_mov_b32_e32 v107, v0
	v_mov_b32_e32 v108, v0
	v_mov_b32_e32 v109, v0
	v_mov_b32_e32 v118, v0
	v_mov_b32_e32 v119, v0
	v_mov_b32_e32 v120, v0
	v_mov_b32_e32 v121, v0
	v_mov_b32_e32 v122, v0
	v_mov_b32_e32 v123, v0
	v_mov_b32_e32 v124, v0
	v_mov_b32_e32 v125, v0
	v_mov_b32_e32 v126, v0
	v_mov_b32_e32 v127, v0
	v_mov_b32_e32 v128, v0
	v_mov_b32_e32 v129, v0
.LBB0_133:
	s_add_u32 s28, s22, 0x100
	s_addc_u32 s29, s23, 0
	s_add_i32 s85, 0, 0x10000
	v_add_u32_e32 v148, s85, v157
	ds_read_b128 v[130:133], v148
	ds_read_b128 v[134:137], v148 offset:1024
	ds_read_b128 v[138:141], v148 offset:2048
	ds_read_b128 v[148:151], v148 offset:3072
	s_cmp_eq_u32 s84, 40
	s_cselect_b32 s43, s17, s29
	s_cselect_b32 s42, s16, s28
	s_cselect_b32 s41, s19, s79
	s_cselect_b32 s40, s18, s34
	v_lshl_add_u64 v[188:189], s[22:23], 0, v[146:147]
	s_add_i32 m0, s54, 0xc000
	ds_read_b128 v[152:155], v159
	ds_read_b128 v[160:163], v159 offset:1024
	ds_read_b128 v[164:167], v159 offset:2048
	ds_read_b128 v[168:171], v159 offset:3072
	ds_read_b128 v[172:175], v159 offset:4096
	ds_read_b128 v[176:179], v159 offset:5120
	ds_read_b128 v[180:183], v159 offset:6144
	ds_read_b128 v[184:187], v159 offset:7168
	global_load_lds_dwordx4 v[188:189], off
	v_lshl_add_u64 v[188:189], s[22:23], 0, v[144:145]
	s_add_i32 m0, s54, 0xe000
	s_nop 0
	global_load_lds_dwordx4 v[188:189], off
	s_waitcnt lgkmcnt(8)
	s_barrier
	s_waitcnt lgkmcnt(0)
	s_waitcnt lgkmcnt(0)
	v_mfma_f32_16x16x32_bf16 v[126:129], v[130:133], v[152:155], v[126:129]
	v_mfma_f32_16x16x32_bf16 v[122:125], v[138:141], v[152:155], v[122:125]
	v_mfma_f32_16x16x32_bf16 v[118:121], v[130:133], v[164:167], v[118:121]
	v_mfma_f32_16x16x32_bf16 v[106:109], v[138:141], v[164:167], v[106:109]
	v_mfma_f32_16x16x32_bf16 v[102:105], v[130:133], v[172:175], v[102:105]
	v_mfma_f32_16x16x32_bf16 v[90:93], v[138:141], v[172:175], v[90:93]
	v_mfma_f32_16x16x32_bf16 v[86:89], v[130:133], v[180:183], v[86:89]
	v_mfma_f32_16x16x32_bf16 v[74:77], v[138:141], v[180:183], v[74:77]
	v_mfma_f32_16x16x32_bf16 v[126:129], v[134:137], v[160:163], v[126:129]
	v_mfma_f32_16x16x32_bf16 v[122:125], v[148:151], v[160:163], v[122:125]
	v_mfma_f32_16x16x32_bf16 v[118:121], v[134:137], v[168:171], v[118:121]
	v_mfma_f32_16x16x32_bf16 v[106:109], v[148:151], v[168:171], v[106:109]
	v_mfma_f32_16x16x32_bf16 v[102:105], v[134:137], v[176:179], v[102:105]
	v_mfma_f32_16x16x32_bf16 v[90:93], v[148:151], v[176:179], v[90:93]
	v_mfma_f32_16x16x32_bf16 v[86:89], v[134:137], v[184:187], v[86:89]
	v_mfma_f32_16x16x32_bf16 v[74:77], v[148:151], v[184:187], v[74:77]
	s_barrier
	s_add_i32 s86, 0, 0x14000
	v_add_u32_e32 v196, s86, v157
	s_add_i32 s22, s85, s50
	ds_read_b128 v[188:191], v196
	ds_read_b128 v[192:195], v196 offset:1024
	ds_read_b128 v[208:211], v196 offset:2048
	ds_read_b128 v[212:215], v196 offset:3072
	v_lshl_add_u64 v[196:197], s[40:41], 0, v[16:17]
	s_mov_b32 m0, s22
	v_lshl_add_u64 v[216:217], s[40:41], 0, v[142:143]
	global_load_lds_dwordx4 v[196:197], off
	s_add_i32 m0, s22, 0x2000
	s_nop 0
	global_load_lds_dwordx4 v[216:217], off
	s_barrier
	s_waitcnt lgkmcnt(0)
	s_waitcnt lgkmcnt(0)
	v_mfma_f32_16x16x32_bf16 v[114:117], v[188:191], v[152:155], v[114:117]
	v_mfma_f32_16x16x32_bf16 v[110:113], v[208:211], v[152:155], v[110:113]
	v_mfma_f32_16x16x32_bf16 v[98:101], v[188:191], v[164:167], v[98:101]
	v_mfma_f32_16x16x32_bf16 v[94:97], v[208:211], v[164:167], v[94:97]
	v_mfma_f32_16x16x32_bf16 v[82:85], v[188:191], v[172:175], v[82:85]
	v_mfma_f32_16x16x32_bf16 v[78:81], v[208:211], v[172:175], v[78:81]
	v_mfma_f32_16x16x32_bf16 v[70:73], v[188:191], v[180:183], v[70:73]
	v_mfma_f32_16x16x32_bf16 v[66:69], v[208:211], v[180:183], v[66:69]
	v_mfma_f32_16x16x32_bf16 v[114:117], v[192:195], v[160:163], v[114:117]
	v_mfma_f32_16x16x32_bf16 v[110:113], v[212:215], v[160:163], v[110:113]
	v_mfma_f32_16x16x32_bf16 v[98:101], v[192:195], v[168:171], v[98:101]
	v_mfma_f32_16x16x32_bf16 v[94:97], v[212:215], v[168:171], v[94:97]
	v_mfma_f32_16x16x32_bf16 v[82:85], v[192:195], v[176:179], v[82:85]
	v_mfma_f32_16x16x32_bf16 v[78:81], v[212:215], v[176:179], v[78:81]
	v_mfma_f32_16x16x32_bf16 v[70:73], v[192:195], v[184:187], v[70:73]
	v_mfma_f32_16x16x32_bf16 v[66:69], v[212:215], v[184:187], v[66:69]
	s_mov_b32 m0, s54
	v_lshl_add_u64 v[218:219], s[42:43], 0, v[16:17]
	s_barrier
	ds_read_b128 v[152:155], v159 offset:16384
	ds_read_b128 v[160:163], v159 offset:17408
	ds_read_b128 v[164:167], v159 offset:18432
	ds_read_b128 v[168:171], v159 offset:19456
	ds_read_b128 v[172:175], v159 offset:20480
	ds_read_b128 v[176:179], v159 offset:21504
	ds_read_b128 v[180:183], v159 offset:22528
	ds_read_b128 v[184:187], v159 offset:23552
	global_load_lds_dwordx4 v[218:219], off
	v_lshl_add_u64 v[220:221], s[42:43], 0, v[142:143]
	s_mov_b32 m0, s55
	s_nop 0
	global_load_lds_dwordx4 v[220:221], off
	s_barrier
	s_waitcnt lgkmcnt(0)
	s_waitcnt lgkmcnt(0)
	v_mfma_f32_16x16x32_bf16 v[62:65], v[130:133], v[152:155], v[62:65]
	v_mfma_f32_16x16x32_bf16 v[58:61], v[138:141], v[152:155], v[58:61]
	v_mfma_f32_16x16x32_bf16 v[54:57], v[130:133], v[164:167], v[54:57]
	v_mfma_f32_16x16x32_bf16 v[50:53], v[138:141], v[164:167], v[50:53]
	v_mfma_f32_16x16x32_bf16 v[46:49], v[130:133], v[172:175], v[46:49]
	v_mfma_f32_16x16x32_bf16 v[38:41], v[138:141], v[172:175], v[38:41]
	v_mfma_f32_16x16x32_bf16 v[30:33], v[130:133], v[180:183], v[30:33]
	v_mfma_f32_16x16x32_bf16 v[18:21], v[138:141], v[180:183], v[18:21]
	v_mfma_f32_16x16x32_bf16 v[62:65], v[134:137], v[160:163], v[62:65]
	v_mfma_f32_16x16x32_bf16 v[58:61], v[148:151], v[160:163], v[58:61]
	v_mfma_f32_16x16x32_bf16 v[54:57], v[134:137], v[168:171], v[54:57]
	v_mfma_f32_16x16x32_bf16 v[50:53], v[148:151], v[168:171], v[50:53]
	v_mfma_f32_16x16x32_bf16 v[46:49], v[134:137], v[176:179], v[46:49]
	v_mfma_f32_16x16x32_bf16 v[38:41], v[148:151], v[176:179], v[38:41]
	v_mfma_f32_16x16x32_bf16 v[30:33], v[134:137], v[184:187], v[30:33]
	v_mfma_f32_16x16x32_bf16 v[18:21], v[148:151], v[184:187], v[18:21]
	s_barrier
	s_add_u32 s22, s40, 0xb0000
	s_addc_u32 s23, s41, 0
	s_add_i32 s85, s86, s50
	v_lshl_add_u64 v[130:131], s[22:23], 0, v[16:17]
	s_mov_b32 m0, s85
	s_nop 0
	global_load_lds_dwordx4 v[130:131], off
	v_lshl_add_u64 v[130:131], s[22:23], 0, v[142:143]
	s_add_i32 m0, s85, 0x2000
	s_nop 0
	global_load_lds_dwordx4 v[130:131], off
	s_waitcnt vmcnt(6)
	s_barrier
	v_mfma_f32_16x16x32_bf16 v[42:45], v[188:191], v[152:155], v[42:45]
	v_mfma_f32_16x16x32_bf16 v[34:37], v[208:211], v[152:155], v[34:37]
	v_mfma_f32_16x16x32_bf16 v[26:29], v[188:191], v[164:167], v[26:29]
	v_mfma_f32_16x16x32_bf16 v[22:25], v[208:211], v[164:167], v[22:25]
	v_mfma_f32_16x16x32_bf16 v[12:15], v[188:191], v[172:175], v[12:15]
	v_mfma_f32_16x16x32_bf16 v[8:11], v[208:211], v[172:175], v[8:11]
	v_mfma_f32_16x16x32_bf16 v[4:7], v[188:191], v[180:183], v[4:7]
	v_mfma_f32_16x16x32_bf16 v[0:3], v[208:211], v[180:183], v[0:3]
	v_mfma_f32_16x16x32_bf16 v[42:45], v[192:195], v[160:163], v[42:45]
	v_mfma_f32_16x16x32_bf16 v[34:37], v[212:215], v[160:163], v[34:37]
	v_mfma_f32_16x16x32_bf16 v[26:29], v[192:195], v[168:171], v[26:29]
	v_mfma_f32_16x16x32_bf16 v[22:25], v[212:215], v[168:171], v[22:25]
	v_mfma_f32_16x16x32_bf16 v[12:15], v[192:195], v[176:179], v[12:15]
	v_mfma_f32_16x16x32_bf16 v[8:11], v[212:215], v[176:179], v[8:11]
	v_mfma_f32_16x16x32_bf16 v[4:7], v[192:195], v[184:187], v[4:7]
	v_mfma_f32_16x16x32_bf16 v[0:3], v[212:215], v[184:187], v[0:3]
	s_add_i32 s85, 0, 0x18000
	v_add_u32_e32 v148, s85, v157
	s_barrier
	ds_read_b128 v[130:133], v148
	ds_read_b128 v[134:137], v148 offset:1024
	ds_read_b128 v[138:141], v148 offset:2048
	ds_read_b128 v[148:151], v148 offset:3072
	s_add_u32 s22, s42, 0xb0000
	s_addc_u32 s23, s43, 0
	s_mov_b32 m0, s56
	v_lshl_add_u64 v[188:189], s[22:23], 0, v[16:17]
	ds_read_b128 v[152:155], v159 offset:32768
	ds_read_b128 v[160:163], v159 offset:33792
	ds_read_b128 v[164:167], v159 offset:34816
	ds_read_b128 v[168:171], v159 offset:35840
	ds_read_b128 v[172:175], v159 offset:36864
	ds_read_b128 v[176:179], v159 offset:37888
	ds_read_b128 v[180:183], v159 offset:38912
	ds_read_b128 v[184:187], v159 offset:39936
	global_load_lds_dwordx4 v[188:189], off
	v_lshl_add_u64 v[188:189], s[22:23], 0, v[142:143]
	s_mov_b32 m0, s57
	s_nop 0
	global_load_lds_dwordx4 v[188:189], off
	s_waitcnt lgkmcnt(8)
	s_barrier
	s_waitcnt lgkmcnt(0)
	s_waitcnt lgkmcnt(0)
	v_mfma_f32_16x16x32_bf16 v[126:129], v[130:133], v[152:155], v[126:129]
	v_mfma_f32_16x16x32_bf16 v[122:125], v[138:141], v[152:155], v[122:125]
	v_mfma_f32_16x16x32_bf16 v[118:121], v[130:133], v[164:167], v[118:121]
	v_mfma_f32_16x16x32_bf16 v[106:109], v[138:141], v[164:167], v[106:109]
	v_mfma_f32_16x16x32_bf16 v[102:105], v[130:133], v[172:175], v[102:105]
	v_mfma_f32_16x16x32_bf16 v[90:93], v[138:141], v[172:175], v[90:93]
	v_mfma_f32_16x16x32_bf16 v[86:89], v[130:133], v[180:183], v[86:89]
	v_mfma_f32_16x16x32_bf16 v[74:77], v[138:141], v[180:183], v[74:77]
	v_mfma_f32_16x16x32_bf16 v[126:129], v[134:137], v[160:163], v[126:129]
	v_mfma_f32_16x16x32_bf16 v[122:125], v[148:151], v[160:163], v[122:125]
	v_mfma_f32_16x16x32_bf16 v[118:121], v[134:137], v[168:171], v[118:121]
	v_mfma_f32_16x16x32_bf16 v[106:109], v[148:151], v[168:171], v[106:109]
	v_mfma_f32_16x16x32_bf16 v[102:105], v[134:137], v[176:179], v[102:105]
	v_mfma_f32_16x16x32_bf16 v[90:93], v[148:151], v[176:179], v[90:93]
	v_mfma_f32_16x16x32_bf16 v[86:89], v[134:137], v[184:187], v[86:89]
	v_mfma_f32_16x16x32_bf16 v[74:77], v[148:151], v[184:187], v[74:77]
	s_barrier
	s_add_i32 s42, 0, 0x1c000
	s_add_i32 s22, s85, s50
	v_add_u32_e32 v212, s42, v157
	v_lshl_add_u64 v[196:197], v[196:197], 0, s[10:11]
	s_mov_b32 m0, s22
	ds_read_b128 v[188:191], v212
	ds_read_b128 v[192:195], v212 offset:1024
	ds_read_b128 v[208:211], v212 offset:2048
	ds_read_b128 v[212:215], v212 offset:3072
	global_load_lds_dwordx4 v[196:197], off
	v_lshl_add_u64 v[196:197], v[216:217], 0, s[10:11]
	s_add_i32 m0, s22, 0x2000
	s_nop 0
	global_load_lds_dwordx4 v[196:197], off
	s_barrier
	s_waitcnt lgkmcnt(0)
	s_waitcnt lgkmcnt(0)
	v_mfma_f32_16x16x32_bf16 v[114:117], v[188:191], v[152:155], v[114:117]
	v_mfma_f32_16x16x32_bf16 v[110:113], v[208:211], v[152:155], v[110:113]
	v_mfma_f32_16x16x32_bf16 v[98:101], v[188:191], v[164:167], v[98:101]
	v_mfma_f32_16x16x32_bf16 v[94:97], v[208:211], v[164:167], v[94:97]
	v_mfma_f32_16x16x32_bf16 v[82:85], v[188:191], v[172:175], v[82:85]
	v_mfma_f32_16x16x32_bf16 v[78:81], v[208:211], v[172:175], v[78:81]
	v_mfma_f32_16x16x32_bf16 v[70:73], v[188:191], v[180:183], v[70:73]
	v_mfma_f32_16x16x32_bf16 v[66:69], v[208:211], v[180:183], v[66:69]
	v_mfma_f32_16x16x32_bf16 v[114:117], v[192:195], v[160:163], v[114:117]
	v_mfma_f32_16x16x32_bf16 v[110:113], v[212:215], v[160:163], v[110:113]
	v_mfma_f32_16x16x32_bf16 v[98:101], v[192:195], v[168:171], v[98:101]
	v_mfma_f32_16x16x32_bf16 v[94:97], v[212:215], v[168:171], v[94:97]
	v_mfma_f32_16x16x32_bf16 v[82:85], v[192:195], v[176:179], v[82:85]
	v_mfma_f32_16x16x32_bf16 v[78:81], v[212:215], v[176:179], v[78:81]
	v_mfma_f32_16x16x32_bf16 v[70:73], v[192:195], v[184:187], v[70:73]
	v_mfma_f32_16x16x32_bf16 v[66:69], v[212:215], v[184:187], v[66:69]
	s_mov_b32 m0, s58
	v_lshl_add_u64 v[196:197], v[218:219], 0, s[10:11]
	s_barrier
	ds_read_b128 v[152:155], v159 offset:49152
	ds_read_b128 v[160:163], v159 offset:50176
	ds_read_b128 v[164:167], v159 offset:51200
	ds_read_b128 v[168:171], v159 offset:52224
	ds_read_b128 v[172:175], v159 offset:53248
	ds_read_b128 v[176:179], v159 offset:54272
	ds_read_b128 v[180:183], v159 offset:55296
	ds_read_b128 v[184:187], v159 offset:56320
	global_load_lds_dwordx4 v[196:197], off
	v_lshl_add_u64 v[196:197], v[220:221], 0, s[10:11]
	s_mov_b32 m0, s59
	s_nop 0
	global_load_lds_dwordx4 v[196:197], off
	s_barrier
	s_waitcnt lgkmcnt(0)
	s_waitcnt lgkmcnt(0)
	v_mfma_f32_16x16x32_bf16 v[62:65], v[130:133], v[152:155], v[62:65]
	v_mfma_f32_16x16x32_bf16 v[58:61], v[138:141], v[152:155], v[58:61]
	v_mfma_f32_16x16x32_bf16 v[54:57], v[130:133], v[164:167], v[54:57]
	v_mfma_f32_16x16x32_bf16 v[50:53], v[138:141], v[164:167], v[50:53]
	v_mfma_f32_16x16x32_bf16 v[46:49], v[130:133], v[172:175], v[46:49]
	v_mfma_f32_16x16x32_bf16 v[38:41], v[138:141], v[172:175], v[38:41]
	v_mfma_f32_16x16x32_bf16 v[30:33], v[130:133], v[180:183], v[30:33]
	v_mfma_f32_16x16x32_bf16 v[18:21], v[138:141], v[180:183], v[18:21]
	v_mfma_f32_16x16x32_bf16 v[62:65], v[134:137], v[160:163], v[62:65]
	v_mfma_f32_16x16x32_bf16 v[58:61], v[148:151], v[160:163], v[58:61]
	v_mfma_f32_16x16x32_bf16 v[54:57], v[134:137], v[168:171], v[54:57]
	v_mfma_f32_16x16x32_bf16 v[50:53], v[148:151], v[168:171], v[50:53]
	v_mfma_f32_16x16x32_bf16 v[46:49], v[134:137], v[176:179], v[46:49]
	v_mfma_f32_16x16x32_bf16 v[38:41], v[148:151], v[176:179], v[38:41]
	v_mfma_f32_16x16x32_bf16 v[30:33], v[134:137], v[184:187], v[30:33]
	v_mfma_f32_16x16x32_bf16 v[18:21], v[148:151], v[184:187], v[18:21]
	s_barrier
	s_add_u32 s22, s40, 0xb0080
	s_addc_u32 s23, s41, 0
	s_add_i32 s40, s42, s50
	v_lshl_add_u64 v[130:131], s[22:23], 0, v[16:17]
	s_mov_b32 m0, s40
	s_nop 0
	global_load_lds_dwordx4 v[130:131], off
	v_lshl_add_u64 v[130:131], s[22:23], 0, v[142:143]
	s_add_i32 m0, s40, 0x2000
	s_nop 0
	global_load_lds_dwordx4 v[130:131], off
	s_waitcnt vmcnt(6)
	s_barrier
	v_mfma_f32_16x16x32_bf16 v[42:45], v[188:191], v[152:155], v[42:45]
	v_mfma_f32_16x16x32_bf16 v[34:37], v[208:211], v[152:155], v[34:37]
	v_mfma_f32_16x16x32_bf16 v[26:29], v[188:191], v[164:167], v[26:29]
	v_mfma_f32_16x16x32_bf16 v[22:25], v[208:211], v[164:167], v[22:25]
	v_mfma_f32_16x16x32_bf16 v[12:15], v[188:191], v[172:175], v[12:15]
	v_mfma_f32_16x16x32_bf16 v[8:11], v[208:211], v[172:175], v[8:11]
	v_mfma_f32_16x16x32_bf16 v[4:7], v[188:191], v[180:183], v[4:7]
	v_mfma_f32_16x16x32_bf16 v[0:3], v[208:211], v[180:183], v[0:3]
	v_mfma_f32_16x16x32_bf16 v[42:45], v[192:195], v[160:163], v[42:45]
	v_mfma_f32_16x16x32_bf16 v[34:37], v[212:215], v[160:163], v[34:37]
	v_mfma_f32_16x16x32_bf16 v[26:29], v[192:195], v[168:171], v[26:29]
	v_mfma_f32_16x16x32_bf16 v[22:25], v[212:215], v[168:171], v[22:25]
	v_mfma_f32_16x16x32_bf16 v[12:15], v[192:195], v[176:179], v[12:15]
	v_mfma_f32_16x16x32_bf16 v[8:11], v[212:215], v[176:179], v[8:11]
	v_mfma_f32_16x16x32_bf16 v[4:7], v[192:195], v[184:187], v[4:7]
	v_mfma_f32_16x16x32_bf16 v[0:3], v[212:215], v[184:187], v[0:3]
	s_add_i32 s84, s84, 2
	s_add_u32 s34, s34, 0x100
	s_addc_u32 s79, s79, 0
	s_cmp_gt_u32 s84, 41
	s_mov_b64 s[22:23], s[28:29]
	s_barrier
	s_cbranch_scc0 .LBB0_133
	v_lshl_or_b32 v132, s12, 8, v158
	v_lshl_add_u32 v130, s2, 8, v156
	v_ashrrev_i32_e32 v133, 31, v132
	v_lshlrev_b64 v[148:149], 2, v[132:133]
	v_ashrrev_i32_e32 v131, 31, v130
	v_lshl_add_u64 v[150:151], s[4:5], 0, v[148:149]
	v_lshlrev_b64 v[152:153], 12, v[130:131]
	v_lshl_add_u64 v[132:133], v[150:151], 0, v[152:153]
	global_load_dwordx4 v[160:163], v[132:133], off
	global_load_dwordx4 v[164:167], v[132:133], off offset:64
	global_load_dwordx4 v[168:171], v[132:133], off offset:512
	global_load_dwordx4 v[172:175], v[132:133], off offset:576
	v_or_b32_e32 v132, 16, v130
	v_ashrrev_i32_e32 v133, 31, v132
	v_lshlrev_b64 v[196:197], 12, v[132:133]
	v_lshl_add_u64 v[132:133], v[150:151], 0, v[196:197]
	global_load_dwordx4 v[176:179], v[132:133], off
	global_load_dwordx4 v[180:183], v[132:133], off offset:64
	global_load_dwordx4 v[184:187], v[132:133], off offset:512
	global_load_dwordx4 v[188:191], v[132:133], off offset:576
	v_or_b32_e32 v132, 32, v130
	v_ashrrev_i32_e32 v133, 31, v132
	v_or_b32_e32 v130, 48, v130
	v_lshlrev_b64 v[224:225], 12, v[132:133]
	v_ashrrev_i32_e32 v131, 31, v130
	v_lshl_add_u64 v[132:133], v[150:151], 0, v[224:225]
	v_lshlrev_b64 v[154:155], 12, v[130:131]
	global_load_dwordx4 v[192:195], v[132:133], off
	global_load_dwordx4 v[208:211], v[132:133], off offset:64
	global_load_dwordx4 v[212:215], v[132:133], off offset:512
	global_load_dwordx4 v[216:219], v[132:133], off offset:576
	v_lshl_add_u64 v[130:131], v[150:151], 0, v[154:155]
	global_load_dwordx4 v[220:223], v[130:131], off
	global_load_dwordx4 v[138:141], v[130:131], off offset:64
	global_load_dwordx4 v[134:137], v[130:131], off offset:512
	s_nop 0
	global_load_dwordx4 v[130:133], v[130:131], off offset:576
	s_waitcnt vmcnt(0) lgkmcnt(0)
	v_pk_fma_f32 v[126:127], v[126:127], 0.5, v[160:161] op_sel_hi:[1,0,1]
	v_lshl_add_u64 v[160:161], s[14:15], 0, v[152:153]
	v_lshl_add_u64 v[160:161], v[160:161], 0, v[148:149]
	v_pk_fma_f32 v[116:117], v[116:117], 0.5, v[170:171] op_sel_hi:[1,0,1]
	v_pk_fma_f32 v[114:115], v[114:115], 0.5, v[168:169] op_sel_hi:[1,0,1]
	global_store_dwordx4 v[160:161], v[114:117], off offset:512
	v_pk_fma_f32 v[112:113], v[112:113], 0.5, v[174:175] op_sel_hi:[1,0,1]
	v_pk_fma_f32 v[100:101], v[100:101], 0.5, v[186:187] op_sel_hi:[1,0,1]
	v_lshl_add_u64 v[114:115], s[14:15], 0, v[196:197]
	v_lshl_add_u64 v[114:115], v[114:115], 0, v[148:149]
	v_pk_fma_f32 v[98:99], v[98:99], 0.5, v[184:185] op_sel_hi:[1,0,1]
	global_store_dwordx4 v[114:115], v[98:101], off offset:512
	v_pk_fma_f32 v[110:111], v[110:111], 0.5, v[172:173] op_sel_hi:[1,0,1]
	v_pk_fma_f32 v[96:97], v[96:97], 0.5, v[190:191] op_sel_hi:[1,0,1]
	v_lshl_add_u64 v[98:99], s[14:15], 0, v[224:225]
	v_lshl_add_u64 v[98:99], v[98:99], 0, v[148:149]
	v_pk_fma_f32 v[84:85], v[84:85], 0.5, v[214:215] op_sel_hi:[1,0,1]
	v_pk_fma_f32 v[82:83], v[82:83], 0.5, v[212:213] op_sel_hi:[1,0,1]
	v_pk_fma_f32 v[94:95], v[94:95], 0.5, v[188:189] op_sel_hi:[1,0,1]
	global_store_dwordx4 v[98:99], v[82:85], off offset:512
	v_pk_fma_f32 v[80:81], v[80:81], 0.5, v[218:219] op_sel_hi:[1,0,1]
	v_pk_fma_f32 v[78:79], v[78:79], 0.5, v[216:217] op_sel_hi:[1,0,1]
	v_lshl_add_u64 v[82:83], s[14:15], 0, v[154:155]
	v_pk_fma_f32 v[128:129], v[128:129], 0.5, v[162:163] op_sel_hi:[1,0,1]
	v_pk_fma_f32 v[124:125], v[124:125], 0.5, v[166:167] op_sel_hi:[1,0,1]
	v_pk_fma_f32 v[122:123], v[122:123], 0.5, v[164:165] op_sel_hi:[1,0,1]
	global_store_dwordx4 v[160:161], v[110:113], off offset:576
	v_pk_fma_f32 v[108:109], v[108:109], 0.5, v[182:183] op_sel_hi:[1,0,1]
	v_pk_fma_f32 v[106:107], v[106:107], 0.5, v[180:181] op_sel_hi:[1,0,1]
	v_pk_fma_f32 v[112:113], v[120:121], 0.5, v[178:179] op_sel_hi:[1,0,1]
	v_pk_fma_f32 v[110:111], v[118:119], 0.5, v[176:177] op_sel_hi:[1,0,1]
	global_store_dwordx4 v[114:115], v[94:97], off offset:576
	v_pk_fma_f32 v[92:93], v[92:93], 0.5, v[210:211] op_sel_hi:[1,0,1]
	v_pk_fma_f32 v[90:91], v[90:91], 0.5, v[208:209] op_sel_hi:[1,0,1]
	v_pk_fma_f32 v[96:97], v[104:105], 0.5, v[194:195] op_sel_hi:[1,0,1]
	v_pk_fma_f32 v[94:95], v[102:103], 0.5, v[192:193] op_sel_hi:[1,0,1]
	global_store_dwordx4 v[98:99], v[78:81], off offset:576
	v_lshl_add_u64 v[82:83], v[82:83], 0, v[148:149]
	v_pk_fma_f32 v[76:77], v[76:77], 0.5, v[140:141] op_sel_hi:[1,0,1]
	v_pk_fma_f32 v[80:81], v[88:89], 0.5, v[222:223] op_sel_hi:[1,0,1]
	v_pk_fma_f32 v[78:79], v[86:87], 0.5, v[220:221] op_sel_hi:[1,0,1]
	v_pk_fma_f32 v[74:75], v[74:75], 0.5, v[138:139] op_sel_hi:[1,0,1]
	v_pk_fma_f32 v[72:73], v[72:73], 0.5, v[136:137] op_sel_hi:[1,0,1]
	v_pk_fma_f32 v[70:71], v[70:71], 0.5, v[134:135] op_sel_hi:[1,0,1]
	v_pk_fma_f32 v[68:69], v[68:69], 0.5, v[132:133] op_sel_hi:[1,0,1]
	v_pk_fma_f32 v[66:67], v[66:67], 0.5, v[130:131] op_sel_hi:[1,0,1]
	global_store_dwordx4 v[160:161], v[126:129], off
	global_store_dwordx4 v[160:161], v[122:125], off offset:64
	global_store_dwordx4 v[114:115], v[110:113], off
	global_store_dwordx4 v[114:115], v[106:109], off offset:64
	global_store_dwordx4 v[98:99], v[94:97], off
	global_store_dwordx4 v[98:99], v[90:93], off offset:64
	global_store_dwordx4 v[82:83], v[78:81], off
	global_store_dwordx4 v[82:83], v[74:77], off offset:64
	global_store_dwordx4 v[82:83], v[70:73], off offset:512
	global_store_dwordx4 v[82:83], v[66:69], off offset:576
	s_mov_b64 s[22:23], 0x80000
	v_lshl_add_u64 v[130:131], v[152:153], 0, s[22:23]
	s_mov_b64 s[22:23], 0x90000
	v_lshl_add_u64 v[132:133], v[152:153], 0, s[22:23]
	s_mov_b64 s[22:23], 0xa0000
	v_lshl_add_u64 v[134:135], v[152:153], 0, s[22:23]
	s_mov_b64 s[22:23], 0xb0000
	v_lshl_add_u64 v[136:137], v[152:153], 0, s[22:23]
	v_lshl_add_u64 v[78:79], v[150:151], 0, v[130:131]
	v_lshl_add_u64 v[94:95], v[150:151], 0, v[132:133]
	v_lshl_add_u64 v[110:111], v[150:151], 0, v[134:135]
	v_lshl_add_u64 v[126:127], v[150:151], 0, v[136:137]
	global_load_dwordx4 v[66:69], v[78:79], off
	global_load_dwordx4 v[70:73], v[78:79], off offset:64
	global_load_dwordx4 v[74:77], v[78:79], off offset:512
	v_lshl_add_u64 v[130:131], s[14:15], 0, v[130:131]
	global_load_dwordx4 v[78:81], v[78:79], off offset:576
	s_nop 0
	global_load_dwordx4 v[82:85], v[94:95], off
	global_load_dwordx4 v[86:89], v[94:95], off offset:64
	global_load_dwordx4 v[90:93], v[94:95], off offset:512
	v_lshl_add_u64 v[132:133], s[14:15], 0, v[132:133]
	global_load_dwordx4 v[94:97], v[94:95], off offset:576
	s_nop 0
	global_load_dwordx4 v[98:101], v[110:111], off
	global_load_dwordx4 v[102:105], v[110:111], off offset:64
	global_load_dwordx4 v[106:109], v[110:111], off offset:512
	v_lshl_add_u64 v[134:135], s[14:15], 0, v[134:135]
	global_load_dwordx4 v[110:113], v[110:111], off offset:576
	s_nop 0
	global_load_dwordx4 v[114:117], v[126:127], off
	global_load_dwordx4 v[118:121], v[126:127], off offset:64
	global_load_dwordx4 v[122:125], v[126:127], off offset:512
	s_nop 0
	global_load_dwordx4 v[126:129], v[126:127], off offset:576
	v_lshl_add_u64 v[136:137], s[14:15], 0, v[136:137]
	v_lshl_add_u64 v[130:131], v[130:131], 0, v[148:149]
	v_lshl_add_u64 v[132:133], v[132:133], 0, v[148:149]
	v_lshl_add_u64 v[134:135], v[134:135], 0, v[148:149]
	v_lshl_add_u64 v[136:137], v[136:137], 0, v[148:149]
	s_waitcnt vmcnt(0) lgkmcnt(0)
	v_pk_fma_f32 v[64:65], v[64:65], 0.5, v[68:69] op_sel_hi:[1,0,1]
	v_pk_fma_f32 v[62:63], v[62:63], 0.5, v[66:67] op_sel_hi:[1,0,1]
	v_pk_fma_f32 v[60:61], v[60:61], 0.5, v[72:73] op_sel_hi:[1,0,1]
	v_pk_fma_f32 v[58:59], v[58:59], 0.5, v[70:71] op_sel_hi:[1,0,1]
	v_pk_fma_f32 v[44:45], v[44:45], 0.5, v[76:77] op_sel_hi:[1,0,1]
	v_pk_fma_f32 v[42:43], v[42:43], 0.5, v[74:75] op_sel_hi:[1,0,1]
	v_pk_fma_f32 v[36:37], v[36:37], 0.5, v[80:81] op_sel_hi:[1,0,1]
	v_pk_fma_f32 v[34:35], v[34:35], 0.5, v[78:79] op_sel_hi:[1,0,1]
	v_pk_fma_f32 v[56:57], v[56:57], 0.5, v[84:85] op_sel_hi:[1,0,1]
	v_pk_fma_f32 v[54:55], v[54:55], 0.5, v[82:83] op_sel_hi:[1,0,1]
	v_pk_fma_f32 v[52:53], v[52:53], 0.5, v[88:89] op_sel_hi:[1,0,1]
	v_pk_fma_f32 v[50:51], v[50:51], 0.5, v[86:87] op_sel_hi:[1,0,1]
	v_pk_fma_f32 v[28:29], v[28:29], 0.5, v[92:93] op_sel_hi:[1,0,1]
	v_pk_fma_f32 v[26:27], v[26:27], 0.5, v[90:91] op_sel_hi:[1,0,1]
	v_pk_fma_f32 v[24:25], v[24:25], 0.5, v[96:97] op_sel_hi:[1,0,1]
	v_pk_fma_f32 v[22:23], v[22:23], 0.5, v[94:95] op_sel_hi:[1,0,1]
	v_pk_fma_f32 v[48:49], v[48:49], 0.5, v[100:101] op_sel_hi:[1,0,1]
	v_pk_fma_f32 v[46:47], v[46:47], 0.5, v[98:99] op_sel_hi:[1,0,1]
	v_pk_fma_f32 v[40:41], v[40:41], 0.5, v[104:105] op_sel_hi:[1,0,1]
	v_pk_fma_f32 v[38:39], v[38:39], 0.5, v[102:103] op_sel_hi:[1,0,1]
	v_pk_fma_f32 v[14:15], v[14:15], 0.5, v[108:109] op_sel_hi:[1,0,1]
	v_pk_fma_f32 v[12:13], v[12:13], 0.5, v[106:107] op_sel_hi:[1,0,1]
	v_pk_fma_f32 v[10:11], v[10:11], 0.5, v[112:113] op_sel_hi:[1,0,1]
	v_pk_fma_f32 v[8:9], v[8:9], 0.5, v[110:111] op_sel_hi:[1,0,1]
	v_pk_fma_f32 v[32:33], v[32:33], 0.5, v[116:117] op_sel_hi:[1,0,1]
	v_pk_fma_f32 v[30:31], v[30:31], 0.5, v[114:115] op_sel_hi:[1,0,1]
	v_pk_fma_f32 v[20:21], v[20:21], 0.5, v[120:121] op_sel_hi:[1,0,1]
	v_pk_fma_f32 v[18:19], v[18:19], 0.5, v[118:119] op_sel_hi:[1,0,1]
	v_pk_fma_f32 v[6:7], v[6:7], 0.5, v[124:125] op_sel_hi:[1,0,1]
	v_pk_fma_f32 v[4:5], v[4:5], 0.5, v[122:123] op_sel_hi:[1,0,1]
	v_pk_fma_f32 v[2:3], v[2:3], 0.5, v[128:129] op_sel_hi:[1,0,1]
	v_pk_fma_f32 v[0:1], v[0:1], 0.5, v[126:127] op_sel_hi:[1,0,1]
	global_store_dwordx4 v[130:131], v[62:65], off
	global_store_dwordx4 v[130:131], v[58:61], off offset:64
	global_store_dwordx4 v[130:131], v[42:45], off offset:512
	global_store_dwordx4 v[130:131], v[34:37], off offset:576
	global_store_dwordx4 v[132:133], v[54:57], off
	global_store_dwordx4 v[132:133], v[50:53], off offset:64
	global_store_dwordx4 v[132:133], v[26:29], off offset:512
	global_store_dwordx4 v[132:133], v[22:25], off offset:576
	global_store_dwordx4 v[134:135], v[46:49], off
	global_store_dwordx4 v[134:135], v[38:41], off offset:64
	global_store_dwordx4 v[134:135], v[12:15], off offset:512
	global_store_dwordx4 v[134:135], v[8:11], off offset:576
	global_store_dwordx4 v[136:137], v[30:33], off
	global_store_dwordx4 v[136:137], v[18:21], off offset:64
	global_store_dwordx4 v[136:137], v[4:7], off offset:512
	global_store_dwordx4 v[136:137], v[0:3], off offset:576
	s_and_b64 vcc, exec, s[38:39]
	s_mov_b32 s12, s82
	s_mov_b32 s2, s83
	s_mov_b64 s[28:29], s[18:19]
	s_mov_b64 s[22:23], s[16:17]
	s_mov_b32 s86, 0x38c0000
	s_cbranch_vccz .LBB0_122
	s_waitcnt vmcnt(0)
	s_cmpk_gt_u32 s48, 0xff
	s_cbranch_scc1 .LBB0_137
	s_barrier

.LBB0_146:
	s_ashr_i32 s29, s28, 31
	v_cmp_lt_i64_e32 vcc, s[22:23], v[198:199]
	s_lshl_b64 s[22:23], s[28:29], 19
	s_add_u32 s40, s30, s22
	s_addc_u32 s41, s31, s23
	s_and_b64 s[22:23], vcc, exec
	s_cselect_b32 s12, s41, s19
	s_cselect_b32 s29, s40, s18
	s_ashr_i32 s9, s8, 31
	s_lshl_b64 s[22:23], s[8:9], 19
	s_add_u32 s42, s49, s22
	s_addc_u32 s43, s50, s23
	s_and_b64 s[22:23], vcc, exec
	s_cselect_b32 s9, s43, s17
	s_cselect_b32 s34, s42, s16
	s_add_u32 s61, s16, 0x100
	s_addc_u32 s79, s17, 0
	s_add_u32 s16, s18, 0x40080
	v_mov_b32_e32 v0, 0
	s_addc_u32 s17, s19, 0
	s_mov_b32 s82, -2
	v_mov_b32_e32 v1, v0
	v_mov_b32_e32 v2, v0
	v_mov_b32_e32 v3, v0
	v_mov_b32_e32 v8, v0
	v_mov_b32_e32 v9, v0
	v_mov_b32_e32 v10, v0
	v_mov_b32_e32 v11, v0
	v_mov_b32_e32 v18, v0
	v_mov_b32_e32 v19, v0
	v_mov_b32_e32 v20, v0
	v_mov_b32_e32 v21, v0
	v_mov_b32_e32 v26, v0
	v_mov_b32_e32 v27, v0
	v_mov_b32_e32 v28, v0
	v_mov_b32_e32 v29, v0
	s_waitcnt lgkmcnt(0)
	v_mov_b32_e32 v34, v0
	v_mov_b32_e32 v35, v0
	v_mov_b32_e32 v36, v0
	v_mov_b32_e32 v37, v0
	v_mov_b32_e32 v42, v0
	v_mov_b32_e32 v43, v0
	v_mov_b32_e32 v44, v0
	v_mov_b32_e32 v45, v0
	v_mov_b32_e32 v50, v0
	v_mov_b32_e32 v51, v0
	v_mov_b32_e32 v52, v0
	v_mov_b32_e32 v53, v0
	v_mov_b32_e32 v58, v0
	v_mov_b32_e32 v59, v0
	v_mov_b32_e32 v60, v0
	v_mov_b32_e32 v61, v0
	v_mov_b32_e32 v4, v0
	v_mov_b32_e32 v5, v0
	v_mov_b32_e32 v6, v0
	v_mov_b32_e32 v7, v0
	v_mov_b32_e32 v12, v0
	v_mov_b32_e32 v13, v0
	v_mov_b32_e32 v14, v0
	v_mov_b32_e32 v15, v0
	v_mov_b32_e32 v22, v0
	v_mov_b32_e32 v23, v0
	v_mov_b32_e32 v24, v0
	v_mov_b32_e32 v25, v0
	v_mov_b32_e32 v30, v0
	v_mov_b32_e32 v31, v0
	v_mov_b32_e32 v32, v0
	v_mov_b32_e32 v33, v0
	v_mov_b32_e32 v38, v0
	v_mov_b32_e32 v39, v0
	v_mov_b32_e32 v40, v0
	v_mov_b32_e32 v41, v0
	v_mov_b32_e32 v46, v0
	v_mov_b32_e32 v47, v0
	v_mov_b32_e32 v48, v0
	v_mov_b32_e32 v49, v0
	v_mov_b32_e32 v54, v0
	v_mov_b32_e32 v55, v0
	v_mov_b32_e32 v56, v0
	v_mov_b32_e32 v57, v0
	v_mov_b32_e32 v62, v0
	v_mov_b32_e32 v63, v0
	v_mov_b32_e32 v64, v0
	v_mov_b32_e32 v65, v0
	v_mov_b32_e32 v66, v0
	v_mov_b32_e32 v67, v0
	v_mov_b32_e32 v68, v0
	v_mov_b32_e32 v69, v0
	v_mov_b32_e32 v74, v0
	v_mov_b32_e32 v75, v0
	v_mov_b32_e32 v76, v0
	v_mov_b32_e32 v77, v0
	v_mov_b32_e32 v82, v0
	v_mov_b32_e32 v83, v0
	v_mov_b32_e32 v84, v0
	v_mov_b32_e32 v85, v0
	v_mov_b32_e32 v90, v0
	v_mov_b32_e32 v91, v0
	v_mov_b32_e32 v92, v0
	v_mov_b32_e32 v93, v0
	v_mov_b32_e32 v98, v0
	v_mov_b32_e32 v99, v0
	v_mov_b32_e32 v100, v0
	v_mov_b32_e32 v101, v0
	v_mov_b32_e32 v106, v0
	v_mov_b32_e32 v107, v0
	v_mov_b32_e32 v108, v0
	v_mov_b32_e32 v109, v0
	v_mov_b32_e32 v114, v0
	v_mov_b32_e32 v115, v0
	v_mov_b32_e32 v116, v0
	v_mov_b32_e32 v117, v0
	v_mov_b32_e32 v122, v0
	v_mov_b32_e32 v123, v0
	v_mov_b32_e32 v124, v0
	v_mov_b32_e32 v125, v0
	v_mov_b32_e32 v70, v0
	v_mov_b32_e32 v71, v0
	v_mov_b32_e32 v72, v0
	v_mov_b32_e32 v73, v0
	v_mov_b32_e32 v78, v0
	v_mov_b32_e32 v79, v0
	v_mov_b32_e32 v80, v0
	v_mov_b32_e32 v81, v0
	v_mov_b32_e32 v86, v0
	v_mov_b32_e32 v87, v0
	v_mov_b32_e32 v88, v0
	v_mov_b32_e32 v89, v0
	v_mov_b32_e32 v94, v0
	v_mov_b32_e32 v95, v0
	v_mov_b32_e32 v96, v0
	v_mov_b32_e32 v97, v0
	v_mov_b32_e32 v102, v0
	v_mov_b32_e32 v103, v0
	v_mov_b32_e32 v104, v0
	v_mov_b32_e32 v105, v0
	v_mov_b32_e32 v110, v0
	v_mov_b32_e32 v111, v0
	v_mov_b32_e32 v112, v0
	v_mov_b32_e32 v113, v0
	v_mov_b32_e32 v118, v0
	v_mov_b32_e32 v119, v0
	v_mov_b32_e32 v120, v0
	v_mov_b32_e32 v121, v0
	v_mov_b32_e32 v126, v0
	v_mov_b32_e32 v127, v0
	v_mov_b32_e32 v128, v0
	v_mov_b32_e32 v129, v0
.LBB0_147:
	s_add_u32 s18, s16, 0xfffc0080
	s_addc_u32 s19, s17, -1
	s_add_i32 s83, 0, 0x10000
	v_add_u32_e32 v140, s83, v143
	ds_read_b128 v[146:149], v140
	ds_read_b128 v[150:153], v140 offset:1024
	ds_read_b128 v[154:157], v140 offset:2048
	ds_read_b128 v[158:161], v140 offset:3072
	s_cmp_eq_u32 s82, 12
	s_cselect_b32 s23, s12, s19
	s_cselect_b32 s22, s29, s18
	s_cselect_b32 s19, s9, s79
	s_cselect_b32 s18, s34, s61
	v_lshl_add_u64 v[140:141], s[16:17], 0, v[138:139]
	s_add_i32 m0, s15, 0xc000
	ds_read_b128 v[162:165], v145
	ds_read_b128 v[166:169], v145 offset:1024
	ds_read_b128 v[170:173], v145 offset:2048
	ds_read_b128 v[174:177], v145 offset:3072
	ds_read_b128 v[178:181], v145 offset:4096
	ds_read_b128 v[182:185], v145 offset:5120
	ds_read_b128 v[186:189], v145 offset:6144
	ds_read_b128 v[190:193], v145 offset:7168
	global_load_lds_dwordx4 v[140:141], off
	v_lshl_add_u64 v[140:141], s[16:17], 0, v[136:137]
	s_add_i32 m0, s15, 0xe000
	s_nop 0
	global_load_lds_dwordx4 v[140:141], off
	s_waitcnt lgkmcnt(8)
	s_barrier
	s_waitcnt lgkmcnt(0)
	s_waitcnt lgkmcnt(0)
	v_mfma_f32_16x16x32_bf16 v[126:129], v[146:149], v[162:165], v[126:129]
	v_mfma_f32_16x16x32_bf16 v[118:121], v[154:157], v[162:165], v[118:121]
	v_mfma_f32_16x16x32_bf16 v[110:113], v[146:149], v[170:173], v[110:113]
	v_mfma_f32_16x16x32_bf16 v[102:105], v[154:157], v[170:173], v[102:105]
	v_mfma_f32_16x16x32_bf16 v[94:97], v[146:149], v[178:181], v[94:97]
	v_mfma_f32_16x16x32_bf16 v[86:89], v[154:157], v[178:181], v[86:89]
	v_mfma_f32_16x16x32_bf16 v[78:81], v[146:149], v[186:189], v[78:81]
	v_mfma_f32_16x16x32_bf16 v[70:73], v[154:157], v[186:189], v[70:73]
	v_mfma_f32_16x16x32_bf16 v[126:129], v[150:153], v[166:169], v[126:129]
	v_mfma_f32_16x16x32_bf16 v[118:121], v[158:161], v[166:169], v[118:121]
	v_mfma_f32_16x16x32_bf16 v[110:113], v[150:153], v[174:177], v[110:113]
	v_mfma_f32_16x16x32_bf16 v[102:105], v[158:161], v[174:177], v[102:105]
	v_mfma_f32_16x16x32_bf16 v[94:97], v[150:153], v[182:185], v[94:97]
	v_mfma_f32_16x16x32_bf16 v[86:89], v[158:161], v[182:185], v[86:89]
	v_mfma_f32_16x16x32_bf16 v[78:81], v[150:153], v[190:193], v[78:81]
	v_mfma_f32_16x16x32_bf16 v[70:73], v[158:161], v[190:193], v[70:73]
	s_barrier
	s_add_i32 s86, 0, 0x14000
	v_add_u32_e32 v140, s86, v143
	s_add_i32 s83, s83, s51
	ds_read_b128 v[194:197], v140
	ds_read_b128 v[208:211], v140 offset:1024
	ds_read_b128 v[212:215], v140 offset:2048
	ds_read_b128 v[216:219], v140 offset:3072
	v_lshl_add_u64 v[140:141], s[18:19], 0, v[16:17]
	s_mov_b32 m0, s83
	v_lshl_add_u64 v[220:221], s[18:19], 0, v[130:131]
	global_load_lds_dwordx4 v[140:141], off
	s_add_i32 m0, s83, 0x2000
	s_nop 0
	global_load_lds_dwordx4 v[220:221], off
	s_barrier
	s_waitcnt lgkmcnt(0)
	s_waitcnt lgkmcnt(0)
	v_mfma_f32_16x16x32_bf16 v[122:125], v[194:197], v[162:165], v[122:125]
	v_mfma_f32_16x16x32_bf16 v[114:117], v[212:215], v[162:165], v[114:117]
	v_mfma_f32_16x16x32_bf16 v[106:109], v[194:197], v[170:173], v[106:109]
	v_mfma_f32_16x16x32_bf16 v[98:101], v[212:215], v[170:173], v[98:101]
	v_mfma_f32_16x16x32_bf16 v[90:93], v[194:197], v[178:181], v[90:93]
	v_mfma_f32_16x16x32_bf16 v[82:85], v[212:215], v[178:181], v[82:85]
	v_mfma_f32_16x16x32_bf16 v[74:77], v[194:197], v[186:189], v[74:77]
	v_mfma_f32_16x16x32_bf16 v[66:69], v[212:215], v[186:189], v[66:69]
	v_mfma_f32_16x16x32_bf16 v[122:125], v[208:211], v[166:169], v[122:125]
	v_mfma_f32_16x16x32_bf16 v[114:117], v[216:219], v[166:169], v[114:117]
	v_mfma_f32_16x16x32_bf16 v[106:109], v[208:211], v[174:177], v[106:109]
	v_mfma_f32_16x16x32_bf16 v[98:101], v[216:219], v[174:177], v[98:101]
	v_mfma_f32_16x16x32_bf16 v[90:93], v[208:211], v[182:185], v[90:93]
	v_mfma_f32_16x16x32_bf16 v[82:85], v[216:219], v[182:185], v[82:85]
	v_mfma_f32_16x16x32_bf16 v[74:77], v[208:211], v[190:193], v[74:77]
	v_mfma_f32_16x16x32_bf16 v[66:69], v[216:219], v[190:193], v[66:69]
	s_mov_b32 m0, s15
	v_lshl_add_u64 v[222:223], s[22:23], 0, v[134:135]
	s_barrier
	ds_read_b128 v[162:165], v145 offset:16384
	ds_read_b128 v[166:169], v145 offset:17408
	ds_read_b128 v[170:173], v145 offset:18432
	ds_read_b128 v[174:177], v145 offset:19456
	ds_read_b128 v[178:181], v145 offset:20480
	ds_read_b128 v[182:185], v145 offset:21504
	ds_read_b128 v[186:189], v145 offset:22528
	ds_read_b128 v[190:193], v145 offset:23552
	global_load_lds_dwordx4 v[222:223], off
	v_lshl_add_u64 v[224:225], s[22:23], 0, v[132:133]
	s_mov_b32 m0, s54
	s_nop 0
	global_load_lds_dwordx4 v[224:225], off
	s_barrier
	s_waitcnt lgkmcnt(0)
	s_waitcnt lgkmcnt(0)
	v_mfma_f32_16x16x32_bf16 v[62:65], v[146:149], v[162:165], v[62:65]
	v_mfma_f32_16x16x32_bf16 v[54:57], v[154:157], v[162:165], v[54:57]
	v_mfma_f32_16x16x32_bf16 v[46:49], v[146:149], v[170:173], v[46:49]
	v_mfma_f32_16x16x32_bf16 v[38:41], v[154:157], v[170:173], v[38:41]
	v_mfma_f32_16x16x32_bf16 v[30:33], v[146:149], v[178:181], v[30:33]
	v_mfma_f32_16x16x32_bf16 v[22:25], v[154:157], v[178:181], v[22:25]
	v_mfma_f32_16x16x32_bf16 v[12:15], v[146:149], v[186:189], v[12:15]
	v_mfma_f32_16x16x32_bf16 v[4:7], v[154:157], v[186:189], v[4:7]
	v_mfma_f32_16x16x32_bf16 v[62:65], v[150:153], v[166:169], v[62:65]
	v_mfma_f32_16x16x32_bf16 v[54:57], v[158:161], v[166:169], v[54:57]
	v_mfma_f32_16x16x32_bf16 v[46:49], v[150:153], v[174:177], v[46:49]
	v_mfma_f32_16x16x32_bf16 v[38:41], v[158:161], v[174:177], v[38:41]
	v_mfma_f32_16x16x32_bf16 v[30:33], v[150:153], v[182:185], v[30:33]
	v_mfma_f32_16x16x32_bf16 v[22:25], v[158:161], v[182:185], v[22:25]
	v_mfma_f32_16x16x32_bf16 v[12:15], v[150:153], v[190:193], v[12:15]
	v_mfma_f32_16x16x32_bf16 v[4:7], v[158:161], v[190:193], v[4:7]
	s_barrier
	s_add_u32 s84, s18, 0x40000
	s_addc_u32 s85, s19, 0
	s_add_i32 s83, s86, s51
	v_lshl_add_u64 v[146:147], s[84:85], 0, v[16:17]
	s_mov_b32 m0, s83
	s_nop 0
	global_load_lds_dwordx4 v[146:147], off
	v_lshl_add_u64 v[146:147], s[84:85], 0, v[130:131]
	s_add_i32 m0, s83, 0x2000
	s_nop 0
	global_load_lds_dwordx4 v[146:147], off
	s_waitcnt vmcnt(6)
	s_barrier
	v_mfma_f32_16x16x32_bf16 v[58:61], v[194:197], v[162:165], v[58:61]
	v_mfma_f32_16x16x32_bf16 v[50:53], v[212:215], v[162:165], v[50:53]
	v_mfma_f32_16x16x32_bf16 v[42:45], v[194:197], v[170:173], v[42:45]
	v_mfma_f32_16x16x32_bf16 v[34:37], v[212:215], v[170:173], v[34:37]
	v_mfma_f32_16x16x32_bf16 v[26:29], v[194:197], v[178:181], v[26:29]
	v_mfma_f32_16x16x32_bf16 v[18:21], v[212:215], v[178:181], v[18:21]
	v_mfma_f32_16x16x32_bf16 v[8:11], v[194:197], v[186:189], v[8:11]
	v_mfma_f32_16x16x32_bf16 v[0:3], v[212:215], v[186:189], v[0:3]
	v_mfma_f32_16x16x32_bf16 v[58:61], v[208:211], v[166:169], v[58:61]
	v_mfma_f32_16x16x32_bf16 v[50:53], v[216:219], v[166:169], v[50:53]
	v_mfma_f32_16x16x32_bf16 v[42:45], v[208:211], v[174:177], v[42:45]
	v_mfma_f32_16x16x32_bf16 v[34:37], v[216:219], v[174:177], v[34:37]
	v_mfma_f32_16x16x32_bf16 v[26:29], v[208:211], v[182:185], v[26:29]
	v_mfma_f32_16x16x32_bf16 v[18:21], v[216:219], v[182:185], v[18:21]
	v_mfma_f32_16x16x32_bf16 v[8:11], v[208:211], v[190:193], v[8:11]
	v_mfma_f32_16x16x32_bf16 v[0:3], v[216:219], v[190:193], v[0:3]
	s_add_i32 s83, 0, 0x18000
	v_add_u32_e32 v158, s83, v143
	s_barrier
	ds_read_b128 v[146:149], v158
	ds_read_b128 v[150:153], v158 offset:1024
	ds_read_b128 v[154:157], v158 offset:2048
	ds_read_b128 v[158:161], v158 offset:3072
	s_add_u32 s22, s22, 0x40000
	s_addc_u32 s23, s23, 0
	s_mov_b32 m0, s55
	v_lshl_add_u64 v[194:195], s[22:23], 0, v[134:135]
	ds_read_b128 v[162:165], v145 offset:32768
	ds_read_b128 v[166:169], v145 offset:33792
	ds_read_b128 v[170:173], v145 offset:34816
	ds_read_b128 v[174:177], v145 offset:35840
	ds_read_b128 v[178:181], v145 offset:36864
	ds_read_b128 v[182:185], v145 offset:37888
	ds_read_b128 v[186:189], v145 offset:38912
	ds_read_b128 v[190:193], v145 offset:39936
	global_load_lds_dwordx4 v[194:195], off
	v_lshl_add_u64 v[194:195], s[22:23], 0, v[132:133]
	s_mov_b32 m0, s56
	s_nop 0
	global_load_lds_dwordx4 v[194:195], off
	s_waitcnt lgkmcnt(8)
	s_barrier
	s_waitcnt lgkmcnt(0)
	s_waitcnt lgkmcnt(0)
	v_mfma_f32_16x16x32_bf16 v[126:129], v[146:149], v[162:165], v[126:129]
	v_mfma_f32_16x16x32_bf16 v[118:121], v[154:157], v[162:165], v[118:121]
	v_mfma_f32_16x16x32_bf16 v[110:113], v[146:149], v[170:173], v[110:113]
	v_mfma_f32_16x16x32_bf16 v[102:105], v[154:157], v[170:173], v[102:105]
	v_mfma_f32_16x16x32_bf16 v[94:97], v[146:149], v[178:181], v[94:97]
	v_mfma_f32_16x16x32_bf16 v[86:89], v[154:157], v[178:181], v[86:89]
	v_mfma_f32_16x16x32_bf16 v[78:81], v[146:149], v[186:189], v[78:81]
	v_mfma_f32_16x16x32_bf16 v[70:73], v[154:157], v[186:189], v[70:73]
	v_mfma_f32_16x16x32_bf16 v[126:129], v[150:153], v[166:169], v[126:129]
	v_mfma_f32_16x16x32_bf16 v[118:121], v[158:161], v[166:169], v[118:121]
	v_mfma_f32_16x16x32_bf16 v[110:113], v[150:153], v[174:177], v[110:113]
	v_mfma_f32_16x16x32_bf16 v[102:105], v[158:161], v[174:177], v[102:105]
	v_mfma_f32_16x16x32_bf16 v[94:97], v[150:153], v[182:185], v[94:97]
	v_mfma_f32_16x16x32_bf16 v[86:89], v[158:161], v[182:185], v[86:89]
	v_mfma_f32_16x16x32_bf16 v[78:81], v[150:153], v[190:193], v[78:81]
	v_mfma_f32_16x16x32_bf16 v[70:73], v[158:161], v[190:193], v[70:73]
	s_barrier
	s_add_i32 s22, 0, 0x1c000
	s_add_i32 s23, s83, s51
	v_add_u32_e32 v216, s22, v143
	v_lshl_add_u64 v[140:141], v[140:141], 0, s[10:11]
	s_mov_b32 m0, s23
	ds_read_b128 v[194:197], v216
	ds_read_b128 v[208:211], v216 offset:1024
	ds_read_b128 v[212:215], v216 offset:2048
	ds_read_b128 v[216:219], v216 offset:3072
	global_load_lds_dwordx4 v[140:141], off
	v_lshl_add_u64 v[140:141], v[220:221], 0, s[10:11]
	s_add_i32 m0, s23, 0x2000
	s_nop 0
	global_load_lds_dwordx4 v[140:141], off
	s_barrier
	s_waitcnt lgkmcnt(0)
	s_waitcnt lgkmcnt(0)
	v_mfma_f32_16x16x32_bf16 v[122:125], v[194:197], v[162:165], v[122:125]
	v_mfma_f32_16x16x32_bf16 v[114:117], v[212:215], v[162:165], v[114:117]
	v_mfma_f32_16x16x32_bf16 v[106:109], v[194:197], v[170:173], v[106:109]
	v_mfma_f32_16x16x32_bf16 v[98:101], v[212:215], v[170:173], v[98:101]
	v_mfma_f32_16x16x32_bf16 v[90:93], v[194:197], v[178:181], v[90:93]
	v_mfma_f32_16x16x32_bf16 v[82:85], v[212:215], v[178:181], v[82:85]
	v_mfma_f32_16x16x32_bf16 v[74:77], v[194:197], v[186:189], v[74:77]
	v_mfma_f32_16x16x32_bf16 v[66:69], v[212:215], v[186:189], v[66:69]
	v_mfma_f32_16x16x32_bf16 v[122:125], v[208:211], v[166:169], v[122:125]
	v_mfma_f32_16x16x32_bf16 v[114:117], v[216:219], v[166:169], v[114:117]
	v_mfma_f32_16x16x32_bf16 v[106:109], v[208:211], v[174:177], v[106:109]
	v_mfma_f32_16x16x32_bf16 v[98:101], v[216:219], v[174:177], v[98:101]
	v_mfma_f32_16x16x32_bf16 v[90:93], v[208:211], v[182:185], v[90:93]
	v_mfma_f32_16x16x32_bf16 v[82:85], v[216:219], v[182:185], v[82:85]
	v_mfma_f32_16x16x32_bf16 v[74:77], v[208:211], v[190:193], v[74:77]
	v_mfma_f32_16x16x32_bf16 v[66:69], v[216:219], v[190:193], v[66:69]
	s_mov_b32 m0, s57
	v_lshl_add_u64 v[140:141], v[222:223], 0, s[10:11]
	s_barrier
	ds_read_b128 v[162:165], v145 offset:49152
	ds_read_b128 v[166:169], v145 offset:50176
	ds_read_b128 v[170:173], v145 offset:51200
	ds_read_b128 v[174:177], v145 offset:52224
	ds_read_b128 v[178:181], v145 offset:53248
	ds_read_b128 v[182:185], v145 offset:54272
	ds_read_b128 v[186:189], v145 offset:55296
	ds_read_b128 v[190:193], v145 offset:56320
	global_load_lds_dwordx4 v[140:141], off
	v_lshl_add_u64 v[140:141], v[224:225], 0, s[10:11]
	s_mov_b32 m0, s58
	s_nop 0
	global_load_lds_dwordx4 v[140:141], off
	s_barrier
	s_waitcnt lgkmcnt(0)
	s_waitcnt lgkmcnt(0)
	v_mfma_f32_16x16x32_bf16 v[62:65], v[146:149], v[162:165], v[62:65]
	v_mfma_f32_16x16x32_bf16 v[54:57], v[154:157], v[162:165], v[54:57]
	v_mfma_f32_16x16x32_bf16 v[46:49], v[146:149], v[170:173], v[46:49]
	v_mfma_f32_16x16x32_bf16 v[38:41], v[154:157], v[170:173], v[38:41]
	v_mfma_f32_16x16x32_bf16 v[30:33], v[146:149], v[178:181], v[30:33]
	v_mfma_f32_16x16x32_bf16 v[22:25], v[154:157], v[178:181], v[22:25]
	v_mfma_f32_16x16x32_bf16 v[12:15], v[146:149], v[186:189], v[12:15]
	v_mfma_f32_16x16x32_bf16 v[4:7], v[154:157], v[186:189], v[4:7]
	v_mfma_f32_16x16x32_bf16 v[62:65], v[150:153], v[166:169], v[62:65]
	v_mfma_f32_16x16x32_bf16 v[54:57], v[158:161], v[166:169], v[54:57]
	v_mfma_f32_16x16x32_bf16 v[46:49], v[150:153], v[174:177], v[46:49]
	v_mfma_f32_16x16x32_bf16 v[38:41], v[158:161], v[174:177], v[38:41]
	v_mfma_f32_16x16x32_bf16 v[30:33], v[150:153], v[182:185], v[30:33]
	v_mfma_f32_16x16x32_bf16 v[22:25], v[158:161], v[182:185], v[22:25]
	v_mfma_f32_16x16x32_bf16 v[12:15], v[150:153], v[190:193], v[12:15]
	v_mfma_f32_16x16x32_bf16 v[4:7], v[158:161], v[190:193], v[4:7]
	s_barrier
	s_add_u32 s18, s18, 0x40080
	s_addc_u32 s19, s19, 0
	s_add_i32 s22, s22, s51
	v_lshl_add_u64 v[140:141], s[18:19], 0, v[16:17]
	s_mov_b32 m0, s22
	s_nop 0
	global_load_lds_dwordx4 v[140:141], off
	v_lshl_add_u64 v[140:141], s[18:19], 0, v[130:131]
	s_add_i32 m0, s22, 0x2000
	s_nop 0
	global_load_lds_dwordx4 v[140:141], off
	s_waitcnt vmcnt(6)
	s_barrier
	v_mfma_f32_16x16x32_bf16 v[58:61], v[194:197], v[162:165], v[58:61]
	v_mfma_f32_16x16x32_bf16 v[50:53], v[212:215], v[162:165], v[50:53]
	v_mfma_f32_16x16x32_bf16 v[42:45], v[194:197], v[170:173], v[42:45]
	v_mfma_f32_16x16x32_bf16 v[34:37], v[212:215], v[170:173], v[34:37]
	v_mfma_f32_16x16x32_bf16 v[26:29], v[194:197], v[178:181], v[26:29]
	v_mfma_f32_16x16x32_bf16 v[18:21], v[212:215], v[178:181], v[18:21]
	v_mfma_f32_16x16x32_bf16 v[8:11], v[194:197], v[186:189], v[8:11]
	v_mfma_f32_16x16x32_bf16 v[0:3], v[212:215], v[186:189], v[0:3]
	v_mfma_f32_16x16x32_bf16 v[58:61], v[208:211], v[166:169], v[58:61]
	v_mfma_f32_16x16x32_bf16 v[50:53], v[216:219], v[166:169], v[50:53]
	v_mfma_f32_16x16x32_bf16 v[42:45], v[208:211], v[174:177], v[42:45]
	v_mfma_f32_16x16x32_bf16 v[34:37], v[216:219], v[174:177], v[34:37]
	v_mfma_f32_16x16x32_bf16 v[26:29], v[208:211], v[182:185], v[26:29]
	v_mfma_f32_16x16x32_bf16 v[18:21], v[216:219], v[182:185], v[18:21]
	v_mfma_f32_16x16x32_bf16 v[8:11], v[208:211], v[190:193], v[8:11]
	v_mfma_f32_16x16x32_bf16 v[0:3], v[216:219], v[190:193], v[0:3]
	s_add_i32 s82, s82, 2
	s_add_u32 s61, s61, 0x100
	s_addc_u32 s79, s79, 0
	s_add_u32 s16, s16, 0x100
	s_addc_u32 s17, s17, 0
	s_cmp_gt_u32 s82, 13
	s_barrier
	s_cbranch_scc0 .LBB0_147
	v_mul_f32_e32 v147, 0xbfb8aa3b, v126
	v_exp_f32_e32 v147, v147
	v_lshl_or_b32 v148, s2, 7, v144
	v_lshl_add_u32 v146, s14, 8, v142
	v_ashrrev_i32_e32 v149, 31, v148
	v_add_f32_e32 v147, 1.0, v147
	v_rcp_f32_e32 v147, v147
	v_mov_b64_e32 v[140:141], s[94:95]
	v_mad_i64_i32 v[150:151], s[16:17], v146, s65, v[140:141]
	v_mul_f32_e32 v126, v126, v147
	v_mul_f32_e32 v122, v126, v122
	v_mul_f32_e32 v126, 0xbfb8aa3b, v127
	v_exp_f32_e32 v126, v126
	s_nop 0
	v_add_f32_e32 v126, 1.0, v126
	v_rcp_f32_e32 v126, v126
	s_nop 0
	v_mul_f32_e32 v126, v127, v126
	v_mul_f32_e32 v123, v126, v123
	v_mul_f32_e32 v126, 0xbfb8aa3b, v128
	v_exp_f32_e32 v126, v126
	s_nop 0
	v_add_f32_e32 v126, 1.0, v126
	v_rcp_f32_e32 v126, v126
	s_nop 0
	v_mul_f32_e32 v126, v128, v126
	v_mul_f32_e32 v124, v126, v124
	v_mul_f32_e32 v126, 0xbfb8aa3b, v129
	v_exp_f32_e32 v126, v126
	s_nop 0
	v_add_f32_e32 v126, 1.0, v126
	v_rcp_f32_e32 v126, v126
	s_nop 0
	v_mul_f32_e32 v126, v129, v126
	v_mul_f32_e32 v125, v126, v125
	v_mul_f32_e32 v126, 0xbfb8aa3b, v118
	v_exp_f32_e32 v126, v126
	s_nop 0
	v_add_f32_e32 v126, 1.0, v126
	v_rcp_f32_e32 v126, v126
	s_nop 0
	v_mul_f32_e32 v118, v118, v126
	v_mul_f32_e32 v118, v118, v114
	v_mul_f32_e32 v114, 0xbfb8aa3b, v119
	v_exp_f32_e32 v114, v114
	s_nop 0
	v_add_f32_e32 v114, 1.0, v114
	v_rcp_f32_e32 v114, v114
	s_nop 0
	v_mul_f32_e32 v114, v119, v114
	v_mul_f32_e32 v119, v114, v115
	v_mul_f32_e32 v114, 0xbfb8aa3b, v120
	v_exp_f32_e32 v114, v114
	v_cvt_pk_bf16_f32 v118, v118, v119
	s_nop 0
	v_add_f32_e32 v114, 1.0, v114
	v_rcp_f32_e32 v114, v114
	s_nop 0
	v_mul_f32_e32 v114, v120, v114
	v_mul_f32_e32 v126, v114, v116
	v_mul_f32_e32 v114, 0xbfb8aa3b, v121
	v_exp_f32_e32 v114, v114
	v_cvt_pk_bf16_f32 v116, v122, v123
	s_nop 0
	v_add_f32_e32 v114, 1.0, v114
	v_rcp_f32_e32 v114, v114
	s_nop 0
	v_mul_f32_e32 v114, v121, v114
	v_mul_f32_e32 v127, v114, v117
	v_lshlrev_b64 v[114:115], 1, v[148:149]
	v_lshl_add_u64 v[120:121], v[150:151], 0, v[114:115]
	v_cvt_pk_bf16_f32 v117, v124, v125
	v_cvt_pk_bf16_f32 v119, v126, v127
	global_store_dwordx4 v[120:121], v[116:119], off
	s_nop 1
	v_mul_f32_e32 v118, 0xbfb8aa3b, v110
	v_exp_f32_e32 v118, v118
	v_or_b32_e32 v116, 16, v146
	v_mad_i64_i32 v[116:117], s[16:17], v116, s65, v[140:141]
	v_add_f32_e32 v118, 1.0, v118
	v_rcp_f32_e32 v118, v118
	s_nop 0
	v_mul_f32_e32 v110, v110, v118
	v_mul_f32_e32 v106, v110, v106
	v_mul_f32_e32 v110, 0xbfb8aa3b, v111
	v_exp_f32_e32 v110, v110
	s_nop 0
	v_add_f32_e32 v110, 1.0, v110
	v_rcp_f32_e32 v110, v110
	s_nop 0
	v_mul_f32_e32 v110, v111, v110
	v_mul_f32_e32 v107, v110, v107
	v_mul_f32_e32 v110, 0xbfb8aa3b, v112
	v_exp_f32_e32 v110, v110
	s_nop 0
	v_add_f32_e32 v110, 1.0, v110
	v_rcp_f32_e32 v110, v110
	s_nop 0
	v_mul_f32_e32 v110, v112, v110
	v_mul_f32_e32 v108, v110, v108
	v_mul_f32_e32 v110, 0xbfb8aa3b, v113
	v_exp_f32_e32 v110, v110
	s_nop 0
	v_add_f32_e32 v110, 1.0, v110
	v_rcp_f32_e32 v110, v110
	s_nop 0
	v_mul_f32_e32 v110, v113, v110
	v_mul_f32_e32 v109, v110, v109
	v_mul_f32_e32 v110, 0xbfb8aa3b, v102
	v_exp_f32_e32 v110, v110
	s_nop 0
	v_add_f32_e32 v110, 1.0, v110
	v_rcp_f32_e32 v110, v110
	s_nop 0
	v_mul_f32_e32 v102, v102, v110
	v_mul_f32_e32 v110, v102, v98
	v_mul_f32_e32 v98, 0xbfb8aa3b, v103
	v_exp_f32_e32 v98, v98
	s_nop 0
	v_add_f32_e32 v98, 1.0, v98
	v_rcp_f32_e32 v98, v98
	s_nop 0
	v_mul_f32_e32 v98, v103, v98
	v_mul_f32_e32 v111, v98, v99
	v_mul_f32_e32 v98, 0xbfb8aa3b, v104
	v_exp_f32_e32 v98, v98
	v_lshl_add_u64 v[102:103], v[116:117], 0, v[114:115]
	v_cvt_pk_bf16_f32 v99, v108, v109
	v_add_f32_e32 v98, 1.0, v98
	v_rcp_f32_e32 v98, v98
	s_nop 0
	v_mul_f32_e32 v98, v104, v98
	v_mul_f32_e32 v104, v98, v100
	v_mul_f32_e32 v98, 0xbfb8aa3b, v105
	v_exp_f32_e32 v98, v98
	v_cvt_pk_bf16_f32 v100, v110, v111
	s_nop 0
	v_add_f32_e32 v98, 1.0, v98
	v_rcp_f32_e32 v98, v98
	s_nop 0
	v_mul_f32_e32 v98, v105, v98
	v_mul_f32_e32 v101, v98, v101
	v_cvt_pk_bf16_f32 v98, v106, v107
	v_cvt_pk_bf16_f32 v101, v104, v101
	global_store_dwordx4 v[102:103], v[98:101], off
	s_nop 1
	v_mul_f32_e32 v100, 0xbfb8aa3b, v94
	v_exp_f32_e32 v100, v100
	v_or_b32_e32 v98, 32, v146
	v_mad_i64_i32 v[98:99], s[16:17], v98, s65, v[140:141]
	v_add_f32_e32 v100, 1.0, v100
	v_rcp_f32_e32 v100, v100
	s_nop 0
	v_mul_f32_e32 v94, v94, v100
	v_mul_f32_e32 v90, v94, v90
	v_mul_f32_e32 v94, 0xbfb8aa3b, v95
	v_exp_f32_e32 v94, v94
	s_nop 0
	v_add_f32_e32 v94, 1.0, v94
	v_rcp_f32_e32 v94, v94
	s_nop 0
	v_mul_f32_e32 v94, v95, v94
	v_mul_f32_e32 v91, v94, v91
	v_mul_f32_e32 v94, 0xbfb8aa3b, v96
	v_exp_f32_e32 v94, v94
	s_nop 0
	v_add_f32_e32 v94, 1.0, v94
	v_rcp_f32_e32 v94, v94
	s_nop 0
	v_mul_f32_e32 v94, v96, v94
	v_mul_f32_e32 v92, v94, v92
	v_mul_f32_e32 v94, 0xbfb8aa3b, v97
	v_exp_f32_e32 v94, v94
	s_nop 0
	v_add_f32_e32 v94, 1.0, v94
	v_rcp_f32_e32 v94, v94
	s_nop 0
	v_mul_f32_e32 v94, v97, v94
	v_mul_f32_e32 v93, v94, v93
	v_mul_f32_e32 v94, 0xbfb8aa3b, v86
	v_exp_f32_e32 v94, v94
	s_nop 0
	v_add_f32_e32 v94, 1.0, v94
	v_rcp_f32_e32 v94, v94
	s_nop 0
	v_mul_f32_e32 v86, v86, v94
	v_mul_f32_e32 v94, v86, v82
	v_mul_f32_e32 v82, 0xbfb8aa3b, v87
	v_exp_f32_e32 v82, v82
	s_nop 0
	v_add_f32_e32 v82, 1.0, v82
	v_rcp_f32_e32 v82, v82
	s_nop 0
	v_mul_f32_e32 v82, v87, v82
	v_mul_f32_e32 v95, v82, v83
	v_mul_f32_e32 v82, 0xbfb8aa3b, v88
	v_exp_f32_e32 v82, v82
	v_lshl_add_u64 v[86:87], v[98:99], 0, v[114:115]
	v_cvt_pk_bf16_f32 v83, v92, v93
	v_add_f32_e32 v82, 1.0, v82
	v_rcp_f32_e32 v82, v82
	s_nop 0
	v_mul_f32_e32 v82, v88, v82
	v_mul_f32_e32 v88, v82, v84
	v_mul_f32_e32 v82, 0xbfb8aa3b, v89
	v_exp_f32_e32 v82, v82
	v_cvt_pk_bf16_f32 v84, v94, v95
	s_nop 0
	v_add_f32_e32 v82, 1.0, v82
	v_rcp_f32_e32 v82, v82
	s_nop 0
	v_mul_f32_e32 v82, v89, v82
	v_mul_f32_e32 v85, v82, v85
	v_cvt_pk_bf16_f32 v82, v90, v91
	v_cvt_pk_bf16_f32 v85, v88, v85
	global_store_dwordx4 v[86:87], v[82:85], off
	s_nop 1
	v_mul_f32_e32 v84, 0xbfb8aa3b, v78
	v_exp_f32_e32 v84, v84
	v_or_b32_e32 v82, 48, v146
	v_mad_i64_i32 v[82:83], s[16:17], v82, s65, v[140:141]
	v_add_f32_e32 v84, 1.0, v84
	v_rcp_f32_e32 v84, v84
	s_nop 0
	v_mul_f32_e32 v78, v78, v84
	v_mul_f32_e32 v74, v78, v74
	v_mul_f32_e32 v78, 0xbfb8aa3b, v79
	v_exp_f32_e32 v78, v78
	s_nop 0
	v_add_f32_e32 v78, 1.0, v78
	v_rcp_f32_e32 v78, v78
	s_nop 0
	v_mul_f32_e32 v78, v79, v78
	v_mul_f32_e32 v75, v78, v75
	v_mul_f32_e32 v78, 0xbfb8aa3b, v80
	v_exp_f32_e32 v78, v78
	s_nop 0
	v_add_f32_e32 v78, 1.0, v78
	v_rcp_f32_e32 v78, v78
	s_nop 0
	v_mul_f32_e32 v78, v80, v78
	v_mul_f32_e32 v76, v78, v76
	v_mul_f32_e32 v78, 0xbfb8aa3b, v81
	v_exp_f32_e32 v78, v78
	s_nop 0
	v_add_f32_e32 v78, 1.0, v78
	v_rcp_f32_e32 v78, v78
	s_nop 0
	v_mul_f32_e32 v78, v81, v78
	v_mul_f32_e32 v77, v78, v77
	v_mul_f32_e32 v78, 0xbfb8aa3b, v70
	v_exp_f32_e32 v78, v78
	s_nop 0
	v_add_f32_e32 v78, 1.0, v78
	v_rcp_f32_e32 v78, v78
	s_nop 0
	v_mul_f32_e32 v70, v70, v78
	v_mul_f32_e32 v78, v70, v66
	v_mul_f32_e32 v66, 0xbfb8aa3b, v71
	v_exp_f32_e32 v66, v66
	s_nop 0
	v_add_f32_e32 v66, 1.0, v66
	v_rcp_f32_e32 v66, v66
	s_nop 0
	v_mul_f32_e32 v66, v71, v66
	v_mul_f32_e32 v79, v66, v67
	v_mul_f32_e32 v66, 0xbfb8aa3b, v72
	v_exp_f32_e32 v66, v66
	v_lshl_add_u64 v[70:71], v[82:83], 0, v[114:115]
	v_cvt_pk_bf16_f32 v67, v76, v77
	v_add_f32_e32 v66, 1.0, v66
	v_rcp_f32_e32 v66, v66
	s_nop 0
	v_mul_f32_e32 v66, v72, v66
	v_mul_f32_e32 v72, v66, v68
	v_mul_f32_e32 v66, 0xbfb8aa3b, v73
	v_exp_f32_e32 v66, v66
	v_cvt_pk_bf16_f32 v68, v78, v79
	s_nop 0
	v_add_f32_e32 v66, 1.0, v66
	v_rcp_f32_e32 v66, v66
	s_nop 0
	v_mul_f32_e32 v66, v73, v66
	v_mul_f32_e32 v69, v66, v69
	v_cvt_pk_bf16_f32 v66, v74, v75
	v_cvt_pk_bf16_f32 v69, v72, v69
	global_store_dwordx4 v[70:71], v[66:69], off
	s_nop 1
	v_mul_f32_e32 v68, 0xbfb8aa3b, v62
	v_exp_f32_e32 v68, v68
	v_add_u32_e32 v66, 0x80, v146
	v_mad_i64_i32 v[66:67], s[16:17], v66, s65, v[140:141]
	v_add_f32_e32 v68, 1.0, v68
	v_rcp_f32_e32 v68, v68
	s_nop 0
	v_mul_f32_e32 v62, v62, v68
	v_mul_f32_e32 v58, v62, v58
	v_mul_f32_e32 v62, 0xbfb8aa3b, v63
	v_exp_f32_e32 v62, v62
	s_nop 0
	v_add_f32_e32 v62, 1.0, v62
	v_rcp_f32_e32 v62, v62
	s_nop 0
	v_mul_f32_e32 v62, v63, v62
	v_mul_f32_e32 v59, v62, v59
	v_mul_f32_e32 v62, 0xbfb8aa3b, v64
	v_exp_f32_e32 v62, v62
	s_nop 0
	v_add_f32_e32 v62, 1.0, v62
	v_rcp_f32_e32 v62, v62
	s_nop 0
	v_mul_f32_e32 v62, v64, v62
	v_mul_f32_e32 v60, v62, v60
	v_mul_f32_e32 v62, 0xbfb8aa3b, v65
	v_exp_f32_e32 v62, v62
	s_nop 0
	v_add_f32_e32 v62, 1.0, v62
	v_rcp_f32_e32 v62, v62
	s_nop 0
	v_mul_f32_e32 v62, v65, v62
	v_mul_f32_e32 v61, v62, v61
	v_mul_f32_e32 v62, 0xbfb8aa3b, v54
	v_exp_f32_e32 v62, v62
	s_nop 0
	v_add_f32_e32 v62, 1.0, v62
	v_rcp_f32_e32 v62, v62
	s_nop 0
	v_mul_f32_e32 v54, v54, v62
	v_mul_f32_e32 v62, v54, v50
	v_mul_f32_e32 v50, 0xbfb8aa3b, v55
	v_exp_f32_e32 v50, v50
	s_nop 0
	v_add_f32_e32 v50, 1.0, v50
	v_rcp_f32_e32 v50, v50
	s_nop 0
	v_mul_f32_e32 v50, v55, v50
	v_mul_f32_e32 v63, v50, v51
	v_mul_f32_e32 v50, 0xbfb8aa3b, v56
	v_exp_f32_e32 v50, v50
	v_lshl_add_u64 v[54:55], v[66:67], 0, v[114:115]
	v_cvt_pk_bf16_f32 v51, v60, v61
	v_add_f32_e32 v50, 1.0, v50
	v_rcp_f32_e32 v50, v50
	s_nop 0
	v_mul_f32_e32 v50, v56, v50
	v_mul_f32_e32 v56, v50, v52
	v_mul_f32_e32 v50, 0xbfb8aa3b, v57
	v_exp_f32_e32 v50, v50
	v_cvt_pk_bf16_f32 v52, v62, v63
	s_nop 0
	v_add_f32_e32 v50, 1.0, v50
	v_rcp_f32_e32 v50, v50
	s_nop 0
	v_mul_f32_e32 v50, v57, v50
	v_mul_f32_e32 v53, v50, v53
	v_cvt_pk_bf16_f32 v50, v58, v59
	v_cvt_pk_bf16_f32 v53, v56, v53
	global_store_dwordx4 v[54:55], v[50:53], off
	s_nop 1
	v_mul_f32_e32 v52, 0xbfb8aa3b, v46
	v_exp_f32_e32 v52, v52
	v_add_u32_e32 v50, 0x90, v146
	v_mad_i64_i32 v[50:51], s[16:17], v50, s65, v[140:141]
	v_add_f32_e32 v52, 1.0, v52
	v_rcp_f32_e32 v52, v52
	s_nop 0
	v_mul_f32_e32 v46, v46, v52
	v_mul_f32_e32 v42, v46, v42
	v_mul_f32_e32 v46, 0xbfb8aa3b, v47
	v_exp_f32_e32 v46, v46
	s_nop 0
	v_add_f32_e32 v46, 1.0, v46
	v_rcp_f32_e32 v46, v46
	s_nop 0
	v_mul_f32_e32 v46, v47, v46
	v_mul_f32_e32 v43, v46, v43
	v_mul_f32_e32 v46, 0xbfb8aa3b, v48
	v_exp_f32_e32 v46, v46
	s_nop 0
	v_add_f32_e32 v46, 1.0, v46
	v_rcp_f32_e32 v46, v46
	s_nop 0
	v_mul_f32_e32 v46, v48, v46
	v_mul_f32_e32 v44, v46, v44
	v_mul_f32_e32 v46, 0xbfb8aa3b, v49
	v_exp_f32_e32 v46, v46
	s_nop 0
	v_add_f32_e32 v46, 1.0, v46
	v_rcp_f32_e32 v46, v46
	s_nop 0
	v_mul_f32_e32 v46, v49, v46
	v_mul_f32_e32 v45, v46, v45
	v_mul_f32_e32 v46, 0xbfb8aa3b, v38
	v_exp_f32_e32 v46, v46
	s_nop 0
	v_add_f32_e32 v46, 1.0, v46
	v_rcp_f32_e32 v46, v46
	s_nop 0
	v_mul_f32_e32 v38, v38, v46
	v_mul_f32_e32 v46, v38, v34
	v_mul_f32_e32 v34, 0xbfb8aa3b, v39
	v_exp_f32_e32 v34, v34
	s_nop 0
	v_add_f32_e32 v34, 1.0, v34
	v_rcp_f32_e32 v34, v34
	s_nop 0
	v_mul_f32_e32 v34, v39, v34
	v_mul_f32_e32 v47, v34, v35
	v_mul_f32_e32 v34, 0xbfb8aa3b, v40
	v_exp_f32_e32 v34, v34
	v_lshl_add_u64 v[38:39], v[50:51], 0, v[114:115]
	v_cvt_pk_bf16_f32 v35, v44, v45
	v_add_f32_e32 v34, 1.0, v34
	v_rcp_f32_e32 v34, v34
	s_nop 0
	v_mul_f32_e32 v34, v40, v34
	v_mul_f32_e32 v40, v34, v36
	v_mul_f32_e32 v34, 0xbfb8aa3b, v41
	v_exp_f32_e32 v34, v34
	v_cvt_pk_bf16_f32 v36, v46, v47
	s_nop 0
	v_add_f32_e32 v34, 1.0, v34
	v_rcp_f32_e32 v34, v34
	s_nop 0
	v_mul_f32_e32 v34, v41, v34
	v_mul_f32_e32 v37, v34, v37
	v_cvt_pk_bf16_f32 v34, v42, v43
	v_cvt_pk_bf16_f32 v37, v40, v37
	global_store_dwordx4 v[38:39], v[34:37], off
	s_nop 1
	v_mul_f32_e32 v36, 0xbfb8aa3b, v30
	v_exp_f32_e32 v36, v36
	v_add_u32_e32 v34, 0xa0, v146
	v_mad_i64_i32 v[34:35], s[16:17], v34, s65, v[140:141]
	v_add_f32_e32 v36, 1.0, v36
	v_rcp_f32_e32 v36, v36
	s_nop 0
	v_mul_f32_e32 v30, v30, v36
	v_mul_f32_e32 v26, v30, v26
	v_mul_f32_e32 v30, 0xbfb8aa3b, v31
	v_exp_f32_e32 v30, v30
	s_nop 0
	v_add_f32_e32 v30, 1.0, v30
	v_rcp_f32_e32 v30, v30
	s_nop 0
	v_mul_f32_e32 v30, v31, v30
	v_mul_f32_e32 v27, v30, v27
	v_mul_f32_e32 v30, 0xbfb8aa3b, v32
	v_exp_f32_e32 v30, v30
	s_nop 0
	v_add_f32_e32 v30, 1.0, v30
	v_rcp_f32_e32 v30, v30
	s_nop 0
	v_mul_f32_e32 v30, v32, v30
	v_mul_f32_e32 v28, v30, v28
	v_mul_f32_e32 v30, 0xbfb8aa3b, v33
	v_exp_f32_e32 v30, v30
	s_nop 0
	v_add_f32_e32 v30, 1.0, v30
	v_rcp_f32_e32 v30, v30
	s_nop 0
	v_mul_f32_e32 v30, v33, v30
	v_mul_f32_e32 v29, v30, v29
	v_mul_f32_e32 v30, 0xbfb8aa3b, v22
	v_exp_f32_e32 v30, v30
	s_nop 0
	v_add_f32_e32 v30, 1.0, v30
	v_rcp_f32_e32 v30, v30
	s_nop 0
	v_mul_f32_e32 v22, v22, v30
	v_mul_f32_e32 v30, v22, v18
	v_mul_f32_e32 v18, 0xbfb8aa3b, v23
	v_exp_f32_e32 v18, v18
	s_nop 0
	v_add_f32_e32 v18, 1.0, v18
	v_rcp_f32_e32 v18, v18
	s_nop 0
	v_mul_f32_e32 v18, v23, v18
	v_mul_f32_e32 v31, v18, v19
	v_mul_f32_e32 v18, 0xbfb8aa3b, v24
	v_exp_f32_e32 v18, v18
	v_lshl_add_u64 v[22:23], v[34:35], 0, v[114:115]
	v_cvt_pk_bf16_f32 v19, v28, v29
	v_add_f32_e32 v18, 1.0, v18
	v_rcp_f32_e32 v18, v18
	s_nop 0
	v_mul_f32_e32 v18, v24, v18
	v_mul_f32_e32 v24, v18, v20
	v_mul_f32_e32 v18, 0xbfb8aa3b, v25
	v_exp_f32_e32 v18, v18
	v_cvt_pk_bf16_f32 v20, v30, v31
	s_nop 0
	v_add_f32_e32 v18, 1.0, v18
	v_rcp_f32_e32 v18, v18
	s_nop 0
	v_mul_f32_e32 v18, v25, v18
	v_mul_f32_e32 v21, v18, v21
	v_cvt_pk_bf16_f32 v18, v26, v27
	v_cvt_pk_bf16_f32 v21, v24, v21
	global_store_dwordx4 v[22:23], v[18:21], off
	s_nop 1
	v_mul_f32_e32 v20, 0xbfb8aa3b, v12
	v_exp_f32_e32 v20, v20
	v_add_u32_e32 v18, 0xb0, v146
	v_mad_i64_i32 v[18:19], s[16:17], v18, s65, v[140:141]
	v_add_f32_e32 v20, 1.0, v20
	v_rcp_f32_e32 v20, v20
	s_nop 0
	v_mul_f32_e32 v12, v12, v20
	v_mul_f32_e32 v8, v12, v8
	v_mul_f32_e32 v12, 0xbfb8aa3b, v13
	v_exp_f32_e32 v12, v12
	s_nop 0
	v_add_f32_e32 v12, 1.0, v12
	v_rcp_f32_e32 v12, v12
	s_nop 0
	v_mul_f32_e32 v12, v13, v12
	v_mul_f32_e32 v9, v12, v9
	v_mul_f32_e32 v12, 0xbfb8aa3b, v14
	v_exp_f32_e32 v12, v12
	s_nop 0
	v_add_f32_e32 v12, 1.0, v12
	v_rcp_f32_e32 v12, v12
	s_nop 0
	v_mul_f32_e32 v12, v14, v12
	v_mul_f32_e32 v10, v12, v10
	v_mul_f32_e32 v12, 0xbfb8aa3b, v15
	v_exp_f32_e32 v12, v12
	s_nop 0
	v_add_f32_e32 v12, 1.0, v12
	v_rcp_f32_e32 v12, v12
	s_nop 0
	v_mul_f32_e32 v12, v15, v12
	v_mul_f32_e32 v11, v12, v11
	v_mul_f32_e32 v12, 0xbfb8aa3b, v4
	v_exp_f32_e32 v12, v12
	s_nop 0
	v_add_f32_e32 v12, 1.0, v12
	v_rcp_f32_e32 v12, v12
	s_nop 0
	v_mul_f32_e32 v4, v4, v12
	v_mul_f32_e32 v12, v4, v0
	v_mul_f32_e32 v0, 0xbfb8aa3b, v5
	v_exp_f32_e32 v0, v0
	s_nop 0
	v_add_f32_e32 v0, 1.0, v0
	v_rcp_f32_e32 v0, v0
	s_nop 0
	v_mul_f32_e32 v0, v5, v0
	v_mul_f32_e32 v13, v0, v1
	v_mul_f32_e32 v0, 0xbfb8aa3b, v6
	v_exp_f32_e32 v0, v0
	v_lshl_add_u64 v[4:5], v[18:19], 0, v[114:115]
	v_cvt_pk_bf16_f32 v1, v10, v11
	v_add_f32_e32 v0, 1.0, v0
	v_rcp_f32_e32 v0, v0
	s_nop 0
	v_mul_f32_e32 v0, v6, v0
	v_mul_f32_e32 v6, v0, v2
	v_mul_f32_e32 v0, 0xbfb8aa3b, v7
	v_exp_f32_e32 v0, v0
	v_cvt_pk_bf16_f32 v2, v12, v13
	s_nop 0
	v_add_f32_e32 v0, 1.0, v0
	v_rcp_f32_e32 v0, v0
	s_nop 0
	v_mul_f32_e32 v0, v7, v0
	v_mul_f32_e32 v3, v0, v3
	v_cvt_pk_bf16_f32 v0, v8, v9
	v_cvt_pk_bf16_f32 v3, v6, v3
	global_store_dwordx4 v[4:5], v[0:3], off
	s_and_b64 vcc, exec, s[38:39]
	s_mov_b32 s2, s8
	s_mov_b32 s14, s28
	s_mov_b64 s[16:17], s[42:43]
	s_mov_b64 s[18:19], s[40:41]
	s_cbranch_vccz .LBB0_144
	s_waitcnt vmcnt(0)
	s_cmpk_gt_u32 s48, 0xff
	s_cbranch_scc1 .LBB0_151
	s_barrier

.LBB0_173:
	s_ashr_i32 s9, s8, 31
	v_cmp_lt_i64_e32 vcc, s[14:15], v[202:203]
	s_lshl_b64 s[14:15], s[8:9], 19
	s_add_u32 s14, s96, s14
	s_addc_u32 s15, s97, s15
	s_and_b64 s[16:17], vcc, exec
	s_cselect_b32 s9, s15, s23
	s_cselect_b32 s12, s14, s22
	s_ashr_i32 s5, s4, 31
	s_lshl_b64 s[16:17], s[4:5], 19
	s_add_u32 s16, s50, s16
	s_addc_u32 s17, s51, s17
	s_and_b64 s[42:43], vcc, exec
	s_cselect_b32 s5, s17, s41
	s_cselect_b32 s34, s16, s40
	s_add_u32 s61, s40, 0x100
	v_mov_b32_e32 v0, 0
	s_addc_u32 s79, s41, 0
	s_mov_b32 s82, -2
	v_mov_b32_e32 v1, v0
	v_mov_b32_e32 v2, v0
	v_mov_b32_e32 v3, v0
	v_mov_b32_e32 v4, v0
	v_mov_b32_e32 v5, v0
	v_mov_b32_e32 v6, v0
	v_mov_b32_e32 v7, v0
	v_mov_b32_e32 v8, v0
	v_mov_b32_e32 v9, v0
	v_mov_b32_e32 v10, v0
	v_mov_b32_e32 v11, v0
	v_mov_b32_e32 v12, v0
	v_mov_b32_e32 v13, v0
	v_mov_b32_e32 v14, v0
	v_mov_b32_e32 v15, v0
	v_mov_b32_e32 v22, v0
	v_mov_b32_e32 v23, v0
	v_mov_b32_e32 v24, v0
	v_mov_b32_e32 v25, v0
	v_mov_b32_e32 v26, v0
	v_mov_b32_e32 v27, v0
	v_mov_b32_e32 v28, v0
	v_mov_b32_e32 v29, v0
	v_mov_b32_e32 v34, v0
	v_mov_b32_e32 v35, v0
	v_mov_b32_e32 v36, v0
	v_mov_b32_e32 v37, v0
	v_mov_b32_e32 v42, v0
	v_mov_b32_e32 v43, v0
	v_mov_b32_e32 v44, v0
	v_mov_b32_e32 v45, v0
	v_mov_b32_e32 v18, v0
	v_mov_b32_e32 v19, v0
	v_mov_b32_e32 v20, v0
	v_mov_b32_e32 v21, v0
	v_mov_b32_e32 v30, v0
	v_mov_b32_e32 v31, v0
	v_mov_b32_e32 v32, v0
	v_mov_b32_e32 v33, v0
	v_mov_b32_e32 v38, v0
	v_mov_b32_e32 v39, v0
	v_mov_b32_e32 v40, v0
	v_mov_b32_e32 v41, v0
	v_mov_b32_e32 v46, v0
	v_mov_b32_e32 v47, v0
	v_mov_b32_e32 v48, v0
	v_mov_b32_e32 v49, v0
	v_mov_b32_e32 v50, v0
	v_mov_b32_e32 v51, v0
	v_mov_b32_e32 v52, v0
	v_mov_b32_e32 v53, v0
	v_mov_b32_e32 v54, v0
	v_mov_b32_e32 v55, v0
	v_mov_b32_e32 v56, v0
	v_mov_b32_e32 v57, v0
	v_mov_b32_e32 v58, v0
	v_mov_b32_e32 v59, v0
	v_mov_b32_e32 v60, v0
	v_mov_b32_e32 v61, v0
	v_mov_b32_e32 v62, v0
	v_mov_b32_e32 v63, v0
	v_mov_b32_e32 v64, v0
	v_mov_b32_e32 v65, v0
	v_mov_b32_e32 v66, v0
	v_mov_b32_e32 v67, v0
	v_mov_b32_e32 v68, v0
	v_mov_b32_e32 v69, v0
	v_mov_b32_e32 v70, v0
	v_mov_b32_e32 v71, v0
	v_mov_b32_e32 v72, v0
	v_mov_b32_e32 v73, v0
	v_mov_b32_e32 v78, v0
	v_mov_b32_e32 v79, v0
	v_mov_b32_e32 v80, v0
	v_mov_b32_e32 v81, v0
	v_mov_b32_e32 v82, v0
	v_mov_b32_e32 v83, v0
	v_mov_b32_e32 v84, v0
	v_mov_b32_e32 v85, v0
	v_mov_b32_e32 v94, v0
	v_mov_b32_e32 v95, v0
	v_mov_b32_e32 v96, v0
	v_mov_b32_e32 v97, v0
	v_mov_b32_e32 v98, v0
	v_mov_b32_e32 v99, v0
	v_mov_b32_e32 v100, v0
	v_mov_b32_e32 v101, v0
	v_mov_b32_e32 v110, v0
	v_mov_b32_e32 v111, v0
	v_mov_b32_e32 v112, v0
	v_mov_b32_e32 v113, v0
	v_mov_b32_e32 v114, v0
	v_mov_b32_e32 v115, v0
	v_mov_b32_e32 v116, v0
	v_mov_b32_e32 v117, v0
	v_mov_b32_e32 v74, v0
	v_mov_b32_e32 v75, v0
	v_mov_b32_e32 v76, v0
	v_mov_b32_e32 v77, v0
	v_mov_b32_e32 v86, v0
	v_mov_b32_e32 v87, v0
	v_mov_b32_e32 v88, v0
	v_mov_b32_e32 v89, v0
	v_mov_b32_e32 v90, v0
	v_mov_b32_e32 v91, v0
	v_mov_b32_e32 v92, v0
	v_mov_b32_e32 v93, v0
	v_mov_b32_e32 v102, v0
	v_mov_b32_e32 v103, v0
	v_mov_b32_e32 v104, v0
	v_mov_b32_e32 v105, v0
	v_mov_b32_e32 v106, v0
	v_mov_b32_e32 v107, v0
	v_mov_b32_e32 v108, v0
	v_mov_b32_e32 v109, v0
	v_mov_b32_e32 v118, v0
	v_mov_b32_e32 v119, v0
	v_mov_b32_e32 v120, v0
	v_mov_b32_e32 v121, v0
	v_mov_b32_e32 v122, v0
	v_mov_b32_e32 v123, v0
	v_mov_b32_e32 v124, v0
	v_mov_b32_e32 v125, v0
	v_mov_b32_e32 v126, v0
	v_mov_b32_e32 v127, v0
	v_mov_b32_e32 v128, v0
	v_mov_b32_e32 v129, v0
.LBB0_174:
	s_add_u32 s40, s22, 0x100
	s_addc_u32 s41, s23, 0
	s_add_i32 s83, 0, 0x10000
	v_add_u32_e32 v148, s83, v157
	ds_read_b128 v[130:133], v148
	ds_read_b128 v[134:137], v148 offset:1024
	ds_read_b128 v[138:141], v148 offset:2048
	ds_read_b128 v[148:151], v148 offset:3072
	s_cmp_eq_u32 s82, 12
	s_cselect_b32 s49, s9, s41
	s_cselect_b32 s48, s12, s40
	s_cselect_b32 s43, s5, s79
	s_cselect_b32 s42, s34, s61
	v_lshl_add_u64 v[188:189], s[22:23], 0, v[146:147]
	s_add_i32 m0, s19, 0xc000
	ds_read_b128 v[152:155], v159
	ds_read_b128 v[160:163], v159 offset:1024
	ds_read_b128 v[164:167], v159 offset:2048
	ds_read_b128 v[168:171], v159 offset:3072
	ds_read_b128 v[172:175], v159 offset:4096
	ds_read_b128 v[176:179], v159 offset:5120
	ds_read_b128 v[180:183], v159 offset:6144
	ds_read_b128 v[184:187], v159 offset:7168
	global_load_lds_dwordx4 v[188:189], off
	v_lshl_add_u64 v[188:189], s[22:23], 0, v[144:145]
	s_add_i32 m0, s19, 0xe000
	s_nop 0
	global_load_lds_dwordx4 v[188:189], off
	s_waitcnt lgkmcnt(8)
	s_barrier
	s_waitcnt lgkmcnt(0)
	s_waitcnt lgkmcnt(0)
	v_mfma_f32_16x16x32_bf16 v[126:129], v[130:133], v[152:155], v[126:129]
	v_mfma_f32_16x16x32_bf16 v[122:125], v[138:141], v[152:155], v[122:125]
	v_mfma_f32_16x16x32_bf16 v[118:121], v[130:133], v[164:167], v[118:121]
	v_mfma_f32_16x16x32_bf16 v[106:109], v[138:141], v[164:167], v[106:109]
	v_mfma_f32_16x16x32_bf16 v[102:105], v[130:133], v[172:175], v[102:105]
	v_mfma_f32_16x16x32_bf16 v[90:93], v[138:141], v[172:175], v[90:93]
	v_mfma_f32_16x16x32_bf16 v[86:89], v[130:133], v[180:183], v[86:89]
	v_mfma_f32_16x16x32_bf16 v[74:77], v[138:141], v[180:183], v[74:77]
	v_mfma_f32_16x16x32_bf16 v[126:129], v[134:137], v[160:163], v[126:129]
	v_mfma_f32_16x16x32_bf16 v[122:125], v[148:151], v[160:163], v[122:125]
	v_mfma_f32_16x16x32_bf16 v[118:121], v[134:137], v[168:171], v[118:121]
	v_mfma_f32_16x16x32_bf16 v[106:109], v[148:151], v[168:171], v[106:109]
	v_mfma_f32_16x16x32_bf16 v[102:105], v[134:137], v[176:179], v[102:105]
	v_mfma_f32_16x16x32_bf16 v[90:93], v[148:151], v[176:179], v[90:93]
	v_mfma_f32_16x16x32_bf16 v[86:89], v[134:137], v[184:187], v[86:89]
	v_mfma_f32_16x16x32_bf16 v[74:77], v[148:151], v[184:187], v[74:77]
	s_barrier
	s_add_i32 s84, 0, 0x14000
	v_add_u32_e32 v196, s84, v157
	s_add_i32 s22, s83, s52
	ds_read_b128 v[188:191], v196
	ds_read_b128 v[192:195], v196 offset:1024
	ds_read_b128 v[208:211], v196 offset:2048
	ds_read_b128 v[212:215], v196 offset:3072
	v_lshl_add_u64 v[196:197], s[42:43], 0, v[16:17]
	s_mov_b32 m0, s22
	v_lshl_add_u64 v[216:217], s[42:43], 0, v[142:143]
	global_load_lds_dwordx4 v[196:197], off
	s_add_i32 m0, s22, 0x2000
	s_nop 0
	global_load_lds_dwordx4 v[216:217], off
	s_barrier
	s_waitcnt lgkmcnt(0)
	s_waitcnt lgkmcnt(0)
	v_mfma_f32_16x16x32_bf16 v[114:117], v[188:191], v[152:155], v[114:117]
	v_mfma_f32_16x16x32_bf16 v[110:113], v[208:211], v[152:155], v[110:113]
	v_mfma_f32_16x16x32_bf16 v[98:101], v[188:191], v[164:167], v[98:101]
	v_mfma_f32_16x16x32_bf16 v[94:97], v[208:211], v[164:167], v[94:97]
	v_mfma_f32_16x16x32_bf16 v[82:85], v[188:191], v[172:175], v[82:85]
	v_mfma_f32_16x16x32_bf16 v[78:81], v[208:211], v[172:175], v[78:81]
	v_mfma_f32_16x16x32_bf16 v[70:73], v[188:191], v[180:183], v[70:73]
	v_mfma_f32_16x16x32_bf16 v[66:69], v[208:211], v[180:183], v[66:69]
	v_mfma_f32_16x16x32_bf16 v[114:117], v[192:195], v[160:163], v[114:117]
	v_mfma_f32_16x16x32_bf16 v[110:113], v[212:215], v[160:163], v[110:113]
	v_mfma_f32_16x16x32_bf16 v[98:101], v[192:195], v[168:171], v[98:101]
	v_mfma_f32_16x16x32_bf16 v[94:97], v[212:215], v[168:171], v[94:97]
	v_mfma_f32_16x16x32_bf16 v[82:85], v[192:195], v[176:179], v[82:85]
	v_mfma_f32_16x16x32_bf16 v[78:81], v[212:215], v[176:179], v[78:81]
	v_mfma_f32_16x16x32_bf16 v[70:73], v[192:195], v[184:187], v[70:73]
	v_mfma_f32_16x16x32_bf16 v[66:69], v[212:215], v[184:187], v[66:69]
	s_mov_b32 m0, s19
	v_lshl_add_u64 v[218:219], s[48:49], 0, v[16:17]
	s_barrier
	ds_read_b128 v[152:155], v159 offset:16384
	ds_read_b128 v[160:163], v159 offset:17408
	ds_read_b128 v[164:167], v159 offset:18432
	ds_read_b128 v[168:171], v159 offset:19456
	ds_read_b128 v[172:175], v159 offset:20480
	ds_read_b128 v[176:179], v159 offset:21504
	ds_read_b128 v[180:183], v159 offset:22528
	ds_read_b128 v[184:187], v159 offset:23552
	global_load_lds_dwordx4 v[218:219], off
	v_lshl_add_u64 v[220:221], s[48:49], 0, v[142:143]
	s_mov_b32 m0, s54
	s_nop 0
	global_load_lds_dwordx4 v[220:221], off
	s_barrier
	s_waitcnt lgkmcnt(0)
	s_waitcnt lgkmcnt(0)
	v_mfma_f32_16x16x32_bf16 v[62:65], v[130:133], v[152:155], v[62:65]
	v_mfma_f32_16x16x32_bf16 v[58:61], v[138:141], v[152:155], v[58:61]
	v_mfma_f32_16x16x32_bf16 v[54:57], v[130:133], v[164:167], v[54:57]
	v_mfma_f32_16x16x32_bf16 v[50:53], v[138:141], v[164:167], v[50:53]
	v_mfma_f32_16x16x32_bf16 v[46:49], v[130:133], v[172:175], v[46:49]
	v_mfma_f32_16x16x32_bf16 v[38:41], v[138:141], v[172:175], v[38:41]
	v_mfma_f32_16x16x32_bf16 v[30:33], v[130:133], v[180:183], v[30:33]
	v_mfma_f32_16x16x32_bf16 v[18:21], v[138:141], v[180:183], v[18:21]
	v_mfma_f32_16x16x32_bf16 v[62:65], v[134:137], v[160:163], v[62:65]
	v_mfma_f32_16x16x32_bf16 v[58:61], v[148:151], v[160:163], v[58:61]
	v_mfma_f32_16x16x32_bf16 v[54:57], v[134:137], v[168:171], v[54:57]
	v_mfma_f32_16x16x32_bf16 v[50:53], v[148:151], v[168:171], v[50:53]
	v_mfma_f32_16x16x32_bf16 v[46:49], v[134:137], v[176:179], v[46:49]
	v_mfma_f32_16x16x32_bf16 v[38:41], v[148:151], v[176:179], v[38:41]
	v_mfma_f32_16x16x32_bf16 v[30:33], v[134:137], v[184:187], v[30:33]
	v_mfma_f32_16x16x32_bf16 v[18:21], v[148:151], v[184:187], v[18:21]
	s_barrier
	s_add_u32 s22, s42, 0x40000
	s_addc_u32 s23, s43, 0
	s_add_i32 s83, s84, s52
	v_lshl_add_u64 v[130:131], s[22:23], 0, v[16:17]
	s_mov_b32 m0, s83
	s_nop 0
	global_load_lds_dwordx4 v[130:131], off
	v_lshl_add_u64 v[130:131], s[22:23], 0, v[142:143]
	s_add_i32 m0, s83, 0x2000
	s_nop 0
	global_load_lds_dwordx4 v[130:131], off
	s_waitcnt vmcnt(6)
	s_barrier
	v_mfma_f32_16x16x32_bf16 v[42:45], v[188:191], v[152:155], v[42:45]
	v_mfma_f32_16x16x32_bf16 v[34:37], v[208:211], v[152:155], v[34:37]
	v_mfma_f32_16x16x32_bf16 v[26:29], v[188:191], v[164:167], v[26:29]
	v_mfma_f32_16x16x32_bf16 v[22:25], v[208:211], v[164:167], v[22:25]
	v_mfma_f32_16x16x32_bf16 v[12:15], v[188:191], v[172:175], v[12:15]
	v_mfma_f32_16x16x32_bf16 v[8:11], v[208:211], v[172:175], v[8:11]
	v_mfma_f32_16x16x32_bf16 v[4:7], v[188:191], v[180:183], v[4:7]
	v_mfma_f32_16x16x32_bf16 v[0:3], v[208:211], v[180:183], v[0:3]
	v_mfma_f32_16x16x32_bf16 v[42:45], v[192:195], v[160:163], v[42:45]
	v_mfma_f32_16x16x32_bf16 v[34:37], v[212:215], v[160:163], v[34:37]
	v_mfma_f32_16x16x32_bf16 v[26:29], v[192:195], v[168:171], v[26:29]
	v_mfma_f32_16x16x32_bf16 v[22:25], v[212:215], v[168:171], v[22:25]
	v_mfma_f32_16x16x32_bf16 v[12:15], v[192:195], v[176:179], v[12:15]
	v_mfma_f32_16x16x32_bf16 v[8:11], v[212:215], v[176:179], v[8:11]
	v_mfma_f32_16x16x32_bf16 v[4:7], v[192:195], v[184:187], v[4:7]
	v_mfma_f32_16x16x32_bf16 v[0:3], v[212:215], v[184:187], v[0:3]
	s_add_i32 s83, 0, 0x18000
	v_add_u32_e32 v148, s83, v157
	s_barrier
	ds_read_b128 v[130:133], v148
	ds_read_b128 v[134:137], v148 offset:1024
	ds_read_b128 v[138:141], v148 offset:2048
	ds_read_b128 v[148:151], v148 offset:3072
	s_add_u32 s22, s48, 0x40000
	s_addc_u32 s23, s49, 0
	s_mov_b32 m0, s55
	v_lshl_add_u64 v[188:189], s[22:23], 0, v[16:17]
	ds_read_b128 v[152:155], v159 offset:32768
	ds_read_b128 v[160:163], v159 offset:33792
	ds_read_b128 v[164:167], v159 offset:34816
	ds_read_b128 v[168:171], v159 offset:35840
	ds_read_b128 v[172:175], v159 offset:36864
	ds_read_b128 v[176:179], v159 offset:37888
	ds_read_b128 v[180:183], v159 offset:38912
	ds_read_b128 v[184:187], v159 offset:39936
	global_load_lds_dwordx4 v[188:189], off
	v_lshl_add_u64 v[188:189], s[22:23], 0, v[142:143]
	s_mov_b32 m0, s56
	s_nop 0
	global_load_lds_dwordx4 v[188:189], off
	s_waitcnt lgkmcnt(8)
	s_barrier
	s_waitcnt lgkmcnt(0)
	s_waitcnt lgkmcnt(0)
	v_mfma_f32_16x16x32_bf16 v[126:129], v[130:133], v[152:155], v[126:129]
	v_mfma_f32_16x16x32_bf16 v[122:125], v[138:141], v[152:155], v[122:125]
	v_mfma_f32_16x16x32_bf16 v[118:121], v[130:133], v[164:167], v[118:121]
	v_mfma_f32_16x16x32_bf16 v[106:109], v[138:141], v[164:167], v[106:109]
	v_mfma_f32_16x16x32_bf16 v[102:105], v[130:133], v[172:175], v[102:105]
	v_mfma_f32_16x16x32_bf16 v[90:93], v[138:141], v[172:175], v[90:93]
	v_mfma_f32_16x16x32_bf16 v[86:89], v[130:133], v[180:183], v[86:89]
	v_mfma_f32_16x16x32_bf16 v[74:77], v[138:141], v[180:183], v[74:77]
	v_mfma_f32_16x16x32_bf16 v[126:129], v[134:137], v[160:163], v[126:129]
	v_mfma_f32_16x16x32_bf16 v[122:125], v[148:151], v[160:163], v[122:125]
	v_mfma_f32_16x16x32_bf16 v[118:121], v[134:137], v[168:171], v[118:121]
	v_mfma_f32_16x16x32_bf16 v[106:109], v[148:151], v[168:171], v[106:109]
	v_mfma_f32_16x16x32_bf16 v[102:105], v[134:137], v[176:179], v[102:105]
	v_mfma_f32_16x16x32_bf16 v[90:93], v[148:151], v[176:179], v[90:93]
	v_mfma_f32_16x16x32_bf16 v[86:89], v[134:137], v[184:187], v[86:89]
	v_mfma_f32_16x16x32_bf16 v[74:77], v[148:151], v[184:187], v[74:77]
	s_barrier
	s_add_i32 s48, 0, 0x1c000
	s_add_i32 s22, s83, s52
	v_add_u32_e32 v212, s48, v157
	v_lshl_add_u64 v[196:197], v[196:197], 0, s[10:11]
	s_mov_b32 m0, s22
	ds_read_b128 v[188:191], v212
	ds_read_b128 v[192:195], v212 offset:1024
	ds_read_b128 v[208:211], v212 offset:2048
	ds_read_b128 v[212:215], v212 offset:3072
	global_load_lds_dwordx4 v[196:197], off
	v_lshl_add_u64 v[196:197], v[216:217], 0, s[10:11]
	s_add_i32 m0, s22, 0x2000
	s_nop 0
	global_load_lds_dwordx4 v[196:197], off
	s_barrier
	s_waitcnt lgkmcnt(0)
	s_waitcnt lgkmcnt(0)
	v_mfma_f32_16x16x32_bf16 v[114:117], v[188:191], v[152:155], v[114:117]
	v_mfma_f32_16x16x32_bf16 v[110:113], v[208:211], v[152:155], v[110:113]
	v_mfma_f32_16x16x32_bf16 v[98:101], v[188:191], v[164:167], v[98:101]
	v_mfma_f32_16x16x32_bf16 v[94:97], v[208:211], v[164:167], v[94:97]
	v_mfma_f32_16x16x32_bf16 v[82:85], v[188:191], v[172:175], v[82:85]
	v_mfma_f32_16x16x32_bf16 v[78:81], v[208:211], v[172:175], v[78:81]
	v_mfma_f32_16x16x32_bf16 v[70:73], v[188:191], v[180:183], v[70:73]
	v_mfma_f32_16x16x32_bf16 v[66:69], v[208:211], v[180:183], v[66:69]
	v_mfma_f32_16x16x32_bf16 v[114:117], v[192:195], v[160:163], v[114:117]
	v_mfma_f32_16x16x32_bf16 v[110:113], v[212:215], v[160:163], v[110:113]
	v_mfma_f32_16x16x32_bf16 v[98:101], v[192:195], v[168:171], v[98:101]
	v_mfma_f32_16x16x32_bf16 v[94:97], v[212:215], v[168:171], v[94:97]
	v_mfma_f32_16x16x32_bf16 v[82:85], v[192:195], v[176:179], v[82:85]
	v_mfma_f32_16x16x32_bf16 v[78:81], v[212:215], v[176:179], v[78:81]
	v_mfma_f32_16x16x32_bf16 v[70:73], v[192:195], v[184:187], v[70:73]
	v_mfma_f32_16x16x32_bf16 v[66:69], v[212:215], v[184:187], v[66:69]
	s_mov_b32 m0, s57
	v_lshl_add_u64 v[196:197], v[218:219], 0, s[10:11]
	s_barrier
	ds_read_b128 v[152:155], v159 offset:49152
	ds_read_b128 v[160:163], v159 offset:50176
	ds_read_b128 v[164:167], v159 offset:51200
	ds_read_b128 v[168:171], v159 offset:52224
	ds_read_b128 v[172:175], v159 offset:53248
	ds_read_b128 v[176:179], v159 offset:54272
	ds_read_b128 v[180:183], v159 offset:55296
	ds_read_b128 v[184:187], v159 offset:56320
	global_load_lds_dwordx4 v[196:197], off
	v_lshl_add_u64 v[196:197], v[220:221], 0, s[10:11]
	s_mov_b32 m0, s58
	s_nop 0
	global_load_lds_dwordx4 v[196:197], off
	s_barrier
	s_waitcnt lgkmcnt(0)
	s_waitcnt lgkmcnt(0)
	v_mfma_f32_16x16x32_bf16 v[62:65], v[130:133], v[152:155], v[62:65]
	v_mfma_f32_16x16x32_bf16 v[58:61], v[138:141], v[152:155], v[58:61]
	v_mfma_f32_16x16x32_bf16 v[54:57], v[130:133], v[164:167], v[54:57]
	v_mfma_f32_16x16x32_bf16 v[50:53], v[138:141], v[164:167], v[50:53]
	v_mfma_f32_16x16x32_bf16 v[46:49], v[130:133], v[172:175], v[46:49]
	v_mfma_f32_16x16x32_bf16 v[38:41], v[138:141], v[172:175], v[38:41]
	v_mfma_f32_16x16x32_bf16 v[30:33], v[130:133], v[180:183], v[30:33]
	v_mfma_f32_16x16x32_bf16 v[18:21], v[138:141], v[180:183], v[18:21]
	v_mfma_f32_16x16x32_bf16 v[62:65], v[134:137], v[160:163], v[62:65]
	v_mfma_f32_16x16x32_bf16 v[58:61], v[148:151], v[160:163], v[58:61]
	v_mfma_f32_16x16x32_bf16 v[54:57], v[134:137], v[168:171], v[54:57]
	v_mfma_f32_16x16x32_bf16 v[50:53], v[148:151], v[168:171], v[50:53]
	v_mfma_f32_16x16x32_bf16 v[46:49], v[134:137], v[176:179], v[46:49]
	v_mfma_f32_16x16x32_bf16 v[38:41], v[148:151], v[176:179], v[38:41]
	v_mfma_f32_16x16x32_bf16 v[30:33], v[134:137], v[184:187], v[30:33]
	v_mfma_f32_16x16x32_bf16 v[18:21], v[148:151], v[184:187], v[18:21]
	s_barrier
	s_add_u32 s22, s42, 0x40080
	s_addc_u32 s23, s43, 0
	s_add_i32 s42, s48, s52
	v_lshl_add_u64 v[130:131], s[22:23], 0, v[16:17]
	s_mov_b32 m0, s42
	s_nop 0
	global_load_lds_dwordx4 v[130:131], off
	v_lshl_add_u64 v[130:131], s[22:23], 0, v[142:143]
	s_add_i32 m0, s42, 0x2000
	s_nop 0
	global_load_lds_dwordx4 v[130:131], off
	s_waitcnt vmcnt(6)
	s_barrier
	v_mfma_f32_16x16x32_bf16 v[42:45], v[188:191], v[152:155], v[42:45]
	v_mfma_f32_16x16x32_bf16 v[34:37], v[208:211], v[152:155], v[34:37]
	v_mfma_f32_16x16x32_bf16 v[26:29], v[188:191], v[164:167], v[26:29]
	v_mfma_f32_16x16x32_bf16 v[22:25], v[208:211], v[164:167], v[22:25]
	v_mfma_f32_16x16x32_bf16 v[12:15], v[188:191], v[172:175], v[12:15]
	v_mfma_f32_16x16x32_bf16 v[8:11], v[208:211], v[172:175], v[8:11]
	v_mfma_f32_16x16x32_bf16 v[4:7], v[188:191], v[180:183], v[4:7]
	v_mfma_f32_16x16x32_bf16 v[0:3], v[208:211], v[180:183], v[0:3]
	v_mfma_f32_16x16x32_bf16 v[42:45], v[192:195], v[160:163], v[42:45]
	v_mfma_f32_16x16x32_bf16 v[34:37], v[212:215], v[160:163], v[34:37]
	v_mfma_f32_16x16x32_bf16 v[26:29], v[192:195], v[168:171], v[26:29]
	v_mfma_f32_16x16x32_bf16 v[22:25], v[212:215], v[168:171], v[22:25]
	v_mfma_f32_16x16x32_bf16 v[12:15], v[192:195], v[176:179], v[12:15]
	v_mfma_f32_16x16x32_bf16 v[8:11], v[212:215], v[176:179], v[8:11]
	v_mfma_f32_16x16x32_bf16 v[4:7], v[192:195], v[184:187], v[4:7]
	v_mfma_f32_16x16x32_bf16 v[0:3], v[212:215], v[184:187], v[0:3]
	s_add_i32 s82, s82, 2
	s_add_u32 s61, s61, 0x100
	s_addc_u32 s79, s79, 0
	s_cmp_gt_u32 s82, 13
	s_mov_b64 s[22:23], s[40:41]
	s_barrier
	s_cbranch_scc0 .LBB0_174
	v_lshl_or_b32 v132, s2, 8, v158
	v_lshl_add_u32 v130, s18, 8, v156
	v_ashrrev_i32_e32 v133, 31, v132
	v_lshlrev_b64 v[148:149], 2, v[132:133]
	v_ashrrev_i32_e32 v131, 31, v130
	v_lshl_add_u64 v[150:151], s[20:21], 0, v[148:149]
	v_lshlrev_b64 v[152:153], 12, v[130:131]
	v_lshl_add_u64 v[132:133], v[150:151], 0, v[152:153]
	global_load_dwordx4 v[160:163], v[132:133], off
	global_load_dwordx4 v[164:167], v[132:133], off offset:64
	global_load_dwordx4 v[168:171], v[132:133], off offset:512
	global_load_dwordx4 v[172:175], v[132:133], off offset:576
	v_or_b32_e32 v132, 16, v130
	v_ashrrev_i32_e32 v133, 31, v132
	v_lshlrev_b64 v[196:197], 12, v[132:133]
	v_lshl_add_u64 v[132:133], v[150:151], 0, v[196:197]
	global_load_dwordx4 v[176:179], v[132:133], off
	global_load_dwordx4 v[180:183], v[132:133], off offset:64
	global_load_dwordx4 v[184:187], v[132:133], off offset:512
	global_load_dwordx4 v[188:191], v[132:133], off offset:576
	v_or_b32_e32 v132, 32, v130
	v_ashrrev_i32_e32 v133, 31, v132
	v_or_b32_e32 v130, 48, v130
	v_lshlrev_b64 v[224:225], 12, v[132:133]
	v_ashrrev_i32_e32 v131, 31, v130
	v_lshl_add_u64 v[132:133], v[150:151], 0, v[224:225]
	v_lshlrev_b64 v[154:155], 12, v[130:131]
	global_load_dwordx4 v[192:195], v[132:133], off
	global_load_dwordx4 v[208:211], v[132:133], off offset:64
	global_load_dwordx4 v[212:215], v[132:133], off offset:512
	global_load_dwordx4 v[216:219], v[132:133], off offset:576
	v_lshl_add_u64 v[130:131], v[150:151], 0, v[154:155]
	global_load_dwordx4 v[220:223], v[130:131], off
	global_load_dwordx4 v[138:141], v[130:131], off offset:64
	global_load_dwordx4 v[134:137], v[130:131], off offset:512
	s_nop 0
	global_load_dwordx4 v[130:133], v[130:131], off offset:576
	s_waitcnt vmcnt(0) lgkmcnt(0)
	v_pk_add_f32 v[126:127], v[126:127], v[160:161]
	v_lshl_add_u64 v[160:161], s[20:21], 0, v[152:153]
	v_lshl_add_u64 v[160:161], v[160:161], 0, v[148:149]
	v_pk_add_f32 v[116:117], v[116:117], v[170:171]
	v_pk_add_f32 v[114:115], v[114:115], v[168:169]
	global_store_dwordx4 v[160:161], v[114:117], off offset:512
	v_pk_add_f32 v[112:113], v[112:113], v[174:175]
	v_pk_add_f32 v[100:101], v[100:101], v[186:187]
	v_lshl_add_u64 v[114:115], s[20:21], 0, v[196:197]
	v_lshl_add_u64 v[114:115], v[114:115], 0, v[148:149]
	v_pk_add_f32 v[98:99], v[98:99], v[184:185]
	global_store_dwordx4 v[114:115], v[98:101], off offset:512
	v_pk_add_f32 v[110:111], v[110:111], v[172:173]
	v_pk_add_f32 v[96:97], v[96:97], v[190:191]
	v_lshl_add_u64 v[98:99], s[20:21], 0, v[224:225]
	v_lshl_add_u64 v[98:99], v[98:99], 0, v[148:149]
	v_pk_add_f32 v[84:85], v[84:85], v[214:215]
	v_pk_add_f32 v[82:83], v[82:83], v[212:213]
	v_pk_add_f32 v[94:95], v[94:95], v[188:189]
	global_store_dwordx4 v[98:99], v[82:85], off offset:512
	v_pk_add_f32 v[80:81], v[80:81], v[218:219]
	v_pk_add_f32 v[78:79], v[78:79], v[216:217]
	v_lshl_add_u64 v[82:83], s[20:21], 0, v[154:155]
	v_pk_add_f32 v[128:129], v[128:129], v[162:163]
	v_pk_add_f32 v[124:125], v[124:125], v[166:167]
	v_pk_add_f32 v[122:123], v[122:123], v[164:165]
	global_store_dwordx4 v[160:161], v[110:113], off offset:576
	v_pk_add_f32 v[108:109], v[108:109], v[182:183]
	v_pk_add_f32 v[106:107], v[106:107], v[180:181]
	v_pk_add_f32 v[112:113], v[120:121], v[178:179]
	v_pk_add_f32 v[110:111], v[118:119], v[176:177]
	global_store_dwordx4 v[114:115], v[94:97], off offset:576
	v_pk_add_f32 v[92:93], v[92:93], v[210:211]
	v_pk_add_f32 v[90:91], v[90:91], v[208:209]
	v_pk_add_f32 v[96:97], v[104:105], v[194:195]
	v_pk_add_f32 v[94:95], v[102:103], v[192:193]
	global_store_dwordx4 v[98:99], v[78:81], off offset:576
	v_lshl_add_u64 v[82:83], v[82:83], 0, v[148:149]
	v_pk_add_f32 v[76:77], v[76:77], v[140:141]
	v_pk_add_f32 v[80:81], v[88:89], v[222:223]
	v_pk_add_f32 v[78:79], v[86:87], v[220:221]
	v_pk_add_f32 v[74:75], v[74:75], v[138:139]
	v_pk_add_f32 v[72:73], v[72:73], v[136:137]
	v_pk_add_f32 v[70:71], v[70:71], v[134:135]
	v_pk_add_f32 v[68:69], v[68:69], v[132:133]
	v_pk_add_f32 v[66:67], v[66:67], v[130:131]
	global_store_dwordx4 v[160:161], v[126:129], off
	global_store_dwordx4 v[160:161], v[122:125], off offset:64
	global_store_dwordx4 v[114:115], v[110:113], off
	global_store_dwordx4 v[114:115], v[106:109], off offset:64
	global_store_dwordx4 v[98:99], v[94:97], off
	global_store_dwordx4 v[98:99], v[90:93], off offset:64
	global_store_dwordx4 v[82:83], v[78:81], off
	global_store_dwordx4 v[82:83], v[74:77], off offset:64
	global_store_dwordx4 v[82:83], v[70:73], off offset:512
	global_store_dwordx4 v[82:83], v[66:69], off offset:576
	s_mov_b64 s[22:23], 0x80000
	v_lshl_add_u64 v[130:131], v[152:153], 0, s[22:23]
	s_mov_b64 s[22:23], 0x90000
	v_lshl_add_u64 v[132:133], v[152:153], 0, s[22:23]
	s_mov_b64 s[22:23], 0xa0000
	v_lshl_add_u64 v[134:135], v[152:153], 0, s[22:23]
	s_mov_b64 s[22:23], 0xb0000
	v_lshl_add_u64 v[136:137], v[152:153], 0, s[22:23]
	v_lshl_add_u64 v[78:79], v[150:151], 0, v[130:131]
	v_lshl_add_u64 v[94:95], v[150:151], 0, v[132:133]
	v_lshl_add_u64 v[110:111], v[150:151], 0, v[134:135]
	v_lshl_add_u64 v[126:127], v[150:151], 0, v[136:137]
	global_load_dwordx4 v[66:69], v[78:79], off
	global_load_dwordx4 v[70:73], v[78:79], off offset:64
	global_load_dwordx4 v[74:77], v[78:79], off offset:512
	v_lshl_add_u64 v[130:131], s[20:21], 0, v[130:131]
	global_load_dwordx4 v[78:81], v[78:79], off offset:576
	s_nop 0
	global_load_dwordx4 v[82:85], v[94:95], off
	global_load_dwordx4 v[86:89], v[94:95], off offset:64
	global_load_dwordx4 v[90:93], v[94:95], off offset:512
	v_lshl_add_u64 v[132:133], s[20:21], 0, v[132:133]
	global_load_dwordx4 v[94:97], v[94:95], off offset:576
	s_nop 0
	global_load_dwordx4 v[98:101], v[110:111], off
	global_load_dwordx4 v[102:105], v[110:111], off offset:64
	global_load_dwordx4 v[106:109], v[110:111], off offset:512
	v_lshl_add_u64 v[134:135], s[20:21], 0, v[134:135]
	global_load_dwordx4 v[110:113], v[110:111], off offset:576
	s_nop 0
	global_load_dwordx4 v[114:117], v[126:127], off
	global_load_dwordx4 v[118:121], v[126:127], off offset:64
	global_load_dwordx4 v[122:125], v[126:127], off offset:512
	s_nop 0
	global_load_dwordx4 v[126:129], v[126:127], off offset:576
	v_lshl_add_u64 v[136:137], s[20:21], 0, v[136:137]
	v_lshl_add_u64 v[130:131], v[130:131], 0, v[148:149]
	v_lshl_add_u64 v[132:133], v[132:133], 0, v[148:149]
	v_lshl_add_u64 v[134:135], v[134:135], 0, v[148:149]
	v_lshl_add_u64 v[136:137], v[136:137], 0, v[148:149]
	s_waitcnt vmcnt(0) lgkmcnt(0)
	v_pk_add_f32 v[64:65], v[64:65], v[68:69]
	v_pk_add_f32 v[62:63], v[62:63], v[66:67]
	v_pk_add_f32 v[60:61], v[60:61], v[72:73]
	v_pk_add_f32 v[58:59], v[58:59], v[70:71]
	v_pk_add_f32 v[44:45], v[44:45], v[76:77]
	v_pk_add_f32 v[42:43], v[42:43], v[74:75]
	v_pk_add_f32 v[36:37], v[36:37], v[80:81]
	v_pk_add_f32 v[34:35], v[34:35], v[78:79]
	v_pk_add_f32 v[56:57], v[56:57], v[84:85]
	v_pk_add_f32 v[54:55], v[54:55], v[82:83]
	v_pk_add_f32 v[52:53], v[52:53], v[88:89]
	v_pk_add_f32 v[50:51], v[50:51], v[86:87]
	v_pk_add_f32 v[28:29], v[28:29], v[92:93]
	v_pk_add_f32 v[26:27], v[26:27], v[90:91]
	v_pk_add_f32 v[24:25], v[24:25], v[96:97]
	v_pk_add_f32 v[22:23], v[22:23], v[94:95]
	v_pk_add_f32 v[48:49], v[48:49], v[100:101]
	v_pk_add_f32 v[46:47], v[46:47], v[98:99]
	v_pk_add_f32 v[40:41], v[40:41], v[104:105]
	v_pk_add_f32 v[38:39], v[38:39], v[102:103]
	v_pk_add_f32 v[14:15], v[14:15], v[108:109]
	v_pk_add_f32 v[12:13], v[12:13], v[106:107]
	v_pk_add_f32 v[10:11], v[10:11], v[112:113]
	v_pk_add_f32 v[8:9], v[8:9], v[110:111]
	v_pk_add_f32 v[32:33], v[32:33], v[116:117]
	v_pk_add_f32 v[30:31], v[30:31], v[114:115]
	v_pk_add_f32 v[20:21], v[20:21], v[120:121]
	v_pk_add_f32 v[18:19], v[18:19], v[118:119]
	v_pk_add_f32 v[6:7], v[6:7], v[124:125]
	v_pk_add_f32 v[4:5], v[4:5], v[122:123]
	v_pk_add_f32 v[2:3], v[2:3], v[128:129]
	v_pk_add_f32 v[0:1], v[0:1], v[126:127]
	global_store_dwordx4 v[130:131], v[62:65], off
	global_store_dwordx4 v[130:131], v[58:61], off offset:64
	global_store_dwordx4 v[130:131], v[42:45], off offset:512
	global_store_dwordx4 v[130:131], v[34:37], off offset:576
	global_store_dwordx4 v[132:133], v[54:57], off
	global_store_dwordx4 v[132:133], v[50:53], off offset:64
	global_store_dwordx4 v[132:133], v[26:29], off offset:512
	global_store_dwordx4 v[132:133], v[22:25], off offset:576
	global_store_dwordx4 v[134:135], v[46:49], off
	global_store_dwordx4 v[134:135], v[38:41], off offset:64
	global_store_dwordx4 v[134:135], v[12:15], off offset:512
	global_store_dwordx4 v[134:135], v[8:11], off offset:576
	global_store_dwordx4 v[136:137], v[30:33], off
	global_store_dwordx4 v[136:137], v[18:21], off offset:64
	global_store_dwordx4 v[136:137], v[4:7], off offset:512
	global_store_dwordx4 v[136:137], v[0:3], off offset:576
	v_readlane_b32 s82, v255, 5
	s_and_b64 vcc, exec, s[38:39]
	s_mov_b32 s2, s4
	s_mov_b32 s18, s8
	s_mov_b64 s[40:41], s[16:17]
	s_mov_b64 s[22:23], s[14:15]
	v_readlane_b32 s83, v255, 6
	s_cbranch_vccz .LBB0_167
	s_waitcnt vmcnt(0)
	s_cmpk_gt_u32 s35, 0xff
	s_cbranch_scc1 .LBB0_178
	s_barrier

.LBB0_210:
	s_ashr_i32 s91, s90, 31
	v_cmp_lt_i64_e64 s[38:39], s[4:5], v[202:203]
	s_lshl_b64 s[4:5], s[90:91], 24
	s_add_u32 s2, s50, s4
	s_addc_u32 s9, s51, s5
	s_ashr_i32 s93, s92, 31
	s_lshl_b64 s[4:5], s[92:93], 18
	s_add_u32 s56, s2, s4
	s_addc_u32 s57, s9, s5
	s_and_b64 s[4:5], s[38:39], exec
	s_cselect_b32 s2, s57, s19
	s_cselect_b32 s9, s56, s18
	s_lshl_b64 s[4:5], s[90:91], 20
	s_add_u32 s12, s37, s4
	s_addc_u32 s15, s48, s5
	s_ashr_i32 s55, s54, 31
	s_lshl_b64 s[4:5], s[54:55], 18
	s_add_u32 s4, s12, s4
	s_addc_u32 s5, s15, s5
	s_and_b64 s[22:23], s[38:39], exec
	s_cselect_b32 s12, s5, s17
	s_cselect_b32 s15, s4, s16
	s_add_u32 s34, s16, 0x100
	s_addc_u32 s40, s17, 0
	s_add_u32 s16, s18, 0x20080
	s_addc_u32 s17, s19, 0
	s_mov_b32 s41, -2
.LBB0_211:
	s_add_u32 s18, s16, 0xfffe0080
	s_addc_u32 s19, s17, -1
	s_add_i32 s42, 0, 0x10000
	v_add_u32_e32 v12, s42, v241
	ds_read_b128 v[0:3], v12
	ds_read_b128 v[4:7], v12 offset:1024
	ds_read_b128 v[8:11], v12 offset:2048
	ds_read_b128 v[12:15], v12 offset:3072
	s_cmp_eq_u32 s41, 4
	s_cselect_b32 s23, s2, s19
	s_cselect_b32 s22, s9, s18
	s_cselect_b32 s19, s12, s40
	s_cselect_b32 s18, s15, s34
	v_lshl_add_u64 v[178:179], s[16:17], 0, v[216:217]
	s_add_i32 m0, s52, 0xc000
	ds_read_b128 v[146:149], v243
	ds_read_b128 v[150:153], v243 offset:1024
	ds_read_b128 v[154:157], v243 offset:2048
	ds_read_b128 v[158:161], v243 offset:3072
	ds_read_b128 v[162:165], v243 offset:4096
	ds_read_b128 v[166:169], v243 offset:5120
	ds_read_b128 v[170:173], v243 offset:6144
	ds_read_b128 v[174:177], v243 offset:7168
	global_load_lds_dwordx4 v[178:179], off
	v_lshl_add_u64 v[178:179], s[16:17], 0, v[214:215]
	s_add_i32 m0, s52, 0xe000
	s_nop 0
	global_load_lds_dwordx4 v[178:179], off
	s_waitcnt lgkmcnt(8)
	s_barrier
	s_waitcnt lgkmcnt(0)
	s_waitcnt lgkmcnt(0)
	v_mfma_f32_16x16x32_bf16 v[142:145], v[0:3], v[146:149], v[142:145]
	v_mfma_f32_16x16x32_bf16 v[138:141], v[8:11], v[146:149], v[138:141]
	v_mfma_f32_16x16x32_bf16 v[134:137], v[0:3], v[154:157], v[134:137]
	v_mfma_f32_16x16x32_bf16 v[130:133], v[8:11], v[154:157], v[130:133]
	v_mfma_f32_16x16x32_bf16 v[126:129], v[0:3], v[162:165], v[126:129]
	v_mfma_f32_16x16x32_bf16 v[122:125], v[8:11], v[162:165], v[122:125]
	v_mfma_f32_16x16x32_bf16 v[118:121], v[0:3], v[170:173], v[118:121]
	v_mfma_f32_16x16x32_bf16 v[114:117], v[8:11], v[170:173], v[114:117]
	v_mfma_f32_16x16x32_bf16 v[142:145], v[4:7], v[150:153], v[142:145]
	v_mfma_f32_16x16x32_bf16 v[138:141], v[12:15], v[150:153], v[138:141]
	v_mfma_f32_16x16x32_bf16 v[134:137], v[4:7], v[158:161], v[134:137]
	v_mfma_f32_16x16x32_bf16 v[130:133], v[12:15], v[158:161], v[130:133]
	v_mfma_f32_16x16x32_bf16 v[126:129], v[4:7], v[166:169], v[126:129]
	v_mfma_f32_16x16x32_bf16 v[122:125], v[12:15], v[166:169], v[122:125]
	v_mfma_f32_16x16x32_bf16 v[118:121], v[4:7], v[174:177], v[118:121]
	v_mfma_f32_16x16x32_bf16 v[114:117], v[12:15], v[174:177], v[114:117]
	s_barrier
	s_add_i32 s55, 0, 0x14000
	s_add_i32 s42, s42, s49
	v_add_u32_e32 v190, s55, v241
	v_lshl_add_u64 v[194:195], s[18:19], 0, v[16:17]
	s_mov_b32 m0, s42
	ds_read_b128 v[178:181], v190
	ds_read_b128 v[182:185], v190 offset:1024
	ds_read_b128 v[186:189], v190 offset:2048
	ds_read_b128 v[190:193], v190 offset:3072
	global_load_lds_dwordx4 v[194:195], off
	v_lshl_add_u64 v[196:197], s[18:19], 0, v[212:213]
	s_add_i32 m0, s42, 0x2000
	s_nop 0
	global_load_lds_dwordx4 v[196:197], off
	s_barrier
	s_waitcnt lgkmcnt(0)
	s_waitcnt lgkmcnt(0)
	v_mfma_f32_16x16x32_bf16 v[110:113], v[178:181], v[146:149], v[110:113]
	v_mfma_f32_16x16x32_bf16 v[106:109], v[186:189], v[146:149], v[106:109]
	v_mfma_f32_16x16x32_bf16 v[102:105], v[178:181], v[154:157], v[102:105]
	v_mfma_f32_16x16x32_bf16 v[98:101], v[186:189], v[154:157], v[98:101]
	v_mfma_f32_16x16x32_bf16 v[94:97], v[178:181], v[162:165], v[94:97]
	v_mfma_f32_16x16x32_bf16 v[90:93], v[186:189], v[162:165], v[90:93]
	v_mfma_f32_16x16x32_bf16 v[86:89], v[178:181], v[170:173], v[86:89]
	v_mfma_f32_16x16x32_bf16 v[82:85], v[186:189], v[170:173], v[82:85]
	v_mfma_f32_16x16x32_bf16 v[110:113], v[182:185], v[150:153], v[110:113]
	v_mfma_f32_16x16x32_bf16 v[106:109], v[190:193], v[150:153], v[106:109]
	v_mfma_f32_16x16x32_bf16 v[102:105], v[182:185], v[158:161], v[102:105]
	v_mfma_f32_16x16x32_bf16 v[98:101], v[190:193], v[158:161], v[98:101]
	v_mfma_f32_16x16x32_bf16 v[94:97], v[182:185], v[166:169], v[94:97]
	v_mfma_f32_16x16x32_bf16 v[90:93], v[190:193], v[166:169], v[90:93]
	v_mfma_f32_16x16x32_bf16 v[86:89], v[182:185], v[174:177], v[86:89]
	v_mfma_f32_16x16x32_bf16 v[82:85], v[190:193], v[174:177], v[82:85]
	s_mov_b32 m0, s52
	v_lshl_add_u64 v[218:219], s[22:23], 0, v[208:209]
	s_barrier
	ds_read_b128 v[146:149], v243 offset:16384
	ds_read_b128 v[150:153], v243 offset:17408
	ds_read_b128 v[154:157], v243 offset:18432
	ds_read_b128 v[158:161], v243 offset:19456
	ds_read_b128 v[162:165], v243 offset:20480
	ds_read_b128 v[166:169], v243 offset:21504
	ds_read_b128 v[170:173], v243 offset:22528
	ds_read_b128 v[174:177], v243 offset:23552
	global_load_lds_dwordx4 v[218:219], off
	v_lshl_add_u64 v[220:221], s[22:23], 0, v[210:211]
	s_mov_b32 m0, s58
	s_nop 0
	global_load_lds_dwordx4 v[220:221], off
	s_barrier
	s_waitcnt lgkmcnt(0)
	s_waitcnt lgkmcnt(0)
	v_mfma_f32_16x16x32_bf16 v[78:81], v[0:3], v[146:149], v[78:81]
	v_mfma_f32_16x16x32_bf16 v[74:77], v[8:11], v[146:149], v[74:77]
	v_mfma_f32_16x16x32_bf16 v[70:73], v[0:3], v[154:157], v[70:73]
	v_mfma_f32_16x16x32_bf16 v[66:69], v[8:11], v[154:157], v[66:69]
	v_mfma_f32_16x16x32_bf16 v[62:65], v[0:3], v[162:165], v[62:65]
	v_mfma_f32_16x16x32_bf16 v[58:61], v[8:11], v[162:165], v[58:61]
	v_mfma_f32_16x16x32_bf16 v[0:3], v[0:3], v[170:173], v[54:57]
	v_mfma_f32_16x16x32_bf16 v[78:81], v[4:7], v[150:153], v[78:81]
	v_mfma_f32_16x16x32_bf16 v[74:77], v[12:15], v[150:153], v[74:77]
	v_mfma_f32_16x16x32_bf16 v[70:73], v[4:7], v[158:161], v[70:73]
	v_mfma_f32_16x16x32_bf16 v[66:69], v[12:15], v[158:161], v[66:69]
	v_mfma_f32_16x16x32_bf16 v[62:65], v[4:7], v[166:169], v[62:65]
	v_mfma_f32_16x16x32_bf16 v[58:61], v[12:15], v[166:169], v[58:61]
	v_mfma_f32_16x16x32_bf16 v[0:3], v[4:7], v[174:177], v[0:3]
	v_mfma_f32_16x16x32_bf16 v[4:7], v[8:11], v[170:173], v[50:53]
	v_mfma_f32_16x16x32_bf16 v[4:7], v[12:15], v[174:177], v[4:7]
	s_barrier
	s_add_u32 s42, s18, 0x20000
	s_addc_u32 s43, s19, 0
	s_add_i32 s55, s55, s49
	v_lshl_add_u64 v[8:9], s[42:43], 0, v[16:17]
	s_mov_b32 m0, s55
	s_nop 0
	global_load_lds_dwordx4 v[8:9], off
	v_lshl_add_u64 v[8:9], s[42:43], 0, v[212:213]
	s_add_i32 m0, s55, 0x2000
	s_nop 0
	global_load_lds_dwordx4 v[8:9], off
	s_waitcnt vmcnt(6)
	s_barrier
	v_mfma_f32_16x16x32_bf16 v[38:41], v[178:181], v[154:157], v[38:41]
	v_mfma_f32_16x16x32_bf16 v[34:37], v[186:189], v[154:157], v[34:37]
	v_mfma_f32_16x16x32_bf16 v[30:33], v[178:181], v[162:165], v[30:33]
	v_mfma_f32_16x16x32_bf16 v[26:29], v[186:189], v[162:165], v[26:29]
	v_mfma_f32_16x16x32_bf16 v[22:25], v[178:181], v[170:173], v[22:25]
	v_mfma_f32_16x16x32_bf16 v[18:21], v[186:189], v[170:173], v[18:21]
	v_mfma_f32_16x16x32_bf16 v[8:11], v[178:181], v[146:149], v[46:49]
	v_mfma_f32_16x16x32_bf16 v[12:15], v[186:189], v[146:149], v[42:45]
	v_mfma_f32_16x16x32_bf16 v[38:41], v[182:185], v[158:161], v[38:41]
	v_mfma_f32_16x16x32_bf16 v[34:37], v[190:193], v[158:161], v[34:37]
	v_mfma_f32_16x16x32_bf16 v[30:33], v[182:185], v[166:169], v[30:33]
	v_mfma_f32_16x16x32_bf16 v[26:29], v[190:193], v[166:169], v[26:29]
	v_mfma_f32_16x16x32_bf16 v[22:25], v[182:185], v[174:177], v[22:25]
	v_mfma_f32_16x16x32_bf16 v[18:21], v[190:193], v[174:177], v[18:21]
	v_mfma_f32_16x16x32_bf16 v[8:11], v[182:185], v[150:153], v[8:11]
	v_mfma_f32_16x16x32_bf16 v[12:15], v[190:193], v[150:153], v[12:15]
	s_add_i32 s42, 0, 0x18000
	v_add_u32_e32 v54, s42, v241
	s_barrier
	ds_read_b128 v[42:45], v54
	ds_read_b128 v[46:49], v54 offset:1024
	ds_read_b128 v[50:53], v54 offset:2048
	ds_read_b128 v[146:149], v54 offset:3072
	s_add_u32 s22, s22, 0x20000
	s_addc_u32 s23, s23, 0
	s_mov_b32 m0, s59
	v_lshl_add_u64 v[178:179], s[22:23], 0, v[208:209]
	ds_read_b128 v[54:57], v243 offset:32768
	ds_read_b128 v[150:153], v243 offset:33792
	ds_read_b128 v[154:157], v243 offset:34816
	ds_read_b128 v[158:161], v243 offset:35840
	ds_read_b128 v[162:165], v243 offset:36864
	ds_read_b128 v[166:169], v243 offset:37888
	ds_read_b128 v[170:173], v243 offset:38912
	ds_read_b128 v[174:177], v243 offset:39936
	global_load_lds_dwordx4 v[178:179], off
	v_lshl_add_u64 v[178:179], s[22:23], 0, v[210:211]
	s_mov_b32 m0, s60
	s_nop 0
	global_load_lds_dwordx4 v[178:179], off
	s_waitcnt lgkmcnt(8)
	s_barrier
	s_waitcnt lgkmcnt(0)
	s_waitcnt lgkmcnt(0)
	v_mfma_f32_16x16x32_bf16 v[142:145], v[42:45], v[54:57], v[142:145]
	v_mfma_f32_16x16x32_bf16 v[138:141], v[50:53], v[54:57], v[138:141]
	v_mfma_f32_16x16x32_bf16 v[134:137], v[42:45], v[154:157], v[134:137]
	v_mfma_f32_16x16x32_bf16 v[130:133], v[50:53], v[154:157], v[130:133]
	v_mfma_f32_16x16x32_bf16 v[126:129], v[42:45], v[162:165], v[126:129]
	v_mfma_f32_16x16x32_bf16 v[122:125], v[50:53], v[162:165], v[122:125]
	v_mfma_f32_16x16x32_bf16 v[118:121], v[42:45], v[170:173], v[118:121]
	v_mfma_f32_16x16x32_bf16 v[114:117], v[50:53], v[170:173], v[114:117]
	v_mfma_f32_16x16x32_bf16 v[142:145], v[46:49], v[150:153], v[142:145]
	v_mfma_f32_16x16x32_bf16 v[138:141], v[146:149], v[150:153], v[138:141]
	v_mfma_f32_16x16x32_bf16 v[134:137], v[46:49], v[158:161], v[134:137]
	v_mfma_f32_16x16x32_bf16 v[130:133], v[146:149], v[158:161], v[130:133]
	v_mfma_f32_16x16x32_bf16 v[126:129], v[46:49], v[166:169], v[126:129]
	v_mfma_f32_16x16x32_bf16 v[122:125], v[146:149], v[166:169], v[122:125]
	v_mfma_f32_16x16x32_bf16 v[118:121], v[46:49], v[174:177], v[118:121]
	v_mfma_f32_16x16x32_bf16 v[114:117], v[146:149], v[174:177], v[114:117]
	s_barrier
	s_add_i32 s22, 0, 0x1c000
	s_add_i32 s23, s42, s49
	v_add_u32_e32 v190, s22, v241
	v_lshl_add_u64 v[194:195], v[194:195], 0, s[10:11]
	s_mov_b32 m0, s23
	ds_read_b128 v[178:181], v190
	ds_read_b128 v[182:185], v190 offset:1024
	ds_read_b128 v[186:189], v190 offset:2048
	ds_read_b128 v[190:193], v190 offset:3072
	global_load_lds_dwordx4 v[194:195], off
	v_lshl_add_u64 v[194:195], v[196:197], 0, s[10:11]
	s_add_i32 m0, s23, 0x2000
	s_nop 0
	global_load_lds_dwordx4 v[194:195], off
	s_barrier
	s_waitcnt lgkmcnt(0)
	s_waitcnt lgkmcnt(0)
	v_mfma_f32_16x16x32_bf16 v[110:113], v[178:181], v[54:57], v[110:113]
	v_mfma_f32_16x16x32_bf16 v[54:57], v[186:189], v[54:57], v[106:109]
	v_mfma_f32_16x16x32_bf16 v[106:109], v[190:193], v[150:153], v[54:57]
	v_mfma_f32_16x16x32_bf16 v[54:57], v[178:181], v[154:157], v[102:105]
	v_mfma_f32_16x16x32_bf16 v[102:105], v[182:185], v[158:161], v[54:57]
	v_mfma_f32_16x16x32_bf16 v[54:57], v[186:189], v[154:157], v[98:101]
	v_mfma_f32_16x16x32_bf16 v[98:101], v[190:193], v[158:161], v[54:57]
	v_mfma_f32_16x16x32_bf16 v[54:57], v[178:181], v[162:165], v[94:97]
	v_mfma_f32_16x16x32_bf16 v[94:97], v[182:185], v[166:169], v[54:57]
	v_mfma_f32_16x16x32_bf16 v[54:57], v[186:189], v[162:165], v[90:93]
	v_mfma_f32_16x16x32_bf16 v[90:93], v[190:193], v[166:169], v[54:57]
	v_mfma_f32_16x16x32_bf16 v[54:57], v[178:181], v[170:173], v[86:89]
	v_mfma_f32_16x16x32_bf16 v[86:89], v[182:185], v[174:177], v[54:57]
	v_mfma_f32_16x16x32_bf16 v[54:57], v[186:189], v[170:173], v[82:85]
	v_mfma_f32_16x16x32_bf16 v[110:113], v[182:185], v[150:153], v[110:113]
	v_mfma_f32_16x16x32_bf16 v[82:85], v[190:193], v[174:177], v[54:57]
	s_mov_b32 m0, s61
	s_nop 3
	v_lshl_add_u64 v[54:55], v[218:219], 0, s[10:11]
	s_barrier
	ds_read_b128 v[150:153], v243 offset:49152
	ds_read_b128 v[154:157], v243 offset:50176
	ds_read_b128 v[158:161], v243 offset:51200
	ds_read_b128 v[162:165], v243 offset:52224
	ds_read_b128 v[166:169], v243 offset:53248
	ds_read_b128 v[170:173], v243 offset:54272
	ds_read_b128 v[174:177], v243 offset:55296
	ds_read_b128 v[194:197], v243 offset:56320
	global_load_lds_dwordx4 v[54:55], off
	v_lshl_add_u64 v[54:55], v[220:221], 0, s[10:11]
	s_mov_b32 m0, s35
	s_nop 0
	global_load_lds_dwordx4 v[54:55], off
	s_barrier
	s_waitcnt lgkmcnt(0)
	s_waitcnt lgkmcnt(0)
	v_mfma_f32_16x16x32_bf16 v[54:57], v[42:45], v[150:153], v[78:81]
	v_mfma_f32_16x16x32_bf16 v[78:81], v[46:49], v[154:157], v[54:57]
	v_mfma_f32_16x16x32_bf16 v[54:57], v[50:53], v[150:153], v[74:77]
	v_mfma_f32_16x16x32_bf16 v[74:77], v[146:149], v[154:157], v[54:57]
	v_mfma_f32_16x16x32_bf16 v[54:57], v[42:45], v[158:161], v[70:73]
	v_mfma_f32_16x16x32_bf16 v[70:73], v[46:49], v[162:165], v[54:57]
	v_mfma_f32_16x16x32_bf16 v[54:57], v[50:53], v[158:161], v[66:69]
	v_mfma_f32_16x16x32_bf16 v[66:69], v[146:149], v[162:165], v[54:57]
	v_mfma_f32_16x16x32_bf16 v[54:57], v[42:45], v[166:169], v[62:65]
	v_mfma_f32_16x16x32_bf16 v[62:65], v[46:49], v[170:173], v[54:57]
	v_mfma_f32_16x16x32_bf16 v[54:57], v[50:53], v[166:169], v[58:61]
	v_mfma_f32_16x16x32_bf16 v[0:3], v[42:45], v[174:177], v[0:3]
	v_mfma_f32_16x16x32_bf16 v[58:61], v[146:149], v[170:173], v[54:57]
	v_mfma_f32_16x16x32_bf16 v[54:57], v[46:49], v[194:197], v[0:3]
	v_mfma_f32_16x16x32_bf16 v[0:3], v[50:53], v[174:177], v[4:7]
	v_mfma_f32_16x16x32_bf16 v[50:53], v[146:149], v[194:197], v[0:3]
	s_barrier
	s_add_u32 s18, s18, 0x20080
	s_addc_u32 s19, s19, 0
	s_add_i32 s22, s22, s49
	s_nop 1
	v_lshl_add_u64 v[0:1], s[18:19], 0, v[16:17]
	s_mov_b32 m0, s22
	s_nop 0
	global_load_lds_dwordx4 v[0:1], off
	v_lshl_add_u64 v[0:1], s[18:19], 0, v[212:213]
	s_add_i32 m0, s22, 0x2000
	s_nop 0
	global_load_lds_dwordx4 v[0:1], off
	s_waitcnt vmcnt(6)
	s_barrier
	v_mfma_f32_16x16x32_bf16 v[0:3], v[178:181], v[150:153], v[8:11]
	v_mfma_f32_16x16x32_bf16 v[46:49], v[182:185], v[154:157], v[0:3]
	v_mfma_f32_16x16x32_bf16 v[0:3], v[186:189], v[150:153], v[12:15]
	v_mfma_f32_16x16x32_bf16 v[42:45], v[190:193], v[154:157], v[0:3]
	v_mfma_f32_16x16x32_bf16 v[0:3], v[178:181], v[158:161], v[38:41]
	v_mfma_f32_16x16x32_bf16 v[38:41], v[182:185], v[162:165], v[0:3]
	v_mfma_f32_16x16x32_bf16 v[0:3], v[186:189], v[158:161], v[34:37]
	v_mfma_f32_16x16x32_bf16 v[34:37], v[190:193], v[162:165], v[0:3]
	v_mfma_f32_16x16x32_bf16 v[0:3], v[178:181], v[166:169], v[30:33]
	v_mfma_f32_16x16x32_bf16 v[30:33], v[182:185], v[170:173], v[0:3]
	v_mfma_f32_16x16x32_bf16 v[0:3], v[186:189], v[166:169], v[26:29]
	v_mfma_f32_16x16x32_bf16 v[26:29], v[190:193], v[170:173], v[0:3]
	v_mfma_f32_16x16x32_bf16 v[0:3], v[178:181], v[174:177], v[22:25]
	v_mfma_f32_16x16x32_bf16 v[22:25], v[182:185], v[194:197], v[0:3]
	v_mfma_f32_16x16x32_bf16 v[0:3], v[186:189], v[174:177], v[18:21]
	v_mfma_f32_16x16x32_bf16 v[18:21], v[190:193], v[194:197], v[0:3]
	s_add_i32 s41, s41, 2
	s_add_u32 s34, s34, 0x100
	s_addc_u32 s40, s40, 0
	s_add_u32 s16, s16, 0x100
	s_addc_u32 s17, s17, 0
	s_cmp_gt_u32 s41, 5
	s_barrier
	s_cbranch_scc0 .LBB0_211
	s_cmp_eq_u32 s84, 3
	s_cselect_b64 s[16:17], -1, 0
	s_cmp_lg_u32 s84, 3
	v_lshl_add_u32 v220, s8, 8, v240
	v_lshl_or_b32 v218, s14, 8, v242
	s_cselect_b64 s[8:9], -1, 0
	s_lshl_b32 s14, s84, 10
	v_mov_b64_e32 v[0:1], s[94:95]
	s_ashr_i32 s15, s14, 31
	v_mad_i64_i32 v[0:1], s[18:19], v220, s66, v[0:1]
	v_ashrrev_i32_e32 v219, 31, v218
	v_lshl_add_u64 v[0:1], s[14:15], 1, v[0:1]
	v_lshl_add_u64 v[4:5], v[218:219], 1, v[0:1]
	v_add_co_u32_e32 v0, vcc, 0x2000, v4
	s_mov_b64 s[18:19], 0x2400
	s_nop 0
	v_addc_co_u32_e32 v1, vcc, 0, v5, vcc
	global_load_dwordx4 v[0:3], v[0:1], off offset:1024
	s_and_b64 vcc, exec, s[16:17]
	v_lshl_add_u64 v[4:5], v[4:5], 0, s[18:19]
	s_cbranch_vccnz .LBB0_214
	global_load_dwordx4 v[12:15], v[4:5], off offset:2048

.LBB0_978:
	s_ashr_i32 s9, s8, 31
	v_cmp_lt_i64_e32 vcc, s[14:15], v[206:207]
	s_lshl_b64 s[14:15], s[8:9], 19
	s_add_u32 s14, s30, s14
	s_addc_u32 s15, s31, s15
	s_and_b64 s[16:17], vcc, exec
	s_cselect_b32 s9, s15, s23
	s_cselect_b32 s56, s14, s22
	s_ashr_i32 s5, s4, 31
	s_lshl_b64 s[16:17], s[4:5], 19
	s_add_u32 s16, s44, s16
	s_addc_u32 s17, s45, s17
	s_and_b64 s[28:29], vcc, exec
	s_cselect_b32 s5, s17, s21
	s_cselect_b32 s57, s16, s20
	s_add_u32 s58, s20, 0x100
	s_addc_u32 s59, s21, 0
	s_add_u32 s20, s22, 0x40080
	v_mov_b32_e32 v26, 0
	s_addc_u32 s21, s23, 0
	s_mov_b32 s60, -2
	v_mov_b32_e32 v27, v26
	v_mov_b32_e32 v28, v26
	v_mov_b32_e32 v29, v26
	v_mov_b32_e32 v38, v26
	v_mov_b32_e32 v39, v26
	v_mov_b32_e32 v40, v26
	v_mov_b32_e32 v41, v26
	v_mov_b32_e32 v46, v26
	v_mov_b32_e32 v47, v26
	v_mov_b32_e32 v48, v26
	v_mov_b32_e32 v49, v26
	v_mov_b32_e32 v58, v26
	v_mov_b32_e32 v59, v26
	v_mov_b32_e32 v60, v26
	v_mov_b32_e32 v61, v26
	v_mov_b32_e32 v82, v26
	v_mov_b32_e32 v83, v26
	v_mov_b32_e32 v84, v26
	v_mov_b32_e32 v85, v26
	v_mov_b32_e32 v86, v26
	v_mov_b32_e32 v87, v26
	v_mov_b32_e32 v88, v26
	v_mov_b32_e32 v89, v26
	v_mov_b32_e32 v90, v26
	v_mov_b32_e32 v91, v26
	v_mov_b32_e32 v92, v26
	v_mov_b32_e32 v93, v26
	v_mov_b32_e32 v94, v26
	v_mov_b32_e32 v95, v26
	v_mov_b32_e32 v96, v26
	v_mov_b32_e32 v97, v26
	v_mov_b32_e32 v0, v26
	v_mov_b32_e32 v1, v26
	v_mov_b32_e32 v2, v26
	v_mov_b32_e32 v3, v26
	v_mov_b32_e32 v4, v26
	v_mov_b32_e32 v5, v26
	v_mov_b32_e32 v6, v26
	v_mov_b32_e32 v7, v26
	v_mov_b32_e32 v8, v26
	v_mov_b32_e32 v9, v26
	v_mov_b32_e32 v10, v26
	v_mov_b32_e32 v11, v26
	v_mov_b32_e32 v12, v26
	v_mov_b32_e32 v13, v26
	v_mov_b32_e32 v14, v26
	v_mov_b32_e32 v15, v26
	v_mov_b32_e32 v18, v26
	v_mov_b32_e32 v19, v26
	v_mov_b32_e32 v20, v26
	v_mov_b32_e32 v21, v26
	v_mov_b32_e32 v22, v26
	v_mov_b32_e32 v23, v26
	v_mov_b32_e32 v24, v26
	v_mov_b32_e32 v25, v26
	v_mov_b32_e32 v30, v26
	v_mov_b32_e32 v31, v26
	v_mov_b32_e32 v32, v26
	v_mov_b32_e32 v33, v26
	s_waitcnt lgkmcnt(0)
	v_mov_b32_e32 v34, v26
	v_mov_b32_e32 v35, v26
	v_mov_b32_e32 v36, v26
	v_mov_b32_e32 v37, v26
	v_mov_b32_e32 v98, v26
	v_mov_b32_e32 v99, v26
	v_mov_b32_e32 v100, v26
	v_mov_b32_e32 v101, v26
	v_mov_b32_e32 v102, v26
	v_mov_b32_e32 v103, v26
	v_mov_b32_e32 v104, v26
	v_mov_b32_e32 v105, v26
	v_mov_b32_e32 v106, v26
	v_mov_b32_e32 v107, v26
	v_mov_b32_e32 v108, v26
	v_mov_b32_e32 v109, v26
	v_mov_b32_e32 v110, v26
	v_mov_b32_e32 v111, v26
	v_mov_b32_e32 v112, v26
	v_mov_b32_e32 v113, v26
	v_mov_b32_e32 v114, v26
	v_mov_b32_e32 v115, v26
	v_mov_b32_e32 v116, v26
	v_mov_b32_e32 v117, v26
	v_mov_b32_e32 v118, v26
	v_mov_b32_e32 v119, v26
	v_mov_b32_e32 v120, v26
	v_mov_b32_e32 v121, v26
	v_mov_b32_e32 v122, v26
	v_mov_b32_e32 v123, v26
	v_mov_b32_e32 v124, v26
	v_mov_b32_e32 v125, v26
	v_mov_b32_e32 v126, v26
	v_mov_b32_e32 v127, v26
	v_mov_b32_e32 v128, v26
	v_mov_b32_e32 v129, v26
	v_mov_b32_e32 v42, v26
	v_mov_b32_e32 v43, v26
	v_mov_b32_e32 v44, v26
	v_mov_b32_e32 v45, v26
	v_mov_b32_e32 v50, v26
	v_mov_b32_e32 v51, v26
	v_mov_b32_e32 v52, v26
	v_mov_b32_e32 v53, v26
	v_mov_b32_e32 v54, v26
	v_mov_b32_e32 v55, v26
	v_mov_b32_e32 v56, v26
	v_mov_b32_e32 v57, v26
	v_mov_b32_e32 v62, v26
	v_mov_b32_e32 v63, v26
	v_mov_b32_e32 v64, v26
	v_mov_b32_e32 v65, v26
	v_mov_b32_e32 v66, v26
	v_mov_b32_e32 v67, v26
	v_mov_b32_e32 v68, v26
	v_mov_b32_e32 v69, v26
	v_mov_b32_e32 v70, v26
	v_mov_b32_e32 v71, v26
	v_mov_b32_e32 v72, v26
	v_mov_b32_e32 v73, v26
	v_mov_b32_e32 v74, v26
	v_mov_b32_e32 v75, v26
	v_mov_b32_e32 v76, v26
	v_mov_b32_e32 v77, v26
	v_mov_b32_e32 v78, v26
	v_mov_b32_e32 v79, v26
	v_mov_b32_e32 v80, v26
	v_mov_b32_e32 v81, v26
.LBB0_979:
	s_add_u32 s22, s20, 0xfffc0080
	s_addc_u32 s23, s21, -1
	s_add_i32 s61, 0, 0x10000
	v_add_u32_e32 v144, s61, v147
	ds_read_b128 v[140:143], v144
	ds_read_b128 v[150:153], v144 offset:1024
	ds_read_b128 v[154:157], v144 offset:2048
	ds_read_b128 v[158:161], v144 offset:3072
	s_cmp_eq_u32 s60, 12
	s_cselect_b32 s29, s9, s23
	s_cselect_b32 s28, s56, s22
	s_cselect_b32 s23, s5, s59
	s_cselect_b32 s22, s57, s58
	v_lshl_add_u64 v[144:145], s[20:21], 0, v[138:139]
	s_add_i32 m0, s12, 0xc000
	ds_read_b128 v[162:165], v149
	ds_read_b128 v[166:169], v149 offset:1024
	ds_read_b128 v[170:173], v149 offset:2048
	ds_read_b128 v[174:177], v149 offset:3072
	ds_read_b128 v[178:181], v149 offset:4096
	ds_read_b128 v[182:185], v149 offset:5120
	ds_read_b128 v[186:189], v149 offset:6144
	ds_read_b128 v[190:193], v149 offset:7168
	global_load_lds_dwordx4 v[144:145], off
	v_lshl_add_u64 v[144:145], s[20:21], 0, v[136:137]
	s_add_i32 m0, s12, 0xe000
	s_nop 0
	global_load_lds_dwordx4 v[144:145], off
	s_waitcnt lgkmcnt(8)
	s_barrier
	s_waitcnt lgkmcnt(0)
	s_waitcnt lgkmcnt(0)
	v_mfma_f32_16x16x32_bf16 v[78:81], v[140:143], v[162:165], v[78:81]
	v_mfma_f32_16x16x32_bf16 v[74:77], v[154:157], v[162:165], v[74:77]
	v_mfma_f32_16x16x32_bf16 v[70:73], v[140:143], v[170:173], v[70:73]
	v_mfma_f32_16x16x32_bf16 v[66:69], v[154:157], v[170:173], v[66:69]
	v_mfma_f32_16x16x32_bf16 v[62:65], v[140:143], v[178:181], v[62:65]
	v_mfma_f32_16x16x32_bf16 v[54:57], v[154:157], v[178:181], v[54:57]
	v_mfma_f32_16x16x32_bf16 v[50:53], v[140:143], v[186:189], v[50:53]
	v_mfma_f32_16x16x32_bf16 v[42:45], v[154:157], v[186:189], v[42:45]
	v_mfma_f32_16x16x32_bf16 v[78:81], v[150:153], v[166:169], v[78:81]
	v_mfma_f32_16x16x32_bf16 v[74:77], v[158:161], v[166:169], v[74:77]
	v_mfma_f32_16x16x32_bf16 v[70:73], v[150:153], v[174:177], v[70:73]
	v_mfma_f32_16x16x32_bf16 v[66:69], v[158:161], v[174:177], v[66:69]
	v_mfma_f32_16x16x32_bf16 v[62:65], v[150:153], v[182:185], v[62:65]
	v_mfma_f32_16x16x32_bf16 v[54:57], v[158:161], v[182:185], v[54:57]
	v_mfma_f32_16x16x32_bf16 v[50:53], v[150:153], v[190:193], v[50:53]
	v_mfma_f32_16x16x32_bf16 v[42:45], v[158:161], v[190:193], v[42:45]
	s_barrier
	s_add_i32 s79, 0, 0x14000
	v_add_u32_e32 v144, s79, v147
	s_add_i32 s61, s61, s48
	ds_read_b128 v[194:197], v144
	ds_read_b128 v[208:211], v144 offset:1024
	ds_read_b128 v[212:215], v144 offset:2048
	ds_read_b128 v[216:219], v144 offset:3072
	v_lshl_add_u64 v[144:145], s[22:23], 0, v[16:17]
	s_mov_b32 m0, s61
	v_lshl_add_u64 v[220:221], s[22:23], 0, v[130:131]
	global_load_lds_dwordx4 v[144:145], off
	s_add_i32 m0, s61, 0x2000
	s_nop 0
	global_load_lds_dwordx4 v[220:221], off
	s_barrier
	s_waitcnt lgkmcnt(0)
	s_waitcnt lgkmcnt(0)
	v_mfma_f32_16x16x32_bf16 v[126:129], v[194:197], v[162:165], v[126:129]
	v_mfma_f32_16x16x32_bf16 v[122:125], v[212:215], v[162:165], v[122:125]
	v_mfma_f32_16x16x32_bf16 v[118:121], v[194:197], v[170:173], v[118:121]
	v_mfma_f32_16x16x32_bf16 v[114:117], v[212:215], v[170:173], v[114:117]
	v_mfma_f32_16x16x32_bf16 v[110:113], v[194:197], v[178:181], v[110:113]
	v_mfma_f32_16x16x32_bf16 v[106:109], v[212:215], v[178:181], v[106:109]
	v_mfma_f32_16x16x32_bf16 v[102:105], v[194:197], v[186:189], v[102:105]
	v_mfma_f32_16x16x32_bf16 v[98:101], v[212:215], v[186:189], v[98:101]
	v_mfma_f32_16x16x32_bf16 v[126:129], v[208:211], v[166:169], v[126:129]
	v_mfma_f32_16x16x32_bf16 v[122:125], v[216:219], v[166:169], v[122:125]
	v_mfma_f32_16x16x32_bf16 v[118:121], v[208:211], v[174:177], v[118:121]
	v_mfma_f32_16x16x32_bf16 v[114:117], v[216:219], v[174:177], v[114:117]
	v_mfma_f32_16x16x32_bf16 v[110:113], v[208:211], v[182:185], v[110:113]
	v_mfma_f32_16x16x32_bf16 v[106:109], v[216:219], v[182:185], v[106:109]
	v_mfma_f32_16x16x32_bf16 v[102:105], v[208:211], v[190:193], v[102:105]
	v_mfma_f32_16x16x32_bf16 v[98:101], v[216:219], v[190:193], v[98:101]
	s_mov_b32 m0, s12
	v_lshl_add_u64 v[222:223], s[28:29], 0, v[134:135]
	s_barrier
	ds_read_b128 v[162:165], v149 offset:16384
	ds_read_b128 v[166:169], v149 offset:17408
	ds_read_b128 v[170:173], v149 offset:18432
	ds_read_b128 v[174:177], v149 offset:19456
	ds_read_b128 v[178:181], v149 offset:20480
	ds_read_b128 v[182:185], v149 offset:21504
	ds_read_b128 v[186:189], v149 offset:22528
	ds_read_b128 v[190:193], v149 offset:23552
	global_load_lds_dwordx4 v[222:223], off
	v_lshl_add_u64 v[224:225], s[28:29], 0, v[132:133]
	s_mov_b32 m0, s34
	s_nop 0
	global_load_lds_dwordx4 v[224:225], off
	s_barrier
	s_waitcnt lgkmcnt(0)
	s_waitcnt lgkmcnt(0)
	v_mfma_f32_16x16x32_bf16 v[34:37], v[140:143], v[162:165], v[34:37]
	v_mfma_f32_16x16x32_bf16 v[30:33], v[154:157], v[162:165], v[30:33]
	v_mfma_f32_16x16x32_bf16 v[22:25], v[140:143], v[170:173], v[22:25]
	v_mfma_f32_16x16x32_bf16 v[18:21], v[154:157], v[170:173], v[18:21]
	v_mfma_f32_16x16x32_bf16 v[12:15], v[140:143], v[178:181], v[12:15]
	v_mfma_f32_16x16x32_bf16 v[8:11], v[154:157], v[178:181], v[8:11]
	v_mfma_f32_16x16x32_bf16 v[4:7], v[140:143], v[186:189], v[4:7]
	v_mfma_f32_16x16x32_bf16 v[0:3], v[154:157], v[186:189], v[0:3]
	v_mfma_f32_16x16x32_bf16 v[34:37], v[150:153], v[166:169], v[34:37]
	v_mfma_f32_16x16x32_bf16 v[30:33], v[158:161], v[166:169], v[30:33]
	v_mfma_f32_16x16x32_bf16 v[22:25], v[150:153], v[174:177], v[22:25]
	v_mfma_f32_16x16x32_bf16 v[18:21], v[158:161], v[174:177], v[18:21]
	v_mfma_f32_16x16x32_bf16 v[12:15], v[150:153], v[182:185], v[12:15]
	v_mfma_f32_16x16x32_bf16 v[8:11], v[158:161], v[182:185], v[8:11]
	v_mfma_f32_16x16x32_bf16 v[4:7], v[150:153], v[190:193], v[4:7]
	v_mfma_f32_16x16x32_bf16 v[0:3], v[158:161], v[190:193], v[0:3]
	s_barrier
	s_add_u32 s82, s22, 0x40000
	s_addc_u32 s83, s23, 0
	s_add_i32 s61, s79, s48
	v_lshl_add_u64 v[140:141], s[82:83], 0, v[16:17]
	s_mov_b32 m0, s61
	s_nop 0
	global_load_lds_dwordx4 v[140:141], off
	v_lshl_add_u64 v[140:141], s[82:83], 0, v[130:131]
	s_add_i32 m0, s61, 0x2000
	s_nop 0
	global_load_lds_dwordx4 v[140:141], off
	s_waitcnt vmcnt(6)
	s_barrier
	v_mfma_f32_16x16x32_bf16 v[94:97], v[194:197], v[162:165], v[94:97]
	v_mfma_f32_16x16x32_bf16 v[90:93], v[212:215], v[162:165], v[90:93]
	v_mfma_f32_16x16x32_bf16 v[86:89], v[194:197], v[170:173], v[86:89]
	v_mfma_f32_16x16x32_bf16 v[82:85], v[212:215], v[170:173], v[82:85]
	v_mfma_f32_16x16x32_bf16 v[58:61], v[194:197], v[178:181], v[58:61]
	v_mfma_f32_16x16x32_bf16 v[46:49], v[212:215], v[178:181], v[46:49]
	v_mfma_f32_16x16x32_bf16 v[38:41], v[194:197], v[186:189], v[38:41]
	v_mfma_f32_16x16x32_bf16 v[26:29], v[212:215], v[186:189], v[26:29]
	v_mfma_f32_16x16x32_bf16 v[94:97], v[208:211], v[166:169], v[94:97]
	v_mfma_f32_16x16x32_bf16 v[90:93], v[216:219], v[166:169], v[90:93]
	v_mfma_f32_16x16x32_bf16 v[86:89], v[208:211], v[174:177], v[86:89]
	v_mfma_f32_16x16x32_bf16 v[82:85], v[216:219], v[174:177], v[82:85]
	v_mfma_f32_16x16x32_bf16 v[58:61], v[208:211], v[182:185], v[58:61]
	v_mfma_f32_16x16x32_bf16 v[46:49], v[216:219], v[182:185], v[46:49]
	v_mfma_f32_16x16x32_bf16 v[38:41], v[208:211], v[190:193], v[38:41]
	v_mfma_f32_16x16x32_bf16 v[26:29], v[216:219], v[190:193], v[26:29]
	s_add_i32 s61, 0, 0x18000
	v_add_u32_e32 v158, s61, v147
	s_barrier
	ds_read_b128 v[140:143], v158
	ds_read_b128 v[150:153], v158 offset:1024
	ds_read_b128 v[154:157], v158 offset:2048
	ds_read_b128 v[158:161], v158 offset:3072
	s_add_u32 s28, s28, 0x40000
	s_addc_u32 s29, s29, 0
	s_mov_b32 m0, s49
	v_lshl_add_u64 v[194:195], s[28:29], 0, v[134:135]
	ds_read_b128 v[162:165], v149 offset:32768
	ds_read_b128 v[166:169], v149 offset:33792
	ds_read_b128 v[170:173], v149 offset:34816
	ds_read_b128 v[174:177], v149 offset:35840
	ds_read_b128 v[178:181], v149 offset:36864
	ds_read_b128 v[182:185], v149 offset:37888
	ds_read_b128 v[186:189], v149 offset:38912
	ds_read_b128 v[190:193], v149 offset:39936
	global_load_lds_dwordx4 v[194:195], off
	v_lshl_add_u64 v[194:195], s[28:29], 0, v[132:133]
	s_mov_b32 m0, s50
	s_nop 0
	global_load_lds_dwordx4 v[194:195], off
	s_waitcnt lgkmcnt(8)
	s_barrier
	s_waitcnt lgkmcnt(0)
	s_waitcnt lgkmcnt(0)
	v_mfma_f32_16x16x32_bf16 v[78:81], v[140:143], v[162:165], v[78:81]
	v_mfma_f32_16x16x32_bf16 v[74:77], v[154:157], v[162:165], v[74:77]
	v_mfma_f32_16x16x32_bf16 v[70:73], v[140:143], v[170:173], v[70:73]
	v_mfma_f32_16x16x32_bf16 v[66:69], v[154:157], v[170:173], v[66:69]
	v_mfma_f32_16x16x32_bf16 v[62:65], v[140:143], v[178:181], v[62:65]
	v_mfma_f32_16x16x32_bf16 v[54:57], v[154:157], v[178:181], v[54:57]
	v_mfma_f32_16x16x32_bf16 v[50:53], v[140:143], v[186:189], v[50:53]
	v_mfma_f32_16x16x32_bf16 v[42:45], v[154:157], v[186:189], v[42:45]
	v_mfma_f32_16x16x32_bf16 v[78:81], v[150:153], v[166:169], v[78:81]
	v_mfma_f32_16x16x32_bf16 v[74:77], v[158:161], v[166:169], v[74:77]
	v_mfma_f32_16x16x32_bf16 v[70:73], v[150:153], v[174:177], v[70:73]
	v_mfma_f32_16x16x32_bf16 v[66:69], v[158:161], v[174:177], v[66:69]
	v_mfma_f32_16x16x32_bf16 v[62:65], v[150:153], v[182:185], v[62:65]
	v_mfma_f32_16x16x32_bf16 v[54:57], v[158:161], v[182:185], v[54:57]
	v_mfma_f32_16x16x32_bf16 v[50:53], v[150:153], v[190:193], v[50:53]
	v_mfma_f32_16x16x32_bf16 v[42:45], v[158:161], v[190:193], v[42:45]
	s_barrier
	s_add_i32 s28, 0, 0x1c000
	s_add_i32 s29, s61, s48
	v_add_u32_e32 v216, s28, v147
	v_lshl_add_u64 v[144:145], v[144:145], 0, s[10:11]
	s_mov_b32 m0, s29
	ds_read_b128 v[194:197], v216
	ds_read_b128 v[208:211], v216 offset:1024
	ds_read_b128 v[212:215], v216 offset:2048
	ds_read_b128 v[216:219], v216 offset:3072
	global_load_lds_dwordx4 v[144:145], off
	v_lshl_add_u64 v[144:145], v[220:221], 0, s[10:11]
	s_add_i32 m0, s29, 0x2000
	s_nop 0
	global_load_lds_dwordx4 v[144:145], off
	s_barrier
	s_waitcnt lgkmcnt(0)
	s_waitcnt lgkmcnt(0)
	v_mfma_f32_16x16x32_bf16 v[126:129], v[194:197], v[162:165], v[126:129]
	v_mfma_f32_16x16x32_bf16 v[122:125], v[212:215], v[162:165], v[122:125]
	v_mfma_f32_16x16x32_bf16 v[118:121], v[194:197], v[170:173], v[118:121]
	v_mfma_f32_16x16x32_bf16 v[114:117], v[212:215], v[170:173], v[114:117]
	v_mfma_f32_16x16x32_bf16 v[110:113], v[194:197], v[178:181], v[110:113]
	v_mfma_f32_16x16x32_bf16 v[106:109], v[212:215], v[178:181], v[106:109]
	v_mfma_f32_16x16x32_bf16 v[102:105], v[194:197], v[186:189], v[102:105]
	v_mfma_f32_16x16x32_bf16 v[98:101], v[212:215], v[186:189], v[98:101]
	v_mfma_f32_16x16x32_bf16 v[126:129], v[208:211], v[166:169], v[126:129]
	v_mfma_f32_16x16x32_bf16 v[122:125], v[216:219], v[166:169], v[122:125]
	v_mfma_f32_16x16x32_bf16 v[118:121], v[208:211], v[174:177], v[118:121]
	v_mfma_f32_16x16x32_bf16 v[114:117], v[216:219], v[174:177], v[114:117]
	v_mfma_f32_16x16x32_bf16 v[110:113], v[208:211], v[182:185], v[110:113]
	v_mfma_f32_16x16x32_bf16 v[106:109], v[216:219], v[182:185], v[106:109]
	v_mfma_f32_16x16x32_bf16 v[102:105], v[208:211], v[190:193], v[102:105]
	v_mfma_f32_16x16x32_bf16 v[98:101], v[216:219], v[190:193], v[98:101]
	s_mov_b32 m0, s51
	v_lshl_add_u64 v[144:145], v[222:223], 0, s[10:11]
	s_barrier
	ds_read_b128 v[162:165], v149 offset:49152
	ds_read_b128 v[166:169], v149 offset:50176
	ds_read_b128 v[170:173], v149 offset:51200
	ds_read_b128 v[174:177], v149 offset:52224
	ds_read_b128 v[178:181], v149 offset:53248
	ds_read_b128 v[182:185], v149 offset:54272
	ds_read_b128 v[186:189], v149 offset:55296
	ds_read_b128 v[190:193], v149 offset:56320
	global_load_lds_dwordx4 v[144:145], off
	v_lshl_add_u64 v[144:145], v[224:225], 0, s[10:11]
	s_mov_b32 m0, s52
	s_nop 0
	global_load_lds_dwordx4 v[144:145], off
	s_barrier
	s_waitcnt lgkmcnt(0)
	s_waitcnt lgkmcnt(0)
	v_mfma_f32_16x16x32_bf16 v[34:37], v[140:143], v[162:165], v[34:37]
	v_mfma_f32_16x16x32_bf16 v[30:33], v[154:157], v[162:165], v[30:33]
	v_mfma_f32_16x16x32_bf16 v[22:25], v[140:143], v[170:173], v[22:25]
	v_mfma_f32_16x16x32_bf16 v[18:21], v[154:157], v[170:173], v[18:21]
	v_mfma_f32_16x16x32_bf16 v[12:15], v[140:143], v[178:181], v[12:15]
	v_mfma_f32_16x16x32_bf16 v[8:11], v[154:157], v[178:181], v[8:11]
	v_mfma_f32_16x16x32_bf16 v[4:7], v[140:143], v[186:189], v[4:7]
	v_mfma_f32_16x16x32_bf16 v[0:3], v[154:157], v[186:189], v[0:3]
	v_mfma_f32_16x16x32_bf16 v[34:37], v[150:153], v[166:169], v[34:37]
	v_mfma_f32_16x16x32_bf16 v[30:33], v[158:161], v[166:169], v[30:33]
	v_mfma_f32_16x16x32_bf16 v[22:25], v[150:153], v[174:177], v[22:25]
	v_mfma_f32_16x16x32_bf16 v[18:21], v[158:161], v[174:177], v[18:21]
	v_mfma_f32_16x16x32_bf16 v[12:15], v[150:153], v[182:185], v[12:15]
	v_mfma_f32_16x16x32_bf16 v[8:11], v[158:161], v[182:185], v[8:11]
	v_mfma_f32_16x16x32_bf16 v[4:7], v[150:153], v[190:193], v[4:7]
	v_mfma_f32_16x16x32_bf16 v[0:3], v[158:161], v[190:193], v[0:3]
	s_barrier
	s_add_u32 s22, s22, 0x40080
	s_addc_u32 s23, s23, 0
	s_add_i32 s28, s28, s48
	v_lshl_add_u64 v[140:141], s[22:23], 0, v[16:17]
	s_mov_b32 m0, s28
	s_nop 0
	global_load_lds_dwordx4 v[140:141], off
	v_lshl_add_u64 v[140:141], s[22:23], 0, v[130:131]
	s_add_i32 m0, s28, 0x2000
	s_nop 0
	global_load_lds_dwordx4 v[140:141], off
	s_waitcnt vmcnt(6)
	s_barrier
	v_mfma_f32_16x16x32_bf16 v[94:97], v[194:197], v[162:165], v[94:97]
	v_mfma_f32_16x16x32_bf16 v[90:93], v[212:215], v[162:165], v[90:93]
	v_mfma_f32_16x16x32_bf16 v[86:89], v[194:197], v[170:173], v[86:89]
	v_mfma_f32_16x16x32_bf16 v[82:85], v[212:215], v[170:173], v[82:85]
	v_mfma_f32_16x16x32_bf16 v[58:61], v[194:197], v[178:181], v[58:61]
	v_mfma_f32_16x16x32_bf16 v[46:49], v[212:215], v[178:181], v[46:49]
	v_mfma_f32_16x16x32_bf16 v[38:41], v[194:197], v[186:189], v[38:41]
	v_mfma_f32_16x16x32_bf16 v[26:29], v[212:215], v[186:189], v[26:29]
	v_mfma_f32_16x16x32_bf16 v[94:97], v[208:211], v[166:169], v[94:97]
	v_mfma_f32_16x16x32_bf16 v[90:93], v[216:219], v[166:169], v[90:93]
	v_mfma_f32_16x16x32_bf16 v[86:89], v[208:211], v[174:177], v[86:89]
	v_mfma_f32_16x16x32_bf16 v[82:85], v[216:219], v[174:177], v[82:85]
	v_mfma_f32_16x16x32_bf16 v[58:61], v[208:211], v[182:185], v[58:61]
	v_mfma_f32_16x16x32_bf16 v[46:49], v[216:219], v[182:185], v[46:49]
	v_mfma_f32_16x16x32_bf16 v[38:41], v[208:211], v[190:193], v[38:41]
	v_mfma_f32_16x16x32_bf16 v[26:29], v[216:219], v[190:193], v[26:29]
	s_add_i32 s60, s60, 2
	s_add_u32 s58, s58, 0x100
	s_addc_u32 s59, s59, 0
	s_add_u32 s20, s20, 0x100
	s_addc_u32 s21, s21, 0
	s_cmp_gt_u32 s60, 13
	s_barrier
	s_cbranch_scc0 .LBB0_979
	v_lshl_or_b32 v144, s19, 8, v148
	v_lshl_add_u32 v140, s18, 8, v146
	v_ashrrev_i32_e32 v145, 31, v144
	v_mov_b64_e32 v[142:143], s[94:95]
	v_mad_i64_i32 v[150:151], s[20:21], v140, s66, v[142:143]
	v_lshlrev_b64 v[144:145], 1, v[144:145]
	v_lshl_add_u64 v[154:155], v[150:151], 0, v[144:145]
	v_cvt_pk_bf16_f32 v150, v78, v79
	v_cvt_pk_bf16_f32 v151, v80, v81
	v_cvt_pk_bf16_f32 v152, v74, v75
	v_cvt_pk_bf16_f32 v153, v76, v77
	global_store_dwordx4 v[154:155], v[150:153], off
	v_cvt_pk_bf16_f32 v126, v126, v127
	v_cvt_pk_bf16_f32 v127, v128, v129
	v_cvt_pk_bf16_f32 v128, v122, v123
	v_cvt_pk_bf16_f32 v129, v124, v125
	global_store_dwordx4 v[154:155], v[126:129], off offset:256
	v_or_b32_e32 v122, 16, v140
	v_mad_i64_i32 v[124:125], s[20:21], v122, s66, v[142:143]
	v_lshl_add_u64 v[128:129], v[124:125], 0, v[144:145]
	v_cvt_pk_bf16_f32 v124, v70, v71
	v_cvt_pk_bf16_f32 v125, v72, v73
	v_cvt_pk_bf16_f32 v126, v66, v67
	v_cvt_pk_bf16_f32 v127, v68, v69
	global_store_dwordx4 v[128:129], v[124:127], off
	v_cvt_pk_bf16_f32 v118, v118, v119
	v_cvt_pk_bf16_f32 v119, v120, v121
	v_cvt_pk_bf16_f32 v120, v114, v115
	v_cvt_pk_bf16_f32 v121, v116, v117
	global_store_dwordx4 v[128:129], v[118:121], off offset:256
	v_or_b32_e32 v114, 32, v140
	v_mad_i64_i32 v[116:117], s[20:21], v114, s66, v[142:143]
	v_lshl_add_u64 v[120:121], v[116:117], 0, v[144:145]
	v_cvt_pk_bf16_f32 v116, v62, v63
	v_cvt_pk_bf16_f32 v117, v64, v65
	v_cvt_pk_bf16_f32 v118, v54, v55
	v_cvt_pk_bf16_f32 v119, v56, v57
	global_store_dwordx4 v[120:121], v[116:119], off
	v_cvt_pk_bf16_f32 v110, v110, v111
	v_cvt_pk_bf16_f32 v111, v112, v113
	v_cvt_pk_bf16_f32 v112, v106, v107
	v_cvt_pk_bf16_f32 v113, v108, v109
	global_store_dwordx4 v[120:121], v[110:113], off offset:256
	v_or_b32_e32 v106, 48, v140
	v_mad_i64_i32 v[108:109], s[20:21], v106, s66, v[142:143]
	v_lshl_add_u64 v[112:113], v[108:109], 0, v[144:145]
	v_cvt_pk_bf16_f32 v108, v50, v51
	v_cvt_pk_bf16_f32 v109, v52, v53
	v_cvt_pk_bf16_f32 v110, v42, v43
	v_cvt_pk_bf16_f32 v111, v44, v45
	global_store_dwordx4 v[112:113], v[108:111], off
	v_cvt_pk_bf16_f32 v102, v102, v103
	v_cvt_pk_bf16_f32 v103, v104, v105
	v_cvt_pk_bf16_f32 v104, v98, v99
	v_cvt_pk_bf16_f32 v105, v100, v101
	global_store_dwordx4 v[112:113], v[102:105], off offset:256
	v_add_u32_e32 v98, 0x80, v140
	v_mad_i64_i32 v[100:101], s[20:21], v98, s66, v[142:143]
	v_lshl_add_u64 v[104:105], v[100:101], 0, v[144:145]
	v_cvt_pk_bf16_f32 v100, v34, v35
	v_cvt_pk_bf16_f32 v101, v36, v37
	v_cvt_pk_bf16_f32 v102, v30, v31
	v_cvt_pk_bf16_f32 v103, v32, v33
	global_store_dwordx4 v[104:105], v[100:103], off
	v_cvt_pk_bf16_f32 v94, v94, v95
	v_cvt_pk_bf16_f32 v95, v96, v97
	v_cvt_pk_bf16_f32 v96, v90, v91
	v_cvt_pk_bf16_f32 v97, v92, v93
	global_store_dwordx4 v[104:105], v[94:97], off offset:256
	v_add_u32_e32 v90, 0x90, v140
	v_mad_i64_i32 v[92:93], s[20:21], v90, s66, v[142:143]
	v_lshl_add_u64 v[96:97], v[92:93], 0, v[144:145]
	v_cvt_pk_bf16_f32 v92, v22, v23
	v_cvt_pk_bf16_f32 v93, v24, v25
	v_cvt_pk_bf16_f32 v94, v18, v19
	v_cvt_pk_bf16_f32 v95, v20, v21
	global_store_dwordx4 v[96:97], v[92:95], off
	v_cvt_pk_bf16_f32 v86, v86, v87
	v_cvt_pk_bf16_f32 v87, v88, v89
	v_cvt_pk_bf16_f32 v88, v82, v83
	v_cvt_pk_bf16_f32 v89, v84, v85
	global_store_dwordx4 v[96:97], v[86:89], off offset:256
	v_add_u32_e32 v82, 0xa0, v140
	v_mad_i64_i32 v[84:85], s[20:21], v82, s66, v[142:143]
	v_lshl_add_u64 v[88:89], v[84:85], 0, v[144:145]
	v_cvt_pk_bf16_f32 v84, v12, v13
	v_cvt_pk_bf16_f32 v85, v14, v15
	v_cvt_pk_bf16_f32 v86, v8, v9
	v_cvt_pk_bf16_f32 v87, v10, v11
	global_store_dwordx4 v[88:89], v[84:87], off
	v_cvt_pk_bf16_f32 v58, v58, v59
	v_cvt_pk_bf16_f32 v59, v60, v61
	v_cvt_pk_bf16_f32 v60, v46, v47
	v_cvt_pk_bf16_f32 v61, v48, v49
	global_store_dwordx4 v[88:89], v[58:61], off offset:256
	v_add_u32_e32 v46, 0xb0, v140
	v_mad_i64_i32 v[48:49], s[20:21], v46, s66, v[142:143]
	v_lshl_add_u64 v[48:49], v[48:49], 0, v[144:145]
	v_cvt_pk_bf16_f32 v58, v4, v5
	v_cvt_pk_bf16_f32 v59, v6, v7
	v_cvt_pk_bf16_f32 v60, v0, v1
	v_cvt_pk_bf16_f32 v61, v2, v3
	global_store_dwordx4 v[48:49], v[58:61], off
	v_cvt_pk_bf16_f32 v38, v38, v39
	v_cvt_pk_bf16_f32 v39, v40, v41
	v_cvt_pk_bf16_f32 v40, v26, v27
	v_cvt_pk_bf16_f32 v41, v28, v29
	global_store_dwordx4 v[48:49], v[38:41], off offset:256
	s_cmp_eq_u32 s19, 34
	s_cselect_b64 s[18:19], -1, 0
	s_and_b64 s[20:21], s[38:39], s[18:19]
	s_and_saveexec_b64 s[18:19], s[20:21]
	s_cbranch_execz .LBB0_975
	v_ashrrev_i32_e32 v141, 31, v140
	v_lshlrev_b64 v[26:27], 5, v[140:141]
	v_ashrrev_i32_e32 v123, 31, v122
	v_lshl_add_u64 v[26:27], s[42:43], 0, v[26:27]
	global_store_dwordx4 v[26:27], v[78:81], off
	global_store_dwordx4 v[26:27], v[74:77], off offset:16
	v_lshlrev_b64 v[26:27], 5, v[122:123]
	v_ashrrev_i32_e32 v115, 31, v114
	v_lshl_add_u64 v[26:27], s[42:43], 0, v[26:27]
	global_store_dwordx4 v[26:27], v[70:73], off
	global_store_dwordx4 v[26:27], v[66:69], off offset:16
	v_lshlrev_b64 v[26:27], 5, v[114:115]
	v_ashrrev_i32_e32 v107, 31, v106
	v_lshl_add_u64 v[26:27], s[42:43], 0, v[26:27]
	global_store_dwordx4 v[26:27], v[62:65], off
	global_store_dwordx4 v[26:27], v[54:57], off offset:16
	v_lshlrev_b64 v[26:27], 5, v[106:107]
	v_ashrrev_i32_e32 v99, 31, v98
	v_lshl_add_u64 v[26:27], s[42:43], 0, v[26:27]
	global_store_dwordx4 v[26:27], v[50:53], off
	global_store_dwordx4 v[26:27], v[42:45], off offset:16
	v_lshlrev_b64 v[26:27], 5, v[98:99]
	v_ashrrev_i32_e32 v91, 31, v90
	v_lshl_add_u64 v[26:27], s[42:43], 0, v[26:27]
	global_store_dwordx4 v[26:27], v[34:37], off
	global_store_dwordx4 v[26:27], v[30:33], off offset:16
	v_lshlrev_b64 v[26:27], 5, v[90:91]
	v_ashrrev_i32_e32 v83, 31, v82
	v_lshl_add_u64 v[26:27], s[42:43], 0, v[26:27]
	global_store_dwordx4 v[26:27], v[22:25], off
	global_store_dwordx4 v[26:27], v[18:21], off offset:16
	v_ashrrev_i32_e32 v47, 31, v46
	s_nop 0
	v_lshlrev_b64 v[18:19], 5, v[82:83]
	v_lshl_add_u64 v[18:19], s[42:43], 0, v[18:19]
	global_store_dwordx4 v[18:19], v[12:15], off
	global_store_dwordx4 v[18:19], v[8:11], off offset:16
	s_nop 1
	v_lshlrev_b64 v[8:9], 5, v[46:47]
	v_lshl_add_u64 v[8:9], s[42:43], 0, v[8:9]
	global_store_dwordx4 v[8:9], v[4:7], off
	global_store_dwordx4 v[8:9], v[0:3], off offset:16
	s_branch .LBB0_975
